# v32 with three priority levels per step: LDS/DMA issue 0, MFMA block 1, softmax VALU 2
# speedup vs baseline: 1.0082x; 1.0082x over previous
; DI void expsum(f32x16& p, float& l_reg, bf16x8& pa0, bf16x8& pa1) {
; #pragma unroll
;     for (int r = 0; r < 16; ++r) p[r] = __builtin_amdgcn_exp2f(p[r]);
;     float ps = 0.f;
; #pragma unroll
;     for (int r = 0; r < 16; ++r) ps += p[r];
;     l_reg += ps; asm volatile("" : "+v"(l_reg));
;     ...
;     ATT_PK4(p, 0, pa0); ATT_PK4(p, 8, pa1);
;     ...
; }
; DI int v_rd_base(int lane) { return ((lane & 3) << 3) | (((lane >> 2) & 3) << 6) | (((lane >> 4) & 1) << 5) | (((lane >> 5) & 1) << 8); }
; template <int OFF> DI s16x4 tr_read(int vb) { s16x4 r; asm volatile("ds_read_b64_tr_b16 %0, %1 offset:%2" : "=&v"(r) : "v"(vb), "i"(OFF) : "memory"); return r; }
; template <int H> DI void v_reads(s16x4* vf, int vb) {
;     vf[0] = tr_read<v_rd_off(0, 2 * H, 0)>(vb); vf[1] = tr_read<v_rd_off(0, 2 * H, 1)>(vb); vf[2] = tr_read<v_rd_off(0, 2 * H + 1, 0)>(vb); vf[3] = tr_read<v_rd_off(0, 2 * H + 1, 1)>(vb);
;     vf[4] = tr_read<v_rd_off(1, 2 * H, 0)>(vb); vf[5] = tr_read<v_rd_off(1, 2 * H, 1)>(vb); vf[6] = tr_read<v_rd_off(1, 2 * H + 1, 0)>(vb); vf[7] = tr_read<v_rd_off(1, 2 * H + 1, 1)>(vb);
;     vf[8] = tr_read<v_rd_off(2, 2 * H, 0)>(vb); vf[9] = tr_read<v_rd_off(2, 2 * H, 1)>(vb); vf[10] = tr_read<v_rd_off(2, 2 * H + 1, 0)>(vb); vf[11] = tr_read<v_rd_off(2, 2 * H + 1, 1)>(vb);
;     vf[12] = tr_read<v_rd_off(3, 2 * H, 0)>(vb); vf[13] = tr_read<v_rd_off(3, 2 * H, 1)>(vb); vf[14] = tr_read<v_rd_off(3, 2 * H + 1, 0)>(vb); vf[15] = tr_read<v_rd_off(3, 2 * H + 1, 1)>(vb);
; }
; DI void pv_mma(f32x16* o, const s16x4* vf, bf16x8 pa0, bf16x8 pa1) {
;     ...
; #pragma unroll
;     for (int d0 = 0; d0 < 4; ++d0) {
;         o[d0] = __builtin_amdgcn_mfma_f32_32x32x16_bf16(pa0, ATT_PK(vf[4 * d0], vf[4 * d0 + 1]), o[d0], 0, 0, 0);
;         o[d0] = __builtin_amdgcn_mfma_f32_32x32x16_bf16(pa1, ATT_PK(vf[4 * d0 + 2], vf[4 * d0 + 3]), o[d0], 0, 0, 0); }
;     ...
; }
; template <int DQK, int MODE, int LDQ, int LDK, int LDV> ...
;     ...
;     const int vbase = (int)(unsigned)(size_t)lds + V_OFF + v_rd_base(lane);
;     ...
;     constexpr int NDA = ND0 > 6 ? 6 : ND0;
;     ...
;     f32x16 pA, pB; bf16x8 pa0, pa1;
;     int v0 = 0, v1 = 1, v2 = 2;
;     ATT_TOP(NKP + 2);
;     { bf16x8 kf[NDA]; k_reads<DQK, 0, NDA>(kf, lds, 0, r32, hi); ATT_LGKM0(); qk_mma<0, NDA>(pA, kf, qr);
;       if constexpr (ND0 > NDA) { bf16x8 kg[ND0 - NDA]; k_reads<DQK, NDA, ND0>(kg, lds, 0, r32, hi); ATT_LGKM0(); qk_mma<NDA, ND0>(pA, kg, qr); }
.Lstg_d0_top_10:
	s_setprio 0
	s_add_i32 s1, s95, s1
	global_load_lds_dwordx4 v[100:101], off
	s_add_i32 s2, s1, 0x400
	s_mov_b32 m0, s1
	s_add_i32 s1, s62, s0
	global_load_lds_dwordx4 v[102:103], off
	s_mov_b32 m0, s2
	s_add_i32 s74, s6, s0
	global_load_lds_dwordx4 v[104:105], off
	s_cmp_eq_u32 s1, 1
	s_cselect_b64 s[2:3], -1, 0
	s_and_b64 vcc, s[4:5], s[2:3]
	s_cmp_eq_u32 s74, 1
	s_cselect_b64 s[2:3], -1, 0
	s_or_b64 vcc, s[2:3], vcc
	s_andn2_b64 vcc, exec, vcc
	s_mov_b32 s1, s23
	s_cbranch_vccnz .LBB0_1922
	v_cndmask_b32_e64 v122, v112, v113, s[2:3]
	v_pk_mul_f32 v[14:15], v[14:15], v[122:123] op_sel_hi:[1,0]
	v_pk_mul_f32 v[12:13], v[12:13], v[122:123] op_sel_hi:[1,0]
	v_pk_mul_f32 v[10:11], v[10:11], v[122:123] op_sel_hi:[1,0]
	v_pk_mul_f32 v[8:9], v[8:9], v[122:123] op_sel_hi:[1,0]
	v_pk_mul_f32 v[6:7], v[6:7], v[122:123] op_sel_hi:[1,0]
	v_pk_mul_f32 v[4:5], v[4:5], v[122:123] op_sel_hi:[1,0]
	v_pk_mul_f32 v[2:3], v[2:3], v[122:123] op_sel_hi:[1,0]
	v_pk_mul_f32 v[0:1], v[0:1], v[122:123] op_sel_hi:[1,0]
	v_pk_mul_f32 v[62:63], v[62:63], v[122:123] op_sel_hi:[1,0]
	v_pk_mul_f32 v[60:61], v[60:61], v[122:123] op_sel_hi:[1,0]
	v_pk_mul_f32 v[58:59], v[58:59], v[122:123] op_sel_hi:[1,0]
	v_pk_mul_f32 v[56:57], v[56:57], v[122:123] op_sel_hi:[1,0]
	v_pk_mul_f32 v[54:55], v[54:55], v[122:123] op_sel_hi:[1,0]
	v_pk_mul_f32 v[52:53], v[52:53], v[122:123] op_sel_hi:[1,0]
	v_pk_mul_f32 v[50:51], v[50:51], v[122:123] op_sel_hi:[1,0]
	v_pk_mul_f32 v[48:49], v[48:49], v[122:123] op_sel_hi:[1,0]
	v_pk_mul_f32 v[46:47], v[46:47], v[122:123] op_sel_hi:[1,0]
	v_pk_mul_f32 v[44:45], v[44:45], v[122:123] op_sel_hi:[1,0]
	v_pk_mul_f32 v[42:43], v[42:43], v[122:123] op_sel_hi:[1,0]
	v_pk_mul_f32 v[40:41], v[40:41], v[122:123] op_sel_hi:[1,0]
	v_pk_mul_f32 v[38:39], v[38:39], v[122:123] op_sel_hi:[1,0]
	v_pk_mul_f32 v[36:37], v[36:37], v[122:123] op_sel_hi:[1,0]
	v_pk_mul_f32 v[34:35], v[34:35], v[122:123] op_sel_hi:[1,0]
	v_pk_mul_f32 v[32:33], v[32:33], v[122:123] op_sel_hi:[1,0]
	v_pk_mul_f32 v[30:31], v[30:31], v[122:123] op_sel_hi:[1,0]
	v_pk_mul_f32 v[28:29], v[28:29], v[122:123] op_sel_hi:[1,0]
	v_pk_mul_f32 v[26:27], v[26:27], v[122:123] op_sel_hi:[1,0]
	v_pk_mul_f32 v[24:25], v[24:25], v[122:123] op_sel_hi:[1,0]
	v_pk_mul_f32 v[22:23], v[22:23], v[122:123] op_sel_hi:[1,0]
	v_pk_mul_f32 v[20:21], v[20:21], v[122:123] op_sel_hi:[1,0]
	v_pk_mul_f32 v[18:19], v[18:19], v[122:123] op_sel_hi:[1,0]
	v_pk_mul_f32 v[16:17], v[16:17], v[122:123] op_sel_hi:[1,0]
	v_mul_f32_e32 v120, v120, v122
.LBB0_1922:
	s_add_i32 s3, s0, -1
	s_add_i32 s2, s22, 0xffffa000
	s_and_b32 s2, s2, 0x6000
	v_add_u32_e32 v121, s2, v114
	v_add_u32_e32 v122, v121, v115
	v_add_u32_e32 v126, v121, v116
	ds_read_b128 v[122:125], v122 offset:4096
	ds_read_b128 v[132:135], v126 offset:4096
	v_add_u32_e32 v126, v121, v117
	v_add_u32_e32 v121, v121, v118
	s_lshl_b32 s2, s1, 14
	ds_read_b128 v[136:139], v126 offset:4096
	ds_read_b128 v[140:143], v121 offset:4096
	v_add_u32_e32 v121, s2, v106
	ds_read_b64_tr_b16 v[144:145], v121 offset:0
	ds_read_b64_tr_b16 v[146:147], v121 offset:0x800
	ds_read_b64_tr_b16 v[148:149], v121 offset:0x1000
	ds_read_b64_tr_b16 v[150:151], v121 offset:0x1800
	ds_read_b64_tr_b16 v[152:153], v121 offset:0x200
	ds_read_b64_tr_b16 v[154:155], v121 offset:0xa00
	ds_read_b64_tr_b16 v[156:157], v121 offset:0x1200
	ds_read_b64_tr_b16 v[158:159], v121 offset:0x1a00
	ds_read_b64_tr_b16 v[162:163], v121 offset:0x400
	ds_read_b64_tr_b16 v[164:165], v121 offset:0xc00
	ds_read_b64_tr_b16 v[166:167], v121 offset:0x1400
	ds_read_b64_tr_b16 v[168:169], v121 offset:0x1c00
	ds_read_b64_tr_b16 v[170:171], v121 offset:0x600
	ds_read_b64_tr_b16 v[172:173], v121 offset:0xe00
	ds_read_b64_tr_b16 v[174:175], v121 offset:0x1600
	ds_read_b64_tr_b16 v[176:177], v121 offset:0x1e00
	s_setprio 2
	v_exp_f32_e32 v64, v64
	v_exp_f32_e32 v65, v65
	v_exp_f32_e32 v66, v66
	v_exp_f32_e32 v67, v67
	v_exp_f32_e32 v68, v68
	v_add_f32_e32 v126, 0, v64
	v_exp_f32_e32 v69, v69
	v_add_f32_e32 v126, v65, v126
	v_exp_f32_e32 v70, v70
	v_add_f32_e32 v126, v66, v126
	v_exp_f32_e32 v71, v71
	v_add_f32_e32 v126, v67, v126
	v_exp_f32_e32 v72, v72
	v_add_f32_e32 v126, v68, v126
	v_exp_f32_e32 v73, v73
	v_add_f32_e32 v126, v69, v126
	v_exp_f32_e32 v74, v74
	v_add_f32_e32 v126, v70, v126
	v_exp_f32_e32 v75, v75
	v_add_f32_e32 v126, v71, v126
	v_exp_f32_e32 v76, v76
	v_add_f32_e32 v126, v72, v126
	v_exp_f32_e32 v77, v77
	v_add_f32_e32 v126, v73, v126
	v_exp_f32_e32 v78, v78
	v_add_f32_e32 v126, v74, v126
	v_exp_f32_e32 v79, v79
	v_add_f32_e32 v126, v75, v126
	v_add_f32_e32 v126, v76, v126
	v_add_f32_e32 v126, v77, v126
	v_add_f32_e32 v126, v78, v126
	v_add_f32_e32 v126, v79, v126
	v_add_f32_e32 v120, v126, v120
	v_cvt_pk_bf16_f32 v64, v64, v65
	v_cvt_pk_bf16_f32 v65, v66, v67
	v_cvt_pk_bf16_f32 v66, v68, v69
	v_cvt_pk_bf16_f32 v67, v70, v71
	v_cvt_pk_bf16_f32 v68, v72, v73
	v_cvt_pk_bf16_f32 v69, v74, v75
	v_cvt_pk_bf16_f32 v70, v76, v77
	v_cvt_pk_bf16_f32 v71, v78, v79
	s_nop 0
	v_permlane32_swap_b32_e32 v64, v66
	v_permlane32_swap_b32_e32 v65, v67
	v_permlane32_swap_b32_e32 v68, v70
	v_permlane32_swap_b32_e32 v69, v71
	s_waitcnt lgkmcnt(0)
	s_setprio 1
	v_mfma_f32_32x32x16_bf16 v[0:15], v[64:67], v[144:147], v[0:15]
	s_cmp_lt_i32 s3, s55
	s_cselect_b64 vcc, -1, 0
	s_cmp_ge_i32 s3, s97
	s_cselect_b64 s[74:75], -1, 0
	s_or_b64 s[74:75], vcc, s[74:75]
	s_and_b64 vcc, exec, s[74:75]
	v_mfma_f32_32x32x16_bf16 v[48:63], v[64:67], v[152:155], v[48:63]
	v_mfma_f32_32x32x16_bf16 v[32:47], v[64:67], v[162:165], v[32:47]
	v_mfma_f32_32x32x16_bf16 v[16:31], v[64:67], v[170:173], v[16:31]
	v_mfma_f32_32x32x16_bf16 v[0:15], v[68:71], v[148:151], v[0:15]
	v_mfma_f32_32x32x16_bf16 v[48:63], v[68:71], v[156:159], v[48:63]
	v_mfma_f32_32x32x16_bf16 v[32:47], v[68:71], v[166:169], v[32:47]
	v_mfma_f32_32x32x16_bf16 v[16:31], v[68:71], v[174:177], v[16:31]
	v_mfma_f32_32x32x16_bf16 v[64:79], v[122:125], v[92:95], 0
	v_mfma_f32_32x32x16_bf16 v[64:79], v[132:135], v[88:91], v[64:79]
	v_mfma_f32_32x32x16_bf16 v[64:79], v[136:139], v[84:87], v[64:79]
	v_mfma_f32_32x32x16_bf16 v[64:79], v[140:143], v[80:83], v[64:79]
	s_setprio 0
	v_add_u32_e32 v122, s7, v119
	s_cbranch_vccnz .LBB0_1924
; #define LAS __attribute__((address_space(3)))
; DI void expsum(f32x16& p, float& l_reg, bf16x8& pa0, bf16x8& pa1) {
; #pragma unroll
;     for (int r = 0; r < 16; ++r) p[r] = __builtin_amdgcn_exp2f(p[r]);
;     float ps = 0.f;
; #pragma unroll
;     for (int r = 0; r < 16; ++r) ps += p[r];
;     l_reg += ps; asm volatile("" : "+v"(l_reg));
;     ...
;     ATT_PK4(p, 0, pa0); ATT_PK4(p, 8, pa1);
;     ...
; }
; DI int v_rd_base(int lane) { return ((lane & 3) << 3) | (((lane >> 2) & 3) << 6) | (((lane >> 4) & 1) << 5) | (((lane >> 5) & 1) << 8); }
; template <int OFF> DI s16x4 tr_read(int vb) { s16x4 r; asm volatile("ds_read_b64_tr_b16 %0, %1 offset:%2" : "=&v"(r) : "v"(vb), "i"(OFF) : "memory"); return r; }
; template <int H> DI void v_reads(s16x4* vf, int vb) {
;     vf[0] = tr_read<v_rd_off(0, 2 * H, 0)>(vb); vf[1] = tr_read<v_rd_off(0, 2 * H, 1)>(vb); vf[2] = tr_read<v_rd_off(0, 2 * H + 1, 0)>(vb); vf[3] = tr_read<v_rd_off(0, 2 * H + 1, 1)>(vb);
;     vf[4] = tr_read<v_rd_off(1, 2 * H, 0)>(vb); vf[5] = tr_read<v_rd_off(1, 2 * H, 1)>(vb); vf[6] = tr_read<v_rd_off(1, 2 * H + 1, 0)>(vb); vf[7] = tr_read<v_rd_off(1, 2 * H + 1, 1)>(vb);
;     vf[8] = tr_read<v_rd_off(2, 2 * H, 0)>(vb); vf[9] = tr_read<v_rd_off(2, 2 * H, 1)>(vb); vf[10] = tr_read<v_rd_off(2, 2 * H + 1, 0)>(vb); vf[11] = tr_read<v_rd_off(2, 2 * H + 1, 1)>(vb);
;     vf[12] = tr_read<v_rd_off(3, 2 * H, 0)>(vb); vf[13] = tr_read<v_rd_off(3, 2 * H, 1)>(vb); vf[14] = tr_read<v_rd_off(3, 2 * H + 1, 0)>(vb); vf[15] = tr_read<v_rd_off(3, 2 * H + 1, 1)>(vb);
; }
; DI void pv_mma(f32x16* o, const s16x4* vf, bf16x8 pa0, bf16x8 pa1) {
;     ...
; #pragma unroll
;     for (int d0 = 0; d0 < 4; ++d0) {
;         o[d0] = __builtin_amdgcn_mfma_f32_32x32x16_bf16(pa0, ATT_PK(vf[4 * d0], vf[4 * d0 + 1]), o[d0], 0, 0, 0);
;         o[d0] = __builtin_amdgcn_mfma_f32_32x32x16_bf16(pa1, ATT_PK(vf[4 * d0 + 2], vf[4 * d0 + 3]), o[d0], 0, 0, 0); }
;     ...
; }
; template <int DQK, int D0A, int D0B> DI void k_reads(bf16x8* kf, const LAS unsigned char* Ks, int half, int r32, int hi) {
; #pragma unroll
;     for (int d0 = D0A; d0 < D0B; ++d0) kf[d0 - D0A] = *(const LAS bf16x8*)(Ks + half * (32 * DQK * 2) + kswz<DQK>(r32, (d0 * 16 + hi * 8) * 2));
; }
; template <int D0A, int D0B> DI void qk_mma(f32x16& p, const bf16x8* kf, const bf16x8* qr) {
; #pragma unroll
;     for (int d0 = D0A; d0 < D0B; ++d0) {
	v_add_u32_e32 v138, 0x28908, v122
	v_add_u32_e32 v140, 0x28920, v122
	v_add_u32_e32 v142, 0x28928, v122
	v_add_u32_e32 v124, 0x28940, v122
	v_add_u32_e32 v126, 0x28948, v122
	v_add_u32_e32 v132, 0x28960, v122
	v_add_u32_e32 v134, 0x28968, v122
	v_add_u32_e32 v123, 0x28900, v122
	ds_read2_b32 v[124:125], v124 offset1:1
	ds_read2_b32 v[126:127], v126 offset1:1
	ds_read2_b32 v[132:133], v132 offset1:1
	ds_read2_b32 v[134:135], v134 offset1:1
	ds_read2_b32 v[136:137], v123 offset1:1
	ds_read2_b32 v[138:139], v138 offset1:1
	ds_read2_b32 v[140:141], v140 offset1:1
	ds_read2_b32 v[142:143], v142 offset1:1
	s_waitcnt lgkmcnt(0)
	v_pk_add_f32 v[78:79], v[78:79], v[134:135]
	v_pk_add_f32 v[76:77], v[76:77], v[132:133]
	v_pk_add_f32 v[74:75], v[74:75], v[126:127]
	v_pk_add_f32 v[72:73], v[72:73], v[124:125]
	v_pk_add_f32 v[70:71], v[70:71], v[142:143]
	v_pk_add_f32 v[68:69], v[68:69], v[140:141]
	v_pk_add_f32 v[66:67], v[66:67], v[138:139]
	v_pk_add_f32 v[64:65], v[64:65], v[136:137]
.LBB0_1924:
	s_add_i32 s3, s22, 0xffffc000
	s_and_b32 s3, s3, 0x6000
	v_add_u32_e32 v123, s3, v114
	v_add_u32_e32 v140, v123, v118
	v_add_u32_e32 v136, v123, v117
	v_add_u32_e32 v132, v123, v116
	v_add_u32_e32 v123, v123, v115
	ds_read_b128 v[124:127], v123
	ds_read_b128 v[132:135], v132
	ds_read_b128 v[136:139], v136
	ds_read_b128 v[140:143], v140
	ds_read_b64_tr_b16 v[144:145], v121 offset:0x2000
	ds_read_b64_tr_b16 v[146:147], v121 offset:0x2800
	ds_read_b64_tr_b16 v[148:149], v121 offset:0x3000
	ds_read_b64_tr_b16 v[150:151], v121 offset:0x3800
	ds_read_b64_tr_b16 v[152:153], v121 offset:0x2200
	ds_read_b64_tr_b16 v[154:155], v121 offset:0x2a00
	ds_read_b64_tr_b16 v[156:157], v121 offset:0x3200
	ds_read_b64_tr_b16 v[158:159], v121 offset:0x3a00
	ds_read_b64_tr_b16 v[162:163], v121 offset:0x2400
	ds_read_b64_tr_b16 v[164:165], v121 offset:0x2c00
	ds_read_b64_tr_b16 v[166:167], v121 offset:0x3400
	ds_read_b64_tr_b16 v[168:169], v121 offset:0x3c00
	ds_read_b64_tr_b16 v[170:171], v121 offset:0x2600
	ds_read_b64_tr_b16 v[172:173], v121 offset:0x2e00
	ds_read_b64_tr_b16 v[174:175], v121 offset:0x3600
	ds_read_b64_tr_b16 v[176:177], v121 offset:0x3e00
	s_setprio 2
	v_exp_f32_e32 v64, v64
	v_exp_f32_e32 v65, v65
	v_exp_f32_e32 v66, v66
	v_exp_f32_e32 v67, v67
	v_exp_f32_e32 v68, v68
	v_add_f32_e32 v121, 0, v64
	v_exp_f32_e32 v69, v69
	v_add_f32_e32 v121, v65, v121
	v_exp_f32_e32 v70, v70
	v_add_f32_e32 v121, v66, v121
	v_exp_f32_e32 v71, v71
	v_add_f32_e32 v121, v67, v121
	v_exp_f32_e32 v72, v72
	v_add_f32_e32 v121, v68, v121
	v_exp_f32_e32 v73, v73
	v_add_f32_e32 v121, v69, v121
	v_exp_f32_e32 v74, v74
	v_add_f32_e32 v121, v70, v121
	v_exp_f32_e32 v75, v75
	v_add_f32_e32 v121, v71, v121
	v_exp_f32_e32 v76, v76
	v_add_f32_e32 v121, v72, v121
	v_exp_f32_e32 v77, v77
	v_add_f32_e32 v121, v73, v121
	v_exp_f32_e32 v78, v78
	v_add_f32_e32 v121, v74, v121
	v_exp_f32_e32 v79, v79
	v_add_f32_e32 v121, v75, v121
	v_add_f32_e32 v121, v76, v121
	v_add_f32_e32 v121, v77, v121
	v_add_f32_e32 v121, v78, v121
	v_add_f32_e32 v121, v79, v121
	v_add_f32_e32 v120, v120, v121
	v_cvt_pk_bf16_f32 v64, v64, v65
	v_cvt_pk_bf16_f32 v65, v66, v67
	v_cvt_pk_bf16_f32 v66, v68, v69
	v_cvt_pk_bf16_f32 v67, v70, v71
	v_cvt_pk_bf16_f32 v68, v72, v73
	v_cvt_pk_bf16_f32 v69, v74, v75
	v_cvt_pk_bf16_f32 v70, v76, v77
	v_cvt_pk_bf16_f32 v71, v78, v79
	s_nop 0
	v_permlane32_swap_b32_e32 v64, v66
	v_permlane32_swap_b32_e32 v65, v67
	v_permlane32_swap_b32_e32 v68, v70
	v_permlane32_swap_b32_e32 v69, v71
	s_waitcnt lgkmcnt(0)
	s_setprio 1
	s_cmp_lt_u32 s33, 0x100
	s_cbranch_scc1 .Lstg_d0_mid_11
	s_waitcnt vmcnt(3)
	s_barrier

; DI int v_rd_base(int lane) { return ((lane & 3) << 3) | (((lane >> 2) & 3) << 6) | (((lane >> 4) & 1) << 5) | (((lane >> 5) & 1) << 8); }
; template <int DQK, int MODE, int LDQ, int LDK, int LDV> ...
;     ...
;     const int vbase = (int)(unsigned)(size_t)lds + V_OFF + v_rd_base(lane);
;     ...
;     constexpr int NDA = ND0 > 6 ? 6 : ND0;
.Lstg_d0_t61_12:
	s_setprio 0
	v_lshl_add_u64 v[96:97], v[96:97], 1, s[56:57]
	s_mov_b32 m0, s0
	v_lshl_add_u64 v[98:99], v[98:99], 1, s[56:57]
	global_load_lds_dwordx4 v[96:97], off
	s_mov_b32 m0, s1
	s_cmp_lg_u32 s55, 61
	global_load_lds_dwordx4 v[98:99], off
	s_cselect_b64 s[0:1], -1, 0
	s_cmp_eq_u32 s58, 61
	s_cselect_b64 s[2:3], -1, 0
	s_cmp_lg_u32 s58, 61
	s_cselect_b64 s[4:5], -1, 0
	s_and_b64 s[0:1], s[4:5], s[0:1]
	s_and_b64 vcc, exec, s[0:1]
	s_cbranch_vccnz .LBB0_1930
	v_cndmask_b32_e64 v96, v112, v113, s[2:3]
	v_pk_mul_f32 v[14:15], v[14:15], v[96:97] op_sel_hi:[1,0]
	v_pk_mul_f32 v[12:13], v[12:13], v[96:97] op_sel_hi:[1,0]
	v_pk_mul_f32 v[10:11], v[10:11], v[96:97] op_sel_hi:[1,0]
	v_pk_mul_f32 v[8:9], v[8:9], v[96:97] op_sel_hi:[1,0]
	v_pk_mul_f32 v[6:7], v[6:7], v[96:97] op_sel_hi:[1,0]
	v_pk_mul_f32 v[4:5], v[4:5], v[96:97] op_sel_hi:[1,0]
	v_pk_mul_f32 v[2:3], v[2:3], v[96:97] op_sel_hi:[1,0]
	v_pk_mul_f32 v[0:1], v[0:1], v[96:97] op_sel_hi:[1,0]
	v_pk_mul_f32 v[62:63], v[62:63], v[96:97] op_sel_hi:[1,0]
	v_pk_mul_f32 v[60:61], v[60:61], v[96:97] op_sel_hi:[1,0]
	v_pk_mul_f32 v[58:59], v[58:59], v[96:97] op_sel_hi:[1,0]
	v_pk_mul_f32 v[56:57], v[56:57], v[96:97] op_sel_hi:[1,0]
	v_pk_mul_f32 v[54:55], v[54:55], v[96:97] op_sel_hi:[1,0]
	v_pk_mul_f32 v[52:53], v[52:53], v[96:97] op_sel_hi:[1,0]
	v_pk_mul_f32 v[50:51], v[50:51], v[96:97] op_sel_hi:[1,0]
	v_pk_mul_f32 v[48:49], v[48:49], v[96:97] op_sel_hi:[1,0]
	v_pk_mul_f32 v[46:47], v[46:47], v[96:97] op_sel_hi:[1,0]
	v_pk_mul_f32 v[44:45], v[44:45], v[96:97] op_sel_hi:[1,0]
	v_pk_mul_f32 v[42:43], v[42:43], v[96:97] op_sel_hi:[1,0]
	v_pk_mul_f32 v[40:41], v[40:41], v[96:97] op_sel_hi:[1,0]
	v_pk_mul_f32 v[38:39], v[38:39], v[96:97] op_sel_hi:[1,0]
	v_pk_mul_f32 v[36:37], v[36:37], v[96:97] op_sel_hi:[1,0]
	v_pk_mul_f32 v[34:35], v[34:35], v[96:97] op_sel_hi:[1,0]
	v_pk_mul_f32 v[32:33], v[32:33], v[96:97] op_sel_hi:[1,0]
	v_pk_mul_f32 v[30:31], v[30:31], v[96:97] op_sel_hi:[1,0]
	v_pk_mul_f32 v[28:29], v[28:29], v[96:97] op_sel_hi:[1,0]
	v_pk_mul_f32 v[26:27], v[26:27], v[96:97] op_sel_hi:[1,0]
	v_pk_mul_f32 v[24:25], v[24:25], v[96:97] op_sel_hi:[1,0]
	v_pk_mul_f32 v[22:23], v[22:23], v[96:97] op_sel_hi:[1,0]
	v_pk_mul_f32 v[20:21], v[20:21], v[96:97] op_sel_hi:[1,0]
	v_pk_mul_f32 v[18:19], v[18:19], v[96:97] op_sel_hi:[1,0]
	v_pk_mul_f32 v[16:17], v[16:17], v[96:97] op_sel_hi:[1,0]
	v_mul_f32_e32 v120, v120, v96
.LBB0_1930:
	s_mov_b64 s[96:97], 0xc00
	ds_read_b128 v[98:101], v107 offset:12288
	ds_read_b128 v[102:105], v108 offset:12288
	ds_read_b128 v[114:117], v109 offset:12288
	ds_read_b128 v[122:125], v110 offset:12288
	v_lshl_add_u32 v96, s64, 14, v106
	ds_read_b64_tr_b16 v[132:133], v96 offset:0
	ds_read_b64_tr_b16 v[134:135], v96 offset:0x800
	ds_read_b64_tr_b16 v[136:137], v96 offset:0x1000
	ds_read_b64_tr_b16 v[138:139], v96 offset:0x1800
	ds_read_b64_tr_b16 v[140:141], v96 offset:0x200
	ds_read_b64_tr_b16 v[142:143], v96 offset:0xa00
	ds_read_b64_tr_b16 v[144:145], v96 offset:0x1200
	ds_read_b64_tr_b16 v[146:147], v96 offset:0x1a00
	ds_read_b64_tr_b16 v[148:149], v96 offset:0x400
	ds_read_b64_tr_b16 v[150:151], v96 offset:0xc00
	ds_read_b64_tr_b16 v[152:153], v96 offset:0x1400
	ds_read_b64_tr_b16 v[154:155], v96 offset:0x1c00
	ds_read_b64_tr_b16 v[156:157], v96 offset:0x600
	ds_read_b64_tr_b16 v[158:159], v96 offset:0xe00
	ds_read_b64_tr_b16 v[162:163], v96 offset:0x1600
	ds_read_b64_tr_b16 v[164:165], v96 offset:0x1e00
	s_setprio 2
	v_exp_f32_e32 v64, v64
	v_exp_f32_e32 v65, v65
	v_exp_f32_e32 v66, v66
	v_exp_f32_e32 v67, v67
	v_exp_f32_e32 v68, v68
	v_add_f32_e32 v97, 0, v64
	v_exp_f32_e32 v69, v69
	v_add_f32_e32 v97, v65, v97
	v_exp_f32_e32 v70, v70
	v_add_f32_e32 v97, v66, v97
	v_exp_f32_e32 v71, v71
	v_add_f32_e32 v97, v67, v97
	v_exp_f32_e32 v72, v72
	v_add_f32_e32 v97, v68, v97
	v_exp_f32_e32 v73, v73
	v_add_f32_e32 v97, v69, v97
	v_exp_f32_e32 v74, v74
	v_add_f32_e32 v97, v70, v97
	v_exp_f32_e32 v75, v75
	v_add_f32_e32 v97, v71, v97
	v_exp_f32_e32 v76, v76
	v_add_f32_e32 v97, v72, v97
	v_exp_f32_e32 v77, v77
	v_add_f32_e32 v97, v73, v97
	v_exp_f32_e32 v78, v78
	v_add_f32_e32 v97, v74, v97
	v_exp_f32_e32 v79, v79
	v_add_f32_e32 v97, v75, v97
	v_add_f32_e32 v97, v76, v97
	v_add_f32_e32 v97, v77, v97
	v_add_f32_e32 v97, v78, v97
	v_add_f32_e32 v97, v79, v97
	v_add_f32_e32 v97, v97, v120
	v_cvt_pk_bf16_f32 v64, v64, v65
	v_cvt_pk_bf16_f32 v65, v66, v67
	v_cvt_pk_bf16_f32 v66, v68, v69
	v_cvt_pk_bf16_f32 v67, v70, v71
	v_cvt_pk_bf16_f32 v68, v72, v73
	v_cvt_pk_bf16_f32 v69, v74, v75
	v_cvt_pk_bf16_f32 v70, v76, v77
	v_cvt_pk_bf16_f32 v71, v78, v79
	s_nop 0
	v_permlane32_swap_b32_e32 v64, v66
	v_permlane32_swap_b32_e32 v65, v67
	v_permlane32_swap_b32_e32 v68, v70
	v_permlane32_swap_b32_e32 v69, v71
	s_waitcnt lgkmcnt(0)
	s_setprio 1
	v_mfma_f32_32x32x16_bf16 v[0:15], v[64:67], v[132:135], v[0:15]
	s_cmp_gt_i32 s55, 61
	s_cselect_b64 s[0:1], -1, 0
	s_cmp_lt_i32 s58, 62
	s_cselect_b64 s[2:3], -1, 0
	s_or_b64 s[0:1], s[0:1], s[2:3]
	s_and_b64 vcc, exec, s[0:1]
	v_mfma_f32_32x32x16_bf16 v[48:63], v[64:67], v[140:143], v[48:63]
	v_mfma_f32_32x32x16_bf16 v[32:47], v[64:67], v[148:151], v[32:47]
	v_mfma_f32_32x32x16_bf16 v[16:31], v[64:67], v[156:159], v[16:31]
	v_mfma_f32_32x32x16_bf16 v[0:15], v[68:71], v[136:139], v[0:15]
	v_mfma_f32_32x32x16_bf16 v[48:63], v[68:71], v[144:147], v[48:63]
	v_mfma_f32_32x32x16_bf16 v[32:47], v[68:71], v[152:155], v[32:47]
	v_mfma_f32_32x32x16_bf16 v[16:31], v[68:71], v[162:165], v[16:31]
	s_waitcnt lgkmcnt(0)
	v_mfma_f32_32x32x16_bf16 v[64:79], v[98:101], v[92:95], 0
	v_mfma_f32_32x32x16_bf16 v[64:79], v[102:105], v[88:91], v[64:79]
	v_mfma_f32_32x32x16_bf16 v[64:79], v[114:117], v[84:87], v[64:79]
	v_mfma_f32_32x32x16_bf16 v[64:79], v[122:125], v[80:83], v[64:79]
	s_setprio 0
	s_cbranch_vccnz .LBB0_1932
	v_sub_u32_e32 v98, 0xf40, v111
	v_lshlrev_b32_e32 v98, 2, v98
	v_add3_u32 v98, s88, v98, v130
	v_add_u32_e32 v114, 0x400, v98
	v_add_u32_e32 v116, 0x408, v98
	v_add_u32_e32 v118, 0x420, v98
	v_add_u32_e32 v120, 0x428, v98
	v_add_u32_e32 v99, 0x440, v98
	v_add_u32_e32 v100, 0x448, v98
	v_add_u32_e32 v102, 0x460, v98
	v_add_u32_e32 v104, 0x468, v98
	ds_read2_b32 v[98:99], v99 offset1:1
	ds_read2_b32 v[100:101], v100 offset1:1
	ds_read2_b32 v[102:103], v102 offset1:1
	ds_read2_b32 v[104:105], v104 offset1:1
	ds_read2_b32 v[114:115], v114 offset1:1
	ds_read2_b32 v[116:117], v116 offset1:1
	ds_read2_b32 v[118:119], v118 offset1:1
	ds_read2_b32 v[120:121], v120 offset1:1
	s_waitcnt lgkmcnt(0)
	v_pk_add_f32 v[78:79], v[78:79], v[104:105]
	v_pk_add_f32 v[76:77], v[76:77], v[102:103]
	v_pk_add_f32 v[74:75], v[74:75], v[100:101]
	v_pk_add_f32 v[72:73], v[72:73], v[98:99]
	v_pk_add_f32 v[70:71], v[70:71], v[120:121]
	v_pk_add_f32 v[68:69], v[68:69], v[118:119]
	v_pk_add_f32 v[66:67], v[66:67], v[116:117]
	v_pk_add_f32 v[64:65], v[64:65], v[114:115]
; #define SBAR() __builtin_amdgcn_sched_barrier(0)
; #define ATT_DMA_K(t) do { const bf16_t* kg_ = Kh + (size_t)(t) * 64 * LDK; LAS unsigned char* sb_ = lds + ((t) & 3) * KBUF; \
;     _Pragma("unroll") for (int i_ = 0; i_ < NKP; ++i_) __builtin_amdgcn_global_load_lds((const unsigned*)(kg_ + kgo[i_]), (LAS unsigned*)(sb_ + (wid + 8 * i_) * 1024), 16, 0, 0); } while (0)
; #define ATT_DMA_V(t, vs) do { const bf16_t* vg_ = Vh + (size_t)(t) * 64 * LDV; LAS unsigned char* sb_ = lds + V_OFF + (vs) * SHM_V; \
;     _Pragma("unroll") for (int i_ = 0; i_ < 2; ++i_) __builtin_amdgcn_global_load_lds((const unsigned*)(vg_ + vgo[i_]), (LAS unsigned*)(sb_ + (2 * wid + i_) * 1024), 16, 0, 0); } while (0)
; #define ATT_SEG(t) do { if constexpr (MODE != 0) { if (((t) == tL && tL > 0) || (t) == tR) { const float f_ = (t) == tR ? fR : fL; l_reg *= f_; \
;     _Pragma("unroll") for (int d = 0; d < 4; ++d) _Pragma("unroll") for (int r = 0; r < 16; ++r) o[d][r] *= f_; } } } while (0)
; #define ATT_BIAS(P, t, half) do { if constexpr (MODE != 0) { if ((t) >= tL && (t) < tR) { const LAS float* bp_ = bt + ((t) * 64 + (half) * 32 - qpos + 224 + 4 * hi);     \
;     _Pragma("unroll") for (int r = 0; r < 16; ++r) P[r] += bp_[(r & 3) + 8 * (r >> 2)]; } } } while (0)
; #define ATT_TOP(N) do { asm volatile("s_waitcnt vmcnt(%0)" :: "n"(N) : "memory"); __builtin_amdgcn_s_barrier(); asm volatile("" ::: "memory"); } while (0)
; #define ATT_LGKM0() do { SBAR(); asm volatile("s_waitcnt lgkmcnt(0)" ::: "memory"); SBAR(); } while (0)
; template <int DQK, int MODE, int LDQ, int LDK, int LDV> ...
;     ...
;     f32x16 pA, pB; bf16x8 pa0, pa1;
;     int v0 = 0, v1 = 1, v2 = 2;
;     ATT_TOP(NKP + 2);
;     { bf16x8 kf[NDA]; k_reads<DQK, 0, NDA>(kf, lds, 0, r32, hi); ATT_LGKM0(); qk_mma<0, NDA>(pA, kf, qr);
;       if constexpr (ND0 > NDA) { bf16x8 kg[ND0 - NDA]; k_reads<DQK, NDA, ND0>(kg, lds, 0, r32, hi); ATT_LGKM0(); qk_mma<NDA, ND0>(pA, kg, qr); }
;       ATT_BIAS(pA, 0, 0); }
;     if (wid >= 4) __builtin_amdgcn_s_setprio(1);
;     for (int j = 0; j < NT; ++j) {
;         if (j + 2 < NT) ATT_TOP(NKP + 2); else ATT_TOP(0);
;         if (j + 3 < NT) ATT_DMA_K(j + 3);
;         if (j + 2 < NT) ATT_DMA_V(j + 2, v2);
;         ATT_SEG(j); SBAR();
;         ATT_STEP(pA, pB, 0, v0, true, 1, j);
;         ATT_STEP(pB, pA, 1, v0, (j + 1 < NT), 0, j + 1);
.LBB0_1932:
	s_movk_i32 s64, 0x70
	ds_read_b128 v[98:101], v107 offset:16384
	ds_read_b128 v[102:105], v108 offset:16384
	ds_read_b128 v[114:117], v109 offset:16384
	ds_read_b128 v[118:121], v110 offset:16384
	ds_read_b64_tr_b16 v[122:123], v96 offset:0x2000
	ds_read_b64_tr_b16 v[124:125], v96 offset:0x2800
	ds_read_b64_tr_b16 v[132:133], v96 offset:0x3000
	ds_read_b64_tr_b16 v[134:135], v96 offset:0x3800
	ds_read_b64_tr_b16 v[136:137], v96 offset:0x2200
	ds_read_b64_tr_b16 v[138:139], v96 offset:0x2a00
	ds_read_b64_tr_b16 v[140:141], v96 offset:0x3200
	ds_read_b64_tr_b16 v[142:143], v96 offset:0x3a00
	ds_read_b64_tr_b16 v[144:145], v96 offset:0x2400
	ds_read_b64_tr_b16 v[146:147], v96 offset:0x2c00
	ds_read_b64_tr_b16 v[148:149], v96 offset:0x3400
	ds_read_b64_tr_b16 v[150:151], v96 offset:0x3c00
	ds_read_b64_tr_b16 v[152:153], v96 offset:0x2600
	ds_read_b64_tr_b16 v[154:155], v96 offset:0x2e00
	ds_read_b64_tr_b16 v[156:157], v96 offset:0x3600
	ds_read_b64_tr_b16 v[158:159], v96 offset:0x3e00
	s_nop 5
	s_setprio 2
	v_exp_f32_e32 v64, v64
	v_exp_f32_e32 v65, v65
	v_exp_f32_e32 v66, v66
	v_exp_f32_e32 v67, v67
	v_exp_f32_e32 v68, v68
	v_add_f32_e32 v96, 0, v64
	v_exp_f32_e32 v69, v69
	v_add_f32_e32 v96, v65, v96
	v_exp_f32_e32 v70, v70
	v_add_f32_e32 v96, v66, v96
	v_exp_f32_e32 v71, v71
	v_add_f32_e32 v96, v67, v96
	v_exp_f32_e32 v72, v72
	v_add_f32_e32 v96, v68, v96
	v_exp_f32_e32 v73, v73
	v_add_f32_e32 v96, v69, v96
	v_exp_f32_e32 v74, v74
	v_add_f32_e32 v96, v70, v96
	v_exp_f32_e32 v75, v75
	v_add_f32_e32 v96, v71, v96
	v_exp_f32_e32 v76, v76
	v_add_f32_e32 v96, v72, v96
	v_exp_f32_e32 v77, v77
	v_add_f32_e32 v96, v73, v96
	v_exp_f32_e32 v78, v78
	v_add_f32_e32 v96, v74, v96
	v_exp_f32_e32 v79, v79
	v_add_f32_e32 v96, v75, v96
	v_add_f32_e32 v96, v76, v96
	v_add_f32_e32 v96, v77, v96
	v_add_f32_e32 v96, v78, v96
	v_add_f32_e32 v96, v79, v96
	v_add_f32_e32 v96, v97, v96
	v_cvt_pk_bf16_f32 v64, v64, v65
	v_cvt_pk_bf16_f32 v65, v66, v67
	v_cvt_pk_bf16_f32 v66, v68, v69
	v_cvt_pk_bf16_f32 v67, v70, v71
	v_cvt_pk_bf16_f32 v68, v72, v73
	v_cvt_pk_bf16_f32 v69, v74, v75
	v_cvt_pk_bf16_f32 v70, v76, v77
	v_cvt_pk_bf16_f32 v71, v78, v79
	s_nop 0
	v_permlane32_swap_b32_e32 v64, v66
	v_permlane32_swap_b32_e32 v65, v67
	v_permlane32_swap_b32_e32 v68, v70
	v_permlane32_swap_b32_e32 v69, v71
	s_waitcnt lgkmcnt(0)
	s_setprio 1
	s_cmp_lt_u32 s33, 0x100
	s_cbranch_scc1 .Lstg_d0_m61_13
	s_waitcnt vmcnt(0)
	s_barrier

; DI int v_rd_base(int lane) { return ((lane & 3) << 3) | (((lane >> 2) & 3) << 6) | (((lane >> 4) & 1) << 5) | (((lane >> 5) & 1) << 8); }
; template <int DQK, int MODE, int LDQ, int LDK, int LDV> ...
;     ...
;     const int vbase = (int)(unsigned)(size_t)lds + V_OFF + v_rd_base(lane);
;     ...
;     constexpr int NDA = ND0 > 6 ? 6 : ND0;
.Lstg_d0_t62_14:
	s_setprio 0
	s_cmp_lg_u32 s58, 62
	s_cselect_b64 s[6:7], -1, 0
	s_and_b64 s[0:1], s[6:7], s[0:1]
	s_and_b64 vcc, exec, s[0:1]
	s_cbranch_vccnz .LBB0_1936
	v_cndmask_b32_e64 v98, v112, v113, s[4:5]
	v_pk_mul_f32 v[14:15], v[98:99], v[14:15] op_sel_hi:[0,1]
	v_pk_mul_f32 v[12:13], v[98:99], v[12:13] op_sel_hi:[0,1]
	v_pk_mul_f32 v[10:11], v[98:99], v[10:11] op_sel_hi:[0,1]
	v_pk_mul_f32 v[8:9], v[98:99], v[8:9] op_sel_hi:[0,1]
	v_pk_mul_f32 v[6:7], v[98:99], v[6:7] op_sel_hi:[0,1]
	v_pk_mul_f32 v[4:5], v[98:99], v[4:5] op_sel_hi:[0,1]
	v_pk_mul_f32 v[2:3], v[98:99], v[2:3] op_sel_hi:[0,1]
	v_pk_mul_f32 v[0:1], v[98:99], v[0:1] op_sel_hi:[0,1]
	v_pk_mul_f32 v[62:63], v[98:99], v[62:63] op_sel_hi:[0,1]
	v_pk_mul_f32 v[60:61], v[98:99], v[60:61] op_sel_hi:[0,1]
	v_pk_mul_f32 v[58:59], v[98:99], v[58:59] op_sel_hi:[0,1]
	v_pk_mul_f32 v[56:57], v[98:99], v[56:57] op_sel_hi:[0,1]
	v_pk_mul_f32 v[54:55], v[98:99], v[54:55] op_sel_hi:[0,1]
	v_pk_mul_f32 v[52:53], v[98:99], v[52:53] op_sel_hi:[0,1]
	v_pk_mul_f32 v[50:51], v[98:99], v[50:51] op_sel_hi:[0,1]
	v_pk_mul_f32 v[48:49], v[98:99], v[48:49] op_sel_hi:[0,1]
	v_pk_mul_f32 v[46:47], v[98:99], v[46:47] op_sel_hi:[0,1]
	v_pk_mul_f32 v[44:45], v[98:99], v[44:45] op_sel_hi:[0,1]
	v_pk_mul_f32 v[42:43], v[98:99], v[42:43] op_sel_hi:[0,1]
	v_pk_mul_f32 v[40:41], v[98:99], v[40:41] op_sel_hi:[0,1]
	v_pk_mul_f32 v[38:39], v[98:99], v[38:39] op_sel_hi:[0,1]
	v_pk_mul_f32 v[36:37], v[98:99], v[36:37] op_sel_hi:[0,1]
	v_pk_mul_f32 v[34:35], v[98:99], v[34:35] op_sel_hi:[0,1]
	v_pk_mul_f32 v[32:33], v[98:99], v[32:33] op_sel_hi:[0,1]
	v_pk_mul_f32 v[30:31], v[98:99], v[30:31] op_sel_hi:[0,1]
	v_pk_mul_f32 v[28:29], v[98:99], v[28:29] op_sel_hi:[0,1]
	v_pk_mul_f32 v[26:27], v[98:99], v[26:27] op_sel_hi:[0,1]
	v_pk_mul_f32 v[24:25], v[98:99], v[24:25] op_sel_hi:[0,1]
	v_pk_mul_f32 v[22:23], v[98:99], v[22:23] op_sel_hi:[0,1]
	v_pk_mul_f32 v[20:21], v[98:99], v[20:21] op_sel_hi:[0,1]
	v_pk_mul_f32 v[18:19], v[98:99], v[18:19] op_sel_hi:[0,1]
	v_pk_mul_f32 v[16:17], v[98:99], v[16:17] op_sel_hi:[0,1]
	v_mul_f32_e32 v96, v98, v96
.LBB0_1936:
	ds_read_b128 v[100:103], v107 offset:20480
	ds_read_b128 v[114:117], v108 offset:20480
	ds_read_b128 v[118:121], v109 offset:20480
	ds_read_b128 v[122:125], v110 offset:20480
	v_add_u32_e32 v98, 0x8000, v106
	ds_read_b64_tr_b16 v[132:133], v98 offset:0
	ds_read_b64_tr_b16 v[134:135], v98 offset:0x800
	ds_read_b64_tr_b16 v[136:137], v98 offset:0x1000
	ds_read_b64_tr_b16 v[138:139], v98 offset:0x1800
	ds_read_b64_tr_b16 v[140:141], v98 offset:0x200
	ds_read_b64_tr_b16 v[142:143], v98 offset:0xa00
	ds_read_b64_tr_b16 v[144:145], v98 offset:0x1200
	ds_read_b64_tr_b16 v[146:147], v98 offset:0x1a00
	ds_read_b64_tr_b16 v[148:149], v98 offset:0x400
	ds_read_b64_tr_b16 v[150:151], v98 offset:0xc00
	ds_read_b64_tr_b16 v[152:153], v98 offset:0x1400
	ds_read_b64_tr_b16 v[154:155], v98 offset:0x1c00
	ds_read_b64_tr_b16 v[156:157], v98 offset:0x600
	ds_read_b64_tr_b16 v[158:159], v98 offset:0xe00
	ds_read_b64_tr_b16 v[162:163], v98 offset:0x1600
	ds_read_b64_tr_b16 v[164:165], v98 offset:0x1e00
	s_setprio 2
	v_exp_f32_e32 v64, v64
	v_exp_f32_e32 v65, v65
	v_exp_f32_e32 v66, v66
	v_exp_f32_e32 v67, v67
	v_exp_f32_e32 v68, v68
	v_add_f32_e32 v99, 0, v64
	v_exp_f32_e32 v69, v69
	v_add_f32_e32 v99, v65, v99
	v_exp_f32_e32 v70, v70
	v_add_f32_e32 v99, v66, v99
	v_exp_f32_e32 v71, v71
	v_add_f32_e32 v99, v67, v99
	v_exp_f32_e32 v72, v72
	v_add_f32_e32 v99, v68, v99
	v_exp_f32_e32 v73, v73
	v_add_f32_e32 v99, v69, v99
	v_exp_f32_e32 v74, v74
	v_add_f32_e32 v99, v70, v99
	v_exp_f32_e32 v75, v75
	v_add_f32_e32 v99, v71, v99
	v_exp_f32_e32 v76, v76
	v_add_f32_e32 v99, v72, v99
	v_exp_f32_e32 v77, v77
	v_add_f32_e32 v99, v73, v99
	v_exp_f32_e32 v78, v78
	v_add_f32_e32 v99, v74, v99
	v_exp_f32_e32 v79, v79
	v_add_f32_e32 v99, v75, v99
	v_add_f32_e32 v99, v76, v99
	v_add_f32_e32 v99, v77, v99
	v_add_f32_e32 v99, v78, v99
	v_add_f32_e32 v99, v79, v99
	v_add_f32_e32 v96, v99, v96
	v_cvt_pk_bf16_f32 v64, v64, v65
	v_cvt_pk_bf16_f32 v65, v66, v67
	v_cvt_pk_bf16_f32 v66, v68, v69
	v_cvt_pk_bf16_f32 v67, v70, v71
	v_cvt_pk_bf16_f32 v68, v72, v73
	v_cvt_pk_bf16_f32 v69, v74, v75
	v_cvt_pk_bf16_f32 v70, v76, v77
	v_cvt_pk_bf16_f32 v71, v78, v79
	s_nop 0
	v_permlane32_swap_b32_e32 v64, v66
	v_permlane32_swap_b32_e32 v65, v67
	v_permlane32_swap_b32_e32 v68, v70
	v_permlane32_swap_b32_e32 v69, v71
	s_waitcnt lgkmcnt(0)
	s_setprio 1
	v_mfma_f32_32x32x16_bf16 v[0:15], v[64:67], v[132:135], v[0:15]
	s_and_b64 vcc, exec, s[2:3]
	v_mfma_f32_32x32x16_bf16 v[48:63], v[64:67], v[140:143], v[48:63]
	v_mfma_f32_32x32x16_bf16 v[32:47], v[64:67], v[148:151], v[32:47]
	v_mfma_f32_32x32x16_bf16 v[16:31], v[64:67], v[156:159], v[16:31]
	v_mfma_f32_32x32x16_bf16 v[0:15], v[68:71], v[136:139], v[0:15]
	v_mfma_f32_32x32x16_bf16 v[48:63], v[68:71], v[144:147], v[48:63]
	v_mfma_f32_32x32x16_bf16 v[32:47], v[68:71], v[152:155], v[32:47]
	v_mfma_f32_32x32x16_bf16 v[16:31], v[68:71], v[162:165], v[16:31]
	s_waitcnt lgkmcnt(0)
	v_mfma_f32_32x32x16_bf16 v[64:79], v[100:103], v[92:95], 0
	v_mfma_f32_32x32x16_bf16 v[64:79], v[114:117], v[88:91], v[64:79]
	v_mfma_f32_32x32x16_bf16 v[64:79], v[118:121], v[84:87], v[64:79]
	v_mfma_f32_32x32x16_bf16 v[64:79], v[122:125], v[80:83], v[64:79]
	s_setprio 0
	s_cbranch_vccnz .LBB0_1938
	v_add3_u32 v97, s88, v97, v130
	v_add_u32_e32 v118, 0x408, v97
	v_add_u32_e32 v120, 0x420, v97
	v_add_u32_e32 v122, 0x428, v97
	v_add_u32_e32 v100, 0x440, v97
	v_add_u32_e32 v102, 0x448, v97
	v_add_u32_e32 v104, 0x460, v97
	v_add_u32_e32 v99, 0x400, v97
	v_add_u32_e32 v97, 0x468, v97
	ds_read2_b32 v[100:101], v100 offset1:1
	ds_read2_b32 v[102:103], v102 offset1:1
	ds_read2_b32 v[104:105], v104 offset1:1
	ds_read2_b32 v[114:115], v97 offset1:1
	ds_read2_b32 v[116:117], v99 offset1:1
	ds_read2_b32 v[118:119], v118 offset1:1
	ds_read2_b32 v[120:121], v120 offset1:1
	ds_read2_b32 v[122:123], v122 offset1:1
	s_waitcnt lgkmcnt(0)
	v_pk_add_f32 v[78:79], v[78:79], v[114:115]
	v_pk_add_f32 v[76:77], v[76:77], v[104:105]
	v_pk_add_f32 v[74:75], v[74:75], v[102:103]
	v_pk_add_f32 v[72:73], v[72:73], v[100:101]
	v_pk_add_f32 v[70:71], v[70:71], v[122:123]
	v_pk_add_f32 v[68:69], v[68:69], v[120:121]
	v_pk_add_f32 v[66:67], v[66:67], v[118:119]
	v_pk_add_f32 v[64:65], v[64:65], v[116:117]
; #define SBAR() __builtin_amdgcn_sched_barrier(0)
; #define ATT_DMA_K(t) do { const bf16_t* kg_ = Kh + (size_t)(t) * 64 * LDK; LAS unsigned char* sb_ = lds + ((t) & 3) * KBUF; \
;     _Pragma("unroll") for (int i_ = 0; i_ < NKP; ++i_) __builtin_amdgcn_global_load_lds((const unsigned*)(kg_ + kgo[i_]), (LAS unsigned*)(sb_ + (wid + 8 * i_) * 1024), 16, 0, 0); } while (0)
; #define ATT_DMA_V(t, vs) do { const bf16_t* vg_ = Vh + (size_t)(t) * 64 * LDV; LAS unsigned char* sb_ = lds + V_OFF + (vs) * SHM_V; \
;     _Pragma("unroll") for (int i_ = 0; i_ < 2; ++i_) __builtin_amdgcn_global_load_lds((const unsigned*)(vg_ + vgo[i_]), (LAS unsigned*)(sb_ + (2 * wid + i_) * 1024), 16, 0, 0); } while (0)
; #define ATT_SEG(t) do { if constexpr (MODE != 0) { if (((t) == tL && tL > 0) || (t) == tR) { const float f_ = (t) == tR ? fR : fL; l_reg *= f_; \
;     _Pragma("unroll") for (int d = 0; d < 4; ++d) _Pragma("unroll") for (int r = 0; r < 16; ++r) o[d][r] *= f_; } } } while (0)
; #define ATT_BIAS(P, t, half) do { if constexpr (MODE != 0) { if ((t) >= tL && (t) < tR) { const LAS float* bp_ = bt + ((t) * 64 + (half) * 32 - qpos + 224 + 4 * hi);     \
;     _Pragma("unroll") for (int r = 0; r < 16; ++r) P[r] += bp_[(r & 3) + 8 * (r >> 2)]; } } } while (0)
; #define ATT_TOP(N) do { asm volatile("s_waitcnt vmcnt(%0)" :: "n"(N) : "memory"); __builtin_amdgcn_s_barrier(); asm volatile("" ::: "memory"); } while (0)
; #define ATT_LGKM0() do { SBAR(); asm volatile("s_waitcnt lgkmcnt(0)" ::: "memory"); SBAR(); } while (0)
; template <int DQK, int MODE, int LDQ, int LDK, int LDV> ...
;     ...
;     f32x16 pA, pB; bf16x8 pa0, pa1;
;     int v0 = 0, v1 = 1, v2 = 2;
;     ATT_TOP(NKP + 2);
;     { bf16x8 kf[NDA]; k_reads<DQK, 0, NDA>(kf, lds, 0, r32, hi); ATT_LGKM0(); qk_mma<0, NDA>(pA, kf, qr);
;       if constexpr (ND0 > NDA) { bf16x8 kg[ND0 - NDA]; k_reads<DQK, NDA, ND0>(kg, lds, 0, r32, hi); ATT_LGKM0(); qk_mma<NDA, ND0>(pA, kg, qr); }
;       ATT_BIAS(pA, 0, 0); }
;     if (wid >= 4) __builtin_amdgcn_s_setprio(1);
;     for (int j = 0; j < NT; ++j) {
;         if (j + 2 < NT) ATT_TOP(NKP + 2); else ATT_TOP(0);
;         if (j + 3 < NT) ATT_DMA_K(j + 3);
;         if (j + 2 < NT) ATT_DMA_V(j + 2, v2);
;         ATT_SEG(j); SBAR();
;         ATT_STEP(pA, pB, 0, v0, true, 1, j);
;         ATT_STEP(pB, pA, 1, v0, (j + 1 < NT), 0, j + 1);
.LBB0_1938:
	ds_read_b128 v[100:103], v107 offset:24576
	ds_read_b128 v[114:117], v108 offset:24576
	ds_read_b128 v[118:121], v109 offset:24576
	ds_read_b128 v[122:125], v110 offset:24576
	ds_read_b64_tr_b16 v[132:133], v98 offset:0x2000
	ds_read_b64_tr_b16 v[134:135], v98 offset:0x2800
	ds_read_b64_tr_b16 v[136:137], v98 offset:0x3000
	ds_read_b64_tr_b16 v[138:139], v98 offset:0x3800
	ds_read_b64_tr_b16 v[140:141], v98 offset:0x2200
	ds_read_b64_tr_b16 v[142:143], v98 offset:0x2a00
	ds_read_b64_tr_b16 v[144:145], v98 offset:0x3200
	ds_read_b64_tr_b16 v[146:147], v98 offset:0x3a00
	ds_read_b64_tr_b16 v[148:149], v98 offset:0x2400
	ds_read_b64_tr_b16 v[150:151], v98 offset:0x2c00
	ds_read_b64_tr_b16 v[152:153], v98 offset:0x3400
	ds_read_b64_tr_b16 v[154:155], v98 offset:0x3c00
	ds_read_b64_tr_b16 v[156:157], v98 offset:0x2600
	ds_read_b64_tr_b16 v[158:159], v98 offset:0x2e00
	ds_read_b64_tr_b16 v[162:163], v98 offset:0x3600
	ds_read_b64_tr_b16 v[164:165], v98 offset:0x3e00
	s_nop 6
	s_setprio 2
	v_exp_f32_e32 v64, v64
	v_exp_f32_e32 v65, v65
	v_exp_f32_e32 v66, v66
	v_exp_f32_e32 v67, v67
	v_exp_f32_e32 v68, v68
	v_add_f32_e32 v97, 0, v64
	v_exp_f32_e32 v69, v69
	v_add_f32_e32 v97, v65, v97
	v_exp_f32_e32 v70, v70
	v_add_f32_e32 v97, v66, v97
	v_exp_f32_e32 v71, v71
	v_add_f32_e32 v97, v67, v97
	v_exp_f32_e32 v72, v72
	v_add_f32_e32 v97, v68, v97
	v_exp_f32_e32 v73, v73
	v_add_f32_e32 v97, v69, v97
	v_exp_f32_e32 v74, v74
	v_add_f32_e32 v97, v70, v97
	v_exp_f32_e32 v75, v75
	v_add_f32_e32 v97, v71, v97
	v_exp_f32_e32 v76, v76
	v_add_f32_e32 v97, v72, v97
	v_exp_f32_e32 v77, v77
	v_add_f32_e32 v97, v73, v97
	v_exp_f32_e32 v78, v78
	v_add_f32_e32 v97, v74, v97
	v_exp_f32_e32 v79, v79
	v_add_f32_e32 v97, v75, v97
	v_add_f32_e32 v97, v76, v97
	v_add_f32_e32 v97, v77, v97
	v_add_f32_e32 v97, v78, v97
	v_add_f32_e32 v97, v79, v97
	v_add_f32_e32 v96, v96, v97
	v_cvt_pk_bf16_f32 v64, v64, v65
	v_cvt_pk_bf16_f32 v65, v66, v67
	v_cvt_pk_bf16_f32 v66, v68, v69
	v_cvt_pk_bf16_f32 v67, v70, v71
	v_cvt_pk_bf16_f32 v68, v72, v73
	v_cvt_pk_bf16_f32 v69, v74, v75
	v_cvt_pk_bf16_f32 v70, v76, v77
	v_cvt_pk_bf16_f32 v71, v78, v79
	s_nop 0
	v_permlane32_swap_b32_e32 v64, v66
	v_permlane32_swap_b32_e32 v65, v67
	v_permlane32_swap_b32_e32 v68, v70
	v_permlane32_swap_b32_e32 v69, v71
	s_waitcnt lgkmcnt(0)
	s_setprio 1
	s_cmp_lt_u32 s33, 0x100
	s_cbranch_scc1 .Lstg_d0_m62_15
	s_waitcnt vmcnt(0)
	s_barrier

; DI int v_rd_base(int lane) { return ((lane & 3) << 3) | (((lane >> 2) & 3) << 6) | (((lane >> 4) & 1) << 5) | (((lane >> 5) & 1) << 8); }
; template <int DQK, int MODE, int LDQ, int LDK, int LDV> ...
;     ...
;     const int vbase = (int)(unsigned)(size_t)lds + V_OFF + v_rd_base(lane);
;     ...
;     constexpr int NDA = ND0 > 6 ? 6 : ND0;
.Lstg_d0_t63_16:
	s_setprio 0
	s_cmp_lg_u32 s58, 63
	s_cselect_b64 s[6:7], -1, 0
	s_and_b64 s[0:1], s[6:7], s[0:1]
	s_and_b64 vcc, exec, s[0:1]
	s_cbranch_vccnz .LBB0_1942
	v_cndmask_b32_e64 v98, v112, v113, s[4:5]
	v_pk_mul_f32 v[14:15], v[98:99], v[14:15] op_sel_hi:[0,1]
	v_pk_mul_f32 v[12:13], v[98:99], v[12:13] op_sel_hi:[0,1]
	v_pk_mul_f32 v[10:11], v[98:99], v[10:11] op_sel_hi:[0,1]
	v_pk_mul_f32 v[8:9], v[98:99], v[8:9] op_sel_hi:[0,1]
	v_pk_mul_f32 v[6:7], v[98:99], v[6:7] op_sel_hi:[0,1]
	v_pk_mul_f32 v[4:5], v[98:99], v[4:5] op_sel_hi:[0,1]
	v_pk_mul_f32 v[2:3], v[98:99], v[2:3] op_sel_hi:[0,1]
	v_pk_mul_f32 v[0:1], v[98:99], v[0:1] op_sel_hi:[0,1]
	v_pk_mul_f32 v[62:63], v[98:99], v[62:63] op_sel_hi:[0,1]
	v_pk_mul_f32 v[60:61], v[98:99], v[60:61] op_sel_hi:[0,1]
	v_pk_mul_f32 v[58:59], v[98:99], v[58:59] op_sel_hi:[0,1]
	v_pk_mul_f32 v[56:57], v[98:99], v[56:57] op_sel_hi:[0,1]
	v_pk_mul_f32 v[54:55], v[98:99], v[54:55] op_sel_hi:[0,1]
	v_pk_mul_f32 v[52:53], v[98:99], v[52:53] op_sel_hi:[0,1]
	v_pk_mul_f32 v[50:51], v[98:99], v[50:51] op_sel_hi:[0,1]
	v_pk_mul_f32 v[48:49], v[98:99], v[48:49] op_sel_hi:[0,1]
	v_pk_mul_f32 v[46:47], v[98:99], v[46:47] op_sel_hi:[0,1]
	v_pk_mul_f32 v[44:45], v[98:99], v[44:45] op_sel_hi:[0,1]
	v_pk_mul_f32 v[42:43], v[98:99], v[42:43] op_sel_hi:[0,1]
	v_pk_mul_f32 v[40:41], v[98:99], v[40:41] op_sel_hi:[0,1]
	v_pk_mul_f32 v[38:39], v[98:99], v[38:39] op_sel_hi:[0,1]
	v_pk_mul_f32 v[36:37], v[98:99], v[36:37] op_sel_hi:[0,1]
	v_pk_mul_f32 v[34:35], v[98:99], v[34:35] op_sel_hi:[0,1]
	v_pk_mul_f32 v[32:33], v[98:99], v[32:33] op_sel_hi:[0,1]
	v_pk_mul_f32 v[30:31], v[98:99], v[30:31] op_sel_hi:[0,1]
	v_pk_mul_f32 v[28:29], v[98:99], v[28:29] op_sel_hi:[0,1]
	v_pk_mul_f32 v[26:27], v[98:99], v[26:27] op_sel_hi:[0,1]
	v_pk_mul_f32 v[24:25], v[98:99], v[24:25] op_sel_hi:[0,1]
	v_pk_mul_f32 v[22:23], v[98:99], v[22:23] op_sel_hi:[0,1]
	v_pk_mul_f32 v[20:21], v[98:99], v[20:21] op_sel_hi:[0,1]
	v_pk_mul_f32 v[18:19], v[98:99], v[18:19] op_sel_hi:[0,1]
	v_pk_mul_f32 v[16:17], v[98:99], v[16:17] op_sel_hi:[0,1]
	v_mul_f32_e32 v96, v98, v96
.LBB0_1942:
	ds_read_b128 v[98:101], v107 offset:28672
	ds_read_b128 v[102:105], v108 offset:28672
	ds_read_b128 v[112:115], v109 offset:28672
	ds_read_b128 v[108:111], v110 offset:28672
	ds_read_b64_tr_b16 v[116:117], v106 offset:0
	ds_read_b64_tr_b16 v[118:119], v106 offset:0x800
	ds_read_b64_tr_b16 v[120:121], v106 offset:0x1000
	ds_read_b64_tr_b16 v[122:123], v106 offset:0x1800
	ds_read_b64_tr_b16 v[124:125], v106 offset:0x200
	ds_read_b64_tr_b16 v[126:127], v106 offset:0xa00
	ds_read_b64_tr_b16 v[132:133], v106 offset:0x1200
	ds_read_b64_tr_b16 v[134:135], v106 offset:0x1a00
	ds_read_b64_tr_b16 v[136:137], v106 offset:0x400
	ds_read_b64_tr_b16 v[138:139], v106 offset:0xc00
	ds_read_b64_tr_b16 v[140:141], v106 offset:0x1400
	ds_read_b64_tr_b16 v[142:143], v106 offset:0x1c00
	ds_read_b64_tr_b16 v[144:145], v106 offset:0x600
	ds_read_b64_tr_b16 v[146:147], v106 offset:0xe00
	ds_read_b64_tr_b16 v[148:149], v106 offset:0x1600
	ds_read_b64_tr_b16 v[150:151], v106 offset:0x1e00
	s_setprio 2
	v_exp_f32_e32 v64, v64
	v_exp_f32_e32 v65, v65
	v_exp_f32_e32 v66, v66
	v_exp_f32_e32 v67, v67
	v_exp_f32_e32 v68, v68
	v_add_f32_e32 v107, 0, v64
	v_exp_f32_e32 v69, v69
	v_add_f32_e32 v107, v65, v107
	v_exp_f32_e32 v70, v70
	v_add_f32_e32 v107, v66, v107
	v_exp_f32_e32 v71, v71
	v_add_f32_e32 v107, v67, v107
	v_exp_f32_e32 v72, v72
	v_add_f32_e32 v107, v68, v107
	v_exp_f32_e32 v73, v73
	v_add_f32_e32 v107, v69, v107
	v_exp_f32_e32 v74, v74
	v_add_f32_e32 v107, v70, v107
	v_exp_f32_e32 v75, v75
	v_add_f32_e32 v107, v71, v107
	v_exp_f32_e32 v76, v76
	v_add_f32_e32 v107, v72, v107
	v_exp_f32_e32 v77, v77
	v_add_f32_e32 v107, v73, v107
	v_exp_f32_e32 v78, v78
	v_add_f32_e32 v107, v74, v107
	v_exp_f32_e32 v79, v79
	v_add_f32_e32 v107, v75, v107
	v_add_f32_e32 v107, v76, v107
	v_add_f32_e32 v107, v77, v107
	v_add_f32_e32 v107, v78, v107
	v_add_f32_e32 v107, v79, v107
	v_add_f32_e32 v96, v107, v96
	v_cvt_pk_bf16_f32 v64, v64, v65
	v_cvt_pk_bf16_f32 v65, v66, v67
	v_cvt_pk_bf16_f32 v66, v68, v69
	v_cvt_pk_bf16_f32 v67, v70, v71
	v_cvt_pk_bf16_f32 v68, v72, v73
	v_cvt_pk_bf16_f32 v69, v74, v75
	v_cvt_pk_bf16_f32 v70, v76, v77
	v_cvt_pk_bf16_f32 v71, v78, v79
	s_nop 0
	v_permlane32_swap_b32_e32 v64, v66
	v_permlane32_swap_b32_e32 v65, v67
	v_permlane32_swap_b32_e32 v68, v70
	v_permlane32_swap_b32_e32 v69, v71
	s_waitcnt lgkmcnt(0)
	s_setprio 1
	v_mfma_f32_32x32x16_bf16 v[0:15], v[64:67], v[116:119], v[0:15]
	s_and_b64 vcc, exec, s[2:3]
	v_mfma_f32_32x32x16_bf16 v[48:63], v[64:67], v[124:127], v[48:63]
	v_mfma_f32_32x32x16_bf16 v[32:47], v[64:67], v[136:139], v[32:47]
	v_mfma_f32_32x32x16_bf16 v[16:31], v[64:67], v[144:147], v[16:31]
	v_mfma_f32_32x32x16_bf16 v[0:15], v[68:71], v[120:123], v[0:15]
	v_mfma_f32_32x32x16_bf16 v[48:63], v[68:71], v[132:135], v[48:63]
	v_mfma_f32_32x32x16_bf16 v[32:47], v[68:71], v[140:143], v[32:47]
	v_mfma_f32_32x32x16_bf16 v[16:31], v[68:71], v[148:151], v[16:31]
	s_waitcnt lgkmcnt(0)
	v_mfma_f32_32x32x16_bf16 v[64:79], v[98:101], v[92:95], 0
	v_mfma_f32_32x32x16_bf16 v[64:79], v[102:105], v[88:91], v[64:79]
	v_mfma_f32_32x32x16_bf16 v[64:79], v[112:115], v[84:87], v[64:79]
	v_mfma_f32_32x32x16_bf16 v[64:79], v[108:111], v[80:83], v[64:79]
	s_setprio 0
	s_cbranch_vccnz .LBB0_1944
	v_add3_u32 v80, s88, v97, v130
	v_add_u32_e32 v88, 0x400, v80
	v_add_u32_e32 v90, 0x408, v80
	v_add_u32_e32 v92, 0x420, v80
	v_add_u32_e32 v94, 0x428, v80
	v_add_u32_e32 v81, 0x440, v80
	v_add_u32_e32 v82, 0x448, v80
	v_add_u32_e32 v84, 0x460, v80
	v_add_u32_e32 v86, 0x468, v80
	ds_read2_b32 v[80:81], v81 offset1:1
	ds_read2_b32 v[82:83], v82 offset1:1
	ds_read2_b32 v[84:85], v84 offset1:1
	ds_read2_b32 v[86:87], v86 offset1:1
	ds_read2_b32 v[88:89], v88 offset1:1
	ds_read2_b32 v[90:91], v90 offset1:1
	ds_read2_b32 v[92:93], v92 offset1:1
	ds_read2_b32 v[94:95], v94 offset1:1
	s_waitcnt lgkmcnt(0)
	v_pk_add_f32 v[78:79], v[78:79], v[86:87]
	v_pk_add_f32 v[76:77], v[76:77], v[84:85]
	v_pk_add_f32 v[74:75], v[74:75], v[82:83]
	v_pk_add_f32 v[72:73], v[72:73], v[80:81]
	v_pk_add_f32 v[70:71], v[70:71], v[94:95]
	v_pk_add_f32 v[68:69], v[68:69], v[92:93]
	v_pk_add_f32 v[66:67], v[66:67], v[90:91]
	v_pk_add_f32 v[64:65], v[64:65], v[88:89]
; template <int TAG = 0> DI int fresh_tid(int wv) { int l; asm volatile("v_mbcnt_lo_u32_b32 %0, -1, 0\n\tv_mbcnt_hi_u32_b32 %0, -1, %0 ; site %1" : "=v"(l) : "n"(TAG)); return wv * 64 + l; }
; DI unsigned short f2bf(float x) { unsigned u = __float_as_uint(x); u += 0x7fffu + ((u >> 16) & 1u); return (unsigned short)(u >> 16); }
; DI int crow(int r, int hi) { return (r & 3) + 8 * (r >> 2) + 4 * hi; }
; DI float swap_sum(float v) { auto rr = __builtin_amdgcn_permlane32_swap(__float_as_uint(v), __float_as_uint(v), false, false); return __uint_as_float(rr[0]) + __uint_as_float(rr[1]); }
; template <int DQK, int MODE, int LDQ, int LDK, int LDV> ...
;     ...
;     l_reg = swap_sum(l_reg);
;     { const int lane2 = fresh_tid<110 + MODE>(wv) & 63, r32 = lane2 & 31, hi = lane2 >> 5;
;     if (hi == 0) li_l[r32] = l_reg;
;     asm volatile("s_waitcnt lgkmcnt(0)" ::: "memory");
;     float s0v[MODE == 2 ? 16 : 1][4];
;     if constexpr (MODE == 2) {
; #pragma unroll
;         for (int r = 0; r < 16; ++r)
; #pragma unroll
;             for (int d0 = 0; d0 < 4; ++d0) s0v[r][d0] = S0[(size_t)(wid * 32 + crow(r, hi)) * 512 + d0 * 32 + r32];
;     }
; #pragma unroll
;     for (int r = 0; r < 16; ++r) { const int orow = wid * 32 + crow(r, hi); const float rl = __builtin_amdgcn_rcpf(li_l[crow(r, hi)]);
;         if constexpr (MODE == 0) {
; #pragma unroll
;             for (int d0 = 0; d0 < 4; ++d0) AOb[(size_t)orow * 1024 + d0 * 32 + r32] = f2bf(o[d0][r] * rl);
;         } else if constexpr (MODE == 1) {
; #pragma unroll
;             for (int d0 = 0; d0 < 4; ++d0) S0[(size_t)orow * 512 + d0 * 32 + r32] = o[d0][r] * rl;
.LBB0_1944:
	s_lshl_b32 s0, s54, 2
	s_add_i32 s0, s0, 0
	s_add_i32 s0, s0, 0x24000
	ds_read_b64_tr_b16 v[80:81], v106 offset:0x2000
	ds_read_b64_tr_b16 v[82:83], v106 offset:0x2800
	ds_read_b64_tr_b16 v[84:85], v106 offset:0x3000
	ds_read_b64_tr_b16 v[86:87], v106 offset:0x3800
	ds_read_b64_tr_b16 v[88:89], v106 offset:0x2200
	ds_read_b64_tr_b16 v[90:91], v106 offset:0x2a00
	ds_read_b64_tr_b16 v[92:93], v106 offset:0x3200
	ds_read_b64_tr_b16 v[94:95], v106 offset:0x3a00
	ds_read_b64_tr_b16 v[98:99], v106 offset:0x2400
	ds_read_b64_tr_b16 v[100:101], v106 offset:0x2c00
	ds_read_b64_tr_b16 v[102:103], v106 offset:0x3400
	ds_read_b64_tr_b16 v[104:105], v106 offset:0x3c00
	ds_read_b64_tr_b16 v[108:109], v106 offset:0x2600
	ds_read_b64_tr_b16 v[110:111], v106 offset:0x2e00
	ds_read_b64_tr_b16 v[112:113], v106 offset:0x3600
	ds_read_b64_tr_b16 v[114:115], v106 offset:0x3e00
	s_nop 7
	s_setprio 2
	v_exp_f32_e32 v97, v64
	v_exp_f32_e32 v65, v65
	v_exp_f32_e32 v106, v66
	v_exp_f32_e32 v67, v67
	v_exp_f32_e32 v68, v68
	v_add_f32_e32 v64, 0, v97
	v_exp_f32_e32 v69, v69
	v_add_f32_e32 v64, v65, v64
	v_exp_f32_e32 v70, v70
	v_add_f32_e32 v64, v106, v64
	v_exp_f32_e32 v71, v71
	v_add_f32_e32 v64, v67, v64
	v_exp_f32_e32 v72, v72
	v_add_f32_e32 v64, v68, v64
	v_exp_f32_e32 v73, v73
	v_add_f32_e32 v64, v69, v64
	v_exp_f32_e32 v74, v74
	v_add_f32_e32 v64, v70, v64
	v_exp_f32_e32 v75, v75
	v_add_f32_e32 v64, v71, v64
	v_exp_f32_e32 v76, v76
	v_add_f32_e32 v64, v72, v64
	v_exp_f32_e32 v77, v77
	v_add_f32_e32 v64, v73, v64
	v_exp_f32_e32 v78, v78
	v_add_f32_e32 v64, v74, v64
	v_exp_f32_e32 v79, v79
	v_add_f32_e32 v64, v75, v64
	v_add_f32_e32 v64, v76, v64
	v_add_f32_e32 v64, v77, v64
	v_add_f32_e32 v64, v78, v64
	v_add_f32_e32 v64, v79, v64
	v_add_f32_e32 v64, v96, v64
	v_cvt_pk_bf16_f32 v66, v97, v65
	v_cvt_pk_bf16_f32 v67, v106, v67
	v_cvt_pk_bf16_f32 v68, v68, v69
	v_cvt_pk_bf16_f32 v69, v70, v71
	v_cvt_pk_bf16_f32 v70, v72, v73
	v_cvt_pk_bf16_f32 v71, v74, v75
	v_cvt_pk_bf16_f32 v72, v76, v77
	v_cvt_pk_bf16_f32 v73, v78, v79
	s_nop 0
	v_permlane32_swap_b32_e32 v66, v68
	v_permlane32_swap_b32_e32 v67, v69
	v_permlane32_swap_b32_e32 v70, v72
	v_permlane32_swap_b32_e32 v71, v73
	s_waitcnt lgkmcnt(0)
	s_setprio 1
	v_mfma_f32_32x32x16_bf16 v[0:15], v[66:69], v[80:83], v[0:15]
	v_mfma_f32_32x32x16_bf16 v[48:63], v[66:69], v[88:91], v[48:63]
	v_mfma_f32_32x32x16_bf16 v[32:47], v[66:69], v[98:101], v[32:47]
	v_mfma_f32_32x32x16_bf16 v[16:31], v[66:69], v[108:111], v[16:31]
	v_mfma_f32_32x32x16_bf16 v[0:15], v[70:73], v[84:87], v[0:15]
	v_mfma_f32_32x32x16_bf16 v[48:63], v[70:73], v[92:95], v[48:63]
	v_mfma_f32_32x32x16_bf16 v[32:47], v[70:73], v[102:105], v[32:47]
	v_mfma_f32_32x32x16_bf16 v[16:31], v[70:73], v[112:115], v[16:31]
	s_setprio 0
	v_mbcnt_lo_u32_b32 v66, -1, 0
	v_mbcnt_hi_u32_b32 v66, -1, v66
	v_mov_b32_e32 v67, v64
	v_and_b32_e32 v65, 31, v66
	v_bfe_u32 v66, v66, 5, 1
	v_permlane32_swap_b32_e32 v64, v67
	v_cmp_eq_u32_e32 vcc, 0, v66
	s_and_saveexec_b64 s[2:3], vcc
	v_lshl_add_u32 v68, v65, 2, s0
	v_add_f32_e32 v64, v64, v67
	ds_write_b32 v68, v64
	s_or_b64 exec, exec, s[2:3]
	s_waitcnt lgkmcnt(0)
	v_lshl_add_u32 v68, v66, 4, s0
	ds_read_b128 v[70:73], v68
	ds_read_b128 v[74:77], v68 offset:32
	s_lshl_b64 s[58:59], s[40:41], 11
	v_readlane_b32 s1, v255, 2
	s_add_u32 s1, s1, s58
	v_readlane_b32 s2, v255, 0
	s_addc_u32 s2, s2, s59
	s_lshl_b32 s3, s87, 2
	s_waitcnt lgkmcnt(0)
	v_rcp_f32_e32 v69, v70
	s_add_u32 s54, s1, s3
	v_lshl_or_b32 v66, v66, 2, s94
	s_addc_u32 s55, s2, 0
	v_lshlrev_b32_e32 v130, 2, v65
	v_ashrrev_i32_e32 v67, 31, v66
	v_lshl_add_u64 v[64:65], s[54:55], 0, v[130:131]
	v_lshlrev_b64 v[78:79], 11, v[66:67]
	v_lshl_add_u64 v[78:79], v[64:65], 0, v[78:79]
	v_mul_f32_e32 v0, v0, v69
	global_store_dword v[78:79], v0, off
	v_mul_f32_e32 v0, v48, v69
	global_store_dword v[78:79], v0, off offset:128
	v_mul_f32_e32 v0, v32, v69
	global_store_dword v[78:79], v0, off offset:256
	v_mul_f32_e32 v0, v16, v69
	global_store_dword v[78:79], v0, off offset:384
	v_rcp_f32_e32 v0, v71
	v_or_b32_e32 v70, 1, v66
	v_ashrrev_i32_e32 v71, 31, v70
	v_lshlrev_b64 v[70:71], 11, v[70:71]
	v_lshl_add_u64 v[70:71], v[64:65], 0, v[70:71]
	v_mul_f32_e32 v1, v1, v0
	global_store_dword v[70:71], v1, off
	v_mul_f32_e32 v1, v49, v0
	global_store_dword v[70:71], v1, off offset:128
	v_mul_f32_e32 v1, v33, v0
	v_mul_f32_e32 v0, v17, v0
	v_rcp_f32_e32 v16, v72
	global_store_dword v[70:71], v0, off offset:384
	v_or_b32_e32 v0, 2, v66
	global_store_dword v[70:71], v1, off offset:256
	v_ashrrev_i32_e32 v1, 31, v0
	v_lshlrev_b64 v[0:1], 11, v[0:1]
	v_lshl_add_u64 v[0:1], v[64:65], 0, v[0:1]
	v_mul_f32_e32 v2, v2, v16
	global_store_dword v[0:1], v2, off
	v_mul_f32_e32 v2, v50, v16
	global_store_dword v[0:1], v2, off offset:128
	v_mul_f32_e32 v2, v34, v16
	global_store_dword v[0:1], v2, off offset:256
	v_mul_f32_e32 v2, v18, v16
	global_store_dword v[0:1], v2, off offset:384
	v_rcp_f32_e32 v2, v73
	v_or_b32_e32 v0, 3, v66
	v_ashrrev_i32_e32 v1, 31, v0
	v_lshlrev_b64 v[0:1], 11, v[0:1]
	v_lshl_add_u64 v[0:1], v[64:65], 0, v[0:1]
	v_mul_f32_e32 v3, v3, v2
	global_store_dword v[0:1], v3, off
	v_mul_f32_e32 v3, v51, v2
	global_store_dword v[0:1], v3, off offset:128
	v_mul_f32_e32 v3, v35, v2
	v_mul_f32_e32 v2, v19, v2
	global_store_dword v[0:1], v2, off offset:384
	v_rcp_f32_e32 v2, v74
	global_store_dword v[0:1], v3, off offset:256
	v_or_b32_e32 v0, 8, v66
	v_ashrrev_i32_e32 v1, 31, v0
	v_lshlrev_b64 v[0:1], 11, v[0:1]
	v_lshl_add_u64 v[0:1], v[64:65], 0, v[0:1]
	v_mul_f32_e32 v3, v4, v2
	global_store_dword v[0:1], v3, off
	v_mul_f32_e32 v3, v52, v2
	global_store_dword v[0:1], v3, off offset:128
; DI unsigned short f2bf(float x) { unsigned u = __float_as_uint(x); u += 0x7fffu + ((u >> 16) & 1u); return (unsigned short)(u >> 16); }
; DI int crow(int r, int hi) { return (r & 3) + 8 * (r >> 2) + 4 * hi; }
; template <int DQK, int MODE, int LDQ, int LDK, int LDV> ...
;     ...
;     for (int r = 0; r < 16; ++r) { const int orow = wid * 32 + crow(r, hi); const float rl = __builtin_amdgcn_rcpf(li_l[crow(r, hi)]);
;         if constexpr (MODE == 0) {
; #pragma unroll
;             for (int d0 = 0; d0 < 4; ++d0) AOb[(size_t)orow * 1024 + d0 * 32 + r32] = f2bf(o[d0][r] * rl);
;         } else if constexpr (MODE == 1) {
; #pragma unroll
;             for (int d0 = 0; d0 < 4; ++d0) S0[(size_t)orow * 512 + d0 * 32 + r32] = o[d0][r] * rl;
	v_mul_f32_e32 v3, v36, v2
	v_mul_f32_e32 v2, v20, v2
	global_store_dword v[0:1], v2, off offset:384
	v_rcp_f32_e32 v2, v75
	global_store_dword v[0:1], v3, off offset:256
	v_or_b32_e32 v0, 9, v66
	v_ashrrev_i32_e32 v1, 31, v0
	v_lshlrev_b64 v[0:1], 11, v[0:1]
	v_lshl_add_u64 v[0:1], v[64:65], 0, v[0:1]
	v_mul_f32_e32 v3, v5, v2
	global_store_dword v[0:1], v3, off
	v_mul_f32_e32 v3, v53, v2
	global_store_dword v[0:1], v3, off offset:128
	v_mul_f32_e32 v3, v37, v2
	v_mul_f32_e32 v2, v21, v2
	global_store_dword v[0:1], v2, off offset:384
	v_rcp_f32_e32 v2, v76
	global_store_dword v[0:1], v3, off offset:256
	v_or_b32_e32 v0, 10, v66
	v_ashrrev_i32_e32 v1, 31, v0
	v_lshlrev_b64 v[0:1], 11, v[0:1]
	v_lshl_add_u64 v[0:1], v[64:65], 0, v[0:1]
	v_mul_f32_e32 v3, v6, v2
	global_store_dword v[0:1], v3, off
	v_mul_f32_e32 v3, v54, v2
	global_store_dword v[0:1], v3, off offset:128
	v_mul_f32_e32 v3, v38, v2
	v_mul_f32_e32 v2, v22, v2
	v_rcp_f32_e32 v6, v77
	global_store_dword v[0:1], v3, off offset:256
	global_store_dword v[0:1], v2, off offset:384
	v_or_b32_e32 v0, 11, v66
	v_ashrrev_i32_e32 v1, 31, v0
	v_lshlrev_b64 v[0:1], 11, v[0:1]
	v_lshl_add_u64 v[4:5], v[64:65], 0, v[0:1]
	v_mul_f32_e32 v0, v7, v6
	global_store_dword v[4:5], v0, off
	v_mul_f32_e32 v0, v55, v6
	global_store_dword v[4:5], v0, off offset:128
	v_mul_f32_e32 v0, v39, v6
	global_store_dword v[4:5], v0, off offset:256
	ds_read_b128 v[0:3], v68 offset:64
	v_mul_f32_e32 v6, v23, v6
	global_store_dword v[4:5], v6, off offset:384
	ds_read_b128 v[4:7], v68 offset:96
	v_or_b32_e32 v16, 16, v66
	s_waitcnt lgkmcnt(0)
	v_rcp_f32_e32 v0, v0
	v_ashrrev_i32_e32 v17, 31, v16
	v_lshlrev_b64 v[16:17], 11, v[16:17]
	v_lshl_add_u64 v[16:17], v[64:65], 0, v[16:17]
	v_mul_f32_e32 v8, v8, v0
	global_store_dword v[16:17], v8, off
	v_mul_f32_e32 v8, v56, v0
	global_store_dword v[16:17], v8, off offset:128
	v_mul_f32_e32 v8, v40, v0
	global_store_dword v[16:17], v8, off offset:256
	v_mul_f32_e32 v0, v24, v0
	v_rcp_f32_e32 v8, v1
	global_store_dword v[16:17], v0, off offset:384
	v_or_b32_e32 v0, 17, v66
	v_ashrrev_i32_e32 v1, 31, v0
	v_lshlrev_b64 v[0:1], 11, v[0:1]
	v_lshl_add_u64 v[0:1], v[64:65], 0, v[0:1]
	v_mul_f32_e32 v9, v9, v8
	global_store_dword v[0:1], v9, off
	v_mul_f32_e32 v9, v57, v8
	global_store_dword v[0:1], v9, off offset:128
	v_mul_f32_e32 v9, v41, v8
	v_mul_f32_e32 v8, v25, v8
	v_rcp_f32_e32 v2, v2
	global_store_dword v[0:1], v9, off offset:256
	global_store_dword v[0:1], v8, off offset:384
	v_or_b32_e32 v0, 18, v66
	v_ashrrev_i32_e32 v1, 31, v0
	v_lshlrev_b64 v[0:1], 11, v[0:1]
	v_lshl_add_u64 v[0:1], v[64:65], 0, v[0:1]
	v_mul_f32_e32 v8, v10, v2
	global_store_dword v[0:1], v8, off
	v_mul_f32_e32 v8, v58, v2
	global_store_dword v[0:1], v8, off offset:128
	v_mul_f32_e32 v8, v42, v2
	v_mul_f32_e32 v2, v26, v2
	global_store_dword v[0:1], v2, off offset:384
	v_rcp_f32_e32 v2, v3
	global_store_dword v[0:1], v8, off offset:256
	v_or_b32_e32 v0, 19, v66
	v_ashrrev_i32_e32 v1, 31, v0
	v_lshlrev_b64 v[0:1], 11, v[0:1]
	v_lshl_add_u64 v[0:1], v[64:65], 0, v[0:1]
	v_mul_f32_e32 v3, v11, v2
	global_store_dword v[0:1], v3, off
	v_mul_f32_e32 v3, v59, v2
	global_store_dword v[0:1], v3, off offset:128
	v_mul_f32_e32 v3, v43, v2
	v_mul_f32_e32 v2, v27, v2
	global_store_dword v[0:1], v2, off offset:384
	v_rcp_f32_e32 v2, v4
	global_store_dword v[0:1], v3, off offset:256
	v_or_b32_e32 v0, 24, v66
	v_ashrrev_i32_e32 v1, 31, v0
	v_lshlrev_b64 v[0:1], 11, v[0:1]
	v_lshl_add_u64 v[0:1], v[64:65], 0, v[0:1]
	v_mul_f32_e32 v3, v12, v2
	global_store_dword v[0:1], v3, off
	v_mul_f32_e32 v3, v60, v2
	global_store_dword v[0:1], v3, off offset:128
	v_mul_f32_e32 v3, v44, v2
	v_mul_f32_e32 v2, v28, v2
	global_store_dword v[0:1], v2, off offset:384
	v_rcp_f32_e32 v2, v5
	global_store_dword v[0:1], v3, off offset:256
	v_or_b32_e32 v0, 25, v66
	v_ashrrev_i32_e32 v1, 31, v0
	v_lshlrev_b64 v[0:1], 11, v[0:1]
	v_lshl_add_u64 v[0:1], v[64:65], 0, v[0:1]
	v_mul_f32_e32 v3, v13, v2
	global_store_dword v[0:1], v3, off
	v_mul_f32_e32 v3, v61, v2
	global_store_dword v[0:1], v3, off offset:128
	v_mul_f32_e32 v3, v45, v2
	v_mul_f32_e32 v2, v29, v2
	global_store_dword v[0:1], v2, off offset:384
	v_rcp_f32_e32 v2, v6
	global_store_dword v[0:1], v3, off offset:256
	v_or_b32_e32 v0, 26, v66
	v_ashrrev_i32_e32 v1, 31, v0
	v_lshlrev_b64 v[0:1], 11, v[0:1]
	v_lshl_add_u64 v[0:1], v[64:65], 0, v[0:1]
	v_mul_f32_e32 v3, v14, v2
	global_store_dword v[0:1], v3, off
	v_mul_f32_e32 v3, v62, v2
	global_store_dword v[0:1], v3, off offset:128
	v_mul_f32_e32 v3, v46, v2
	v_mul_f32_e32 v2, v30, v2
	global_store_dword v[0:1], v2, off offset:384
	v_rcp_f32_e32 v2, v7
	global_store_dword v[0:1], v3, off offset:256
	v_or_b32_e32 v0, 27, v66
	v_ashrrev_i32_e32 v1, 31, v0
	v_lshlrev_b64 v[0:1], 11, v[0:1]
	v_lshl_add_u64 v[0:1], v[64:65], 0, v[0:1]
	v_mul_f32_e32 v3, v15, v2
	global_store_dword v[0:1], v3, off
	v_mul_f32_e32 v3, v63, v2
	global_store_dword v[0:1], v3, off offset:128
	v_mul_f32_e32 v3, v47, v2
	v_mul_f32_e32 v2, v31, v2
	global_store_dword v[0:1], v3, off offset:256
	global_store_dword v[0:1], v2, off offset:384
	s_waitcnt vmcnt(0)
	s_barrier
; DI float bf2f(unsigned short h) { return __uint_as_float((unsigned)h << 16); }
; template <int DQK, int MODE, int LDQ, int LDK, int LDV> ...
;     ...
;     int kgo[NKP], vgo[2];
; #pragma unroll
;     for (int i = 0; i < NKP; ++i) { const int L = (wid + 8 * i) * 64 + lane, row = L / CPR, slot = L % CPR, cc = (slot & ~7) | ((slot & 7) ^ ((row >> 1) & 7)); kgo[i] = row * LDK + cc * 8; }
; #pragma unroll
;     for (int i = 0; i < 2; ++i) { const int L = (2 * wid + i) * 64 + lane, st = L >> 5, w5 = L & 31, kk = (st >> 2) * 8 + (w5 >> 2), c = (st & 3) * 32 + (w5 & 3) * 8;
;         const int k = (kk & ~0xC) | ((kk & 4) << 1) | ((kk & 8) >> 1); vgo[i] = k * LDV + c; }
;     ...
;     ATT_DMA_K(0); ATT_DMA_K(1); ATT_DMA_V(0, 0); ATT_DMA_K(2); ATT_DMA_V(1, 1);
;     bf16x8 qr[ND0];
;     { const bf16_t* Qw = Qb + (size_t)(wid * 32 + r32) * LDQ + hi * 8;
; #pragma unroll
;       for (int d0 = 0; d0 < ND0; ++d0) qr[d0] = *(const bf16x8*)(Qw + d0 * 16);
;       if constexpr (MODE == 0) {
;           float ss = 0.f;
; #pragma unroll
;           for (int d0 = 0; d0 < ND0; ++d0)
; #pragma unroll
;               for (int j = 0; j < 8; ++j) { const float f = bf2f((unsigned short)qr[d0][j]); ss += f * f; }
;           ss = swap_sum(ss);
;           const float rstd = rsqrtf(ss * (1.f / DQK) + EPS) * C;
; #pragma unroll
;           for (int d0 = 0; d0 < ND0; ++d0) { const float* g = gq + d0 * 16 + hi * 8;
;               { float f[8]; _Pragma("unroll") for (int j = 0; j < 8; ++j) f[j] = bf2f((unsigned short)qr[d0][j]) * rstd * g[j];
;                 u32x4 w = {cvtpk(f[0], f[1]), cvtpk(f[2], f[3]), cvtpk(f[4], f[5]), cvtpk(f[6], f[7])}; qr[d0] = __builtin_bit_cast(bf16x8, w); asm volatile("" ::: "memory"); } }
;       } }
;     const int qlo = q0 + wid * 32, qpos = qlo + r32;
;     const int tL = MODE == 0 ? 0 : (qlo >= 191 ? (qlo - 127) >> 6 : 0), tR = MODE == 0 ? NT : min(NT, (qlo + 222) >> 6);
;     float fL = 1.f, fR = 1.f; if constexpr (MODE != 0) { fL = __builtin_amdgcn_exp2f(bt[0]); fR = __builtin_amdgcn_exp2f(-bt[448]); }
;     ...
;     const int vbase = (int)(unsigned)(size_t)lds + V_OFF + v_rd_base(lane);
;     ...
;     constexpr int NDA = ND0 > 6 ? 6 : ND0;
;     ...
;     f32x16 pA, pB; bf16x8 pa0, pa1;
;     int v0 = 0, v1 = 1, v2 = 2;
;     ATT_TOP(NKP + 2);
;     { bf16x8 kf[NDA]; k_reads<DQK, 0, NDA>(kf, lds, 0, r32, hi); ATT_LGKM0(); qk_mma<0, NDA>(pA, kf, qr);
	v_mbcnt_lo_u32_b32 v7, -1, 0
	v_mbcnt_hi_u32_b32 v7, -1, v7
	s_mov_b64 s[4:5], 0x880
	v_add_u32_e32 v0, s33, v7
	v_bfe_u32 v4, v0, 2, 2
	v_readfirstlane_b32 s0, v0
	s_ashr_i32 s2, s0, 31
	s_ashr_i32 s1, s0, 6
	v_mov_b32_e32 v1, s0
	v_bfi_b32 v1, s63, v1, v7
	s_lshr_b32 s2, s2, 29
	v_add_u32_e32 v3, s2, v1
	s_lshl_b32 s2, s1, 7
	v_ashrrev_i32_e32 v9, 3, v3
	v_and_b32_e32 v3, 0x1ffffff8, v3
	s_ashr_i32 s3, s2, 4
	v_lshrrev_b32_e32 v0, 1, v0
	v_sub_u32_e32 v1, v1, v3
	v_lshrrev_b32_e32 v3, 1, v9
	v_lshlrev_b32_e32 v18, 3, v7
	s_and_b32 s2, s3, -16
	v_and_b32_e32 v6, 8, v0
	s_lshr_b32 s3, s3, 1
	v_bitop3_b32 v1, v3, v1, 7 bitop3:0x6c
	v_and_b32_e32 v3, 32, v7
	v_and_b32_e32 v5, 24, v18
	s_and_b32 s3, s3, 4
	v_or3_b32 v0, v6, v4, s2
	v_or_b32_e32 v10, v3, v5
	v_or_b32_e32 v0, s3, v0
	v_lshl_or_b32 v96, v0, 11, v10
	v_lshlrev_b32_e32 v0, 11, v9
	v_lshl_add_u32 v0, v1, 3, v0
	v_ashrrev_i32_e32 v1, 31, v0
	v_lshlrev_b64 v[10:11], 1, v[0:1]
	v_lshl_add_u64 v[12:13], s[46:47], 0, v[10:11]
	v_lshl_add_u64 v[12:13], v[12:13], 0, s[4:5]
	s_lshl_b32 s4, s1, 10
	s_add_i32 s94, s4, 0
	s_mov_b32 m0, s94
	v_lshl_add_u64 v[10:11], s[48:49], 0, v[10:11]
	s_mov_b64 s[4:5], 0x40080
	global_load_lds_dwordx4 v[12:13], off
	v_lshl_add_u64 v[12:13], v[10:11], 0, s[4:5]
	s_add_i32 m0, s94, 0x2000
	s_lshl_b32 s4, s1, 11
	v_ashrrev_i32_e32 v97, 31, v96
	global_load_lds_dwordx4 v[12:13], off
	s_add_i32 s6, s4, 0
	v_lshlrev_b64 v[12:13], 1, v[96:97]
	s_add_i32 s48, s6, 0x18000
	v_lshl_add_u64 v[14:15], s[46:47], 0, v[12:13]
	v_lshl_add_u64 v[16:17], v[14:15], 0, s[96:97]
	s_mov_b32 m0, s48
	s_mov_b64 s[4:5], 0xc80
	global_load_lds_dwordx4 v[16:17], off
	v_lshl_add_u64 v[14:15], v[14:15], 0, s[4:5]
	s_add_i32 m0, s6, 0x18400
	s_mov_b64 s[4:5], 0x80080
	v_or_b32_e32 v98, 64, v96
	global_load_lds_dwordx4 v[14:15], off
	v_lshl_add_u64 v[10:11], v[10:11], 0, s[4:5]
	s_add_i32 m0, s94, 0x4000
	v_ashrrev_i32_e32 v99, 31, v98
	global_load_lds_dwordx4 v[10:11], off
	s_add_i32 m0, s6, 0x1c000
	v_lshl_add_u64 v[10:11], s[52:53], 0, v[12:13]
	v_and_b32_e32 v2, 31, v7
	global_load_lds_dwordx4 v[10:11], off
	v_lshl_add_u64 v[10:11], v[98:99], 1, s[52:53]
	s_add_i32 m0, s6, 0x1c400
	s_lshl_b32 s46, s1, 5
	global_load_lds_dwordx4 v[10:11], off
	v_or_b32_e32 v10, s46, v2
	v_ashrrev_i32_e32 v11, 31, v10
	v_bfe_u32 v8, v7, 5, 1
	v_lshlrev_b64 v[10:11], 12, v[10:11]
	v_lshl_add_u64 v[10:11], s[44:45], 0, v[10:11]
	v_lshlrev_b32_e32 v130, 4, v8
	v_lshl_add_u64 v[10:11], v[10:11], 0, v[130:131]
	global_load_dwordx4 v[92:95], v[10:11], off offset:1152
	global_load_dwordx4 v[88:91], v[10:11], off offset:1184
	global_load_dwordx4 v[84:87], v[10:11], off offset:1216
	global_load_dwordx4 v[80:83], v[10:11], off offset:1248
	v_and_b32_e32 v11, 0x70, v18
	v_mov_b32_e32 v9, s88
	v_mov_b32_e32 v10, s81
	v_lshl_add_u32 v114, v2, 7, 0
	v_bitop3_b32 v115, v130, v18, s64 bitop3:0x78
	v_bitop3_b32 v117, v130, v11, 64 bitop3:0x36
	s_add_i32 s4, s46, s89
	ds_read_b32 v9, v9
	ds_read_b32 v10, v10
	s_waitcnt vmcnt(3)
	s_barrier
	v_add_u32_e32 v107, v114, v115
	v_bitop3_b32 v116, v130, v11, 32 bitop3:0x36
	v_add_u32_e32 v109, v114, v117
	v_bitop3_b32 v118, v130, v11, s65 bitop3:0x36
	s_add_i32 s5, s4, 0xffffff81
	v_add_u32_e32 v108, v114, v116
	ds_read_b128 v[12:15], v107
	ds_read_b128 v[16:19], v108
	v_add_u32_e32 v110, v114, v118
	ds_read_b128 v[20:23], v109
	ds_read_b128 v[24:27], v110
	s_ashr_i32 s5, s5, 6
	s_cmpk_gt_i32 s4, 0xbe
	v_or_b32_e32 v111, s4, v2
	s_cselect_b32 s47, s5, 0
	s_addk_i32 s4, 0xde
	s_ashr_i32 s45, s4, 6
	s_waitcnt lgkmcnt(0)
	s_waitcnt vmcnt(0) lgkmcnt(0)
	v_mfma_f32_32x32x16_bf16 v[64:79], v[12:15], v[92:95], 0
	s_cmp_gt_i32 s47, 0
	s_cselect_b64 s[4:5], -1, 0
	s_cmp_lt_i32 s45, 1
	s_cselect_b64 s[6:7], -1, 0
	s_or_b64 s[4:5], s[6:7], s[4:5]
	s_and_b64 vcc, exec, s[4:5]
	v_mfma_f32_32x32x16_bf16 v[64:79], v[16:19], v[88:91], v[64:79]
	v_mfma_f32_32x32x16_bf16 v[64:79], v[20:23], v[84:87], v[64:79]
	v_mfma_f32_32x32x16_bf16 v[64:79], v[24:27], v[80:83], v[64:79]
	s_cbranch_vccnz .LBB0_1948
	v_lshlrev_b32_e32 v8, 2, v8
	v_sub_u32_e32 v8, v8, v111
	v_lshl_add_u32 v8, v8, 2, s88
	ds_read2_b32 v[12:13], v8 offset0:240 offset1:241
	ds_read2_b32 v[14:15], v8 offset0:242 offset1:243
	ds_read2_b32 v[16:17], v8 offset0:248 offset1:249
	ds_read2_b32 v[18:19], v8 offset0:250 offset1:251
	ds_read2_b32 v[20:21], v8 offset0:224 offset1:225
	ds_read2_b32 v[22:23], v8 offset0:226 offset1:227
	ds_read2_b32 v[24:25], v8 offset0:232 offset1:233
	ds_read2_b32 v[26:27], v8 offset0:234 offset1:235
	s_waitcnt lgkmcnt(4)
	v_pk_add_f32 v[78:79], v[78:79], v[18:19]
	v_pk_add_f32 v[76:77], v[76:77], v[16:17]
	v_pk_add_f32 v[74:75], v[74:75], v[14:15]
	v_pk_add_f32 v[72:73], v[72:73], v[12:13]
	s_waitcnt lgkmcnt(0)
	v_pk_add_f32 v[70:71], v[70:71], v[26:27]
	v_pk_add_f32 v[68:69], v[68:69], v[24:25]
	v_pk_add_f32 v[66:67], v[66:67], v[22:23]
	v_pk_add_f32 v[64:65], v[64:65], v[20:21]

; #define SBAR() __builtin_amdgcn_sched_barrier(0)
; #define ATT_DMA_K(t) do { const bf16_t* kg_ = Kh + (size_t)(t) * 64 * LDK; LAS unsigned char* sb_ = lds + ((t) & 3) * KBUF; \
;     _Pragma("unroll") for (int i_ = 0; i_ < NKP; ++i_) __builtin_amdgcn_global_load_lds((const unsigned*)(kg_ + kgo[i_]), (LAS unsigned*)(sb_ + (wid + 8 * i_) * 1024), 16, 0, 0); } while (0)
; #define ATT_DMA_V(t, vs) do { const bf16_t* vg_ = Vh + (size_t)(t) * 64 * LDV; LAS unsigned char* sb_ = lds + V_OFF + (vs) * SHM_V; \
;     _Pragma("unroll") for (int i_ = 0; i_ < 2; ++i_) __builtin_amdgcn_global_load_lds((const unsigned*)(vg_ + vgo[i_]), (LAS unsigned*)(sb_ + (2 * wid + i_) * 1024), 16, 0, 0); } while (0)
; #define ATT_SEG(t) do { if constexpr (MODE != 0) { if (((t) == tL && tL > 0) || (t) == tR) { const float f_ = (t) == tR ? fR : fL; l_reg *= f_; \
;     _Pragma("unroll") for (int d = 0; d < 4; ++d) _Pragma("unroll") for (int r = 0; r < 16; ++r) o[d][r] *= f_; } } } while (0)
; #define ATT_TOP(N) do { asm volatile("s_waitcnt vmcnt(%0)" :: "n"(N) : "memory"); __builtin_amdgcn_s_barrier(); asm volatile("" ::: "memory"); } while (0)
; template <int DQK, int MODE, int LDQ, int LDK, int LDV> ...
;     ...
;     for (int j = 0; j < NT; ++j) {
;         if (j + 2 < NT) ATT_TOP(NKP + 2); else ATT_TOP(0);
;         if (j + 3 < NT) ATT_DMA_K(j + 3);
;         if (j + 2 < NT) ATT_DMA_V(j + 2, v2);
;         ATT_SEG(j); SBAR();
.Lstg_d1_top_18:
	s_setprio 0
	s_add_i32 s2, s48, s2
	global_load_lds_dwordx4 v[100:101], off
	s_add_i32 s3, s2, 0x400
	s_mov_b32 m0, s2
	s_add_i32 s2, s53, s0
	global_load_lds_dwordx4 v[102:103], off
	s_mov_b32 m0, s3
	s_add_i32 s23, s6, s0
	global_load_lds_dwordx4 v[104:105], off
	s_cmp_eq_u32 s2, 1
	s_cselect_b64 s[2:3], -1, 0
	s_and_b64 s[74:75], s[4:5], s[2:3]
	s_cmp_eq_u32 s23, 1
	s_cselect_b64 s[2:3], -1, 0
	s_or_b64 s[74:75], s[2:3], s[74:75]
	s_andn2_b64 vcc, exec, s[74:75]
	s_mov_b32 s23, s62
	s_cbranch_vccnz .LBB0_1953
	v_cndmask_b32_e64 v122, v112, v113, s[2:3]
	v_pk_mul_f32 v[14:15], v[14:15], v[122:123] op_sel_hi:[1,0]
	v_pk_mul_f32 v[12:13], v[12:13], v[122:123] op_sel_hi:[1,0]
	v_pk_mul_f32 v[10:11], v[10:11], v[122:123] op_sel_hi:[1,0]
	v_pk_mul_f32 v[8:9], v[8:9], v[122:123] op_sel_hi:[1,0]
	v_pk_mul_f32 v[6:7], v[6:7], v[122:123] op_sel_hi:[1,0]
	v_pk_mul_f32 v[4:5], v[4:5], v[122:123] op_sel_hi:[1,0]
	v_pk_mul_f32 v[2:3], v[2:3], v[122:123] op_sel_hi:[1,0]
	v_pk_mul_f32 v[0:1], v[0:1], v[122:123] op_sel_hi:[1,0]
	v_pk_mul_f32 v[62:63], v[62:63], v[122:123] op_sel_hi:[1,0]
	v_pk_mul_f32 v[60:61], v[60:61], v[122:123] op_sel_hi:[1,0]
	v_pk_mul_f32 v[58:59], v[58:59], v[122:123] op_sel_hi:[1,0]
	v_pk_mul_f32 v[56:57], v[56:57], v[122:123] op_sel_hi:[1,0]
	v_pk_mul_f32 v[54:55], v[54:55], v[122:123] op_sel_hi:[1,0]
	v_pk_mul_f32 v[52:53], v[52:53], v[122:123] op_sel_hi:[1,0]
	v_pk_mul_f32 v[50:51], v[50:51], v[122:123] op_sel_hi:[1,0]
	v_pk_mul_f32 v[48:49], v[48:49], v[122:123] op_sel_hi:[1,0]
	v_pk_mul_f32 v[30:31], v[30:31], v[122:123] op_sel_hi:[1,0]
	v_pk_mul_f32 v[28:29], v[28:29], v[122:123] op_sel_hi:[1,0]
	v_pk_mul_f32 v[26:27], v[26:27], v[122:123] op_sel_hi:[1,0]
	v_pk_mul_f32 v[24:25], v[24:25], v[122:123] op_sel_hi:[1,0]
	v_pk_mul_f32 v[22:23], v[22:23], v[122:123] op_sel_hi:[1,0]
	v_pk_mul_f32 v[20:21], v[20:21], v[122:123] op_sel_hi:[1,0]
	v_pk_mul_f32 v[18:19], v[18:19], v[122:123] op_sel_hi:[1,0]
	v_pk_mul_f32 v[16:17], v[16:17], v[122:123] op_sel_hi:[1,0]
	v_pk_mul_f32 v[46:47], v[46:47], v[122:123] op_sel_hi:[1,0]
	v_pk_mul_f32 v[44:45], v[44:45], v[122:123] op_sel_hi:[1,0]
	v_pk_mul_f32 v[42:43], v[42:43], v[122:123] op_sel_hi:[1,0]
	v_pk_mul_f32 v[40:41], v[40:41], v[122:123] op_sel_hi:[1,0]
	v_pk_mul_f32 v[38:39], v[38:39], v[122:123] op_sel_hi:[1,0]
	v_pk_mul_f32 v[36:37], v[36:37], v[122:123] op_sel_hi:[1,0]
	v_pk_mul_f32 v[34:35], v[34:35], v[122:123] op_sel_hi:[1,0]
	v_pk_mul_f32 v[32:33], v[32:33], v[122:123] op_sel_hi:[1,0]
	v_mul_f32_e32 v120, v120, v122
.LBB0_1953:
	s_add_i32 s3, s0, -1
	s_add_i32 s2, s22, 0xffffa000
	s_and_b32 s2, s2, 0x6000
	v_add_u32_e32 v121, s2, v114
	v_add_u32_e32 v122, v121, v115
	v_add_u32_e32 v126, v121, v116
	ds_read_b128 v[122:125], v122 offset:4096
	ds_read_b128 v[132:135], v126 offset:4096
	v_add_u32_e32 v126, v121, v117
	v_add_u32_e32 v121, v121, v118
	s_lshl_b32 s2, s23, 14
	ds_read_b128 v[136:139], v126 offset:4096
	ds_read_b128 v[140:143], v121 offset:4096
	v_add_u32_e32 v121, s2, v106
	ds_read_b64_tr_b16 v[144:145], v121 offset:0
	ds_read_b64_tr_b16 v[146:147], v121 offset:0x800
	ds_read_b64_tr_b16 v[148:149], v121 offset:0x1000
	ds_read_b64_tr_b16 v[150:151], v121 offset:0x1800
	ds_read_b64_tr_b16 v[152:153], v121 offset:0x200
	ds_read_b64_tr_b16 v[154:155], v121 offset:0xa00
	ds_read_b64_tr_b16 v[156:157], v121 offset:0x1200
	ds_read_b64_tr_b16 v[158:159], v121 offset:0x1a00
	ds_read_b64_tr_b16 v[162:163], v121 offset:0x400
	ds_read_b64_tr_b16 v[164:165], v121 offset:0xc00
	ds_read_b64_tr_b16 v[166:167], v121 offset:0x1400
	ds_read_b64_tr_b16 v[168:169], v121 offset:0x1c00
	ds_read_b64_tr_b16 v[170:171], v121 offset:0x600
	ds_read_b64_tr_b16 v[172:173], v121 offset:0xe00
	ds_read_b64_tr_b16 v[174:175], v121 offset:0x1600
	ds_read_b64_tr_b16 v[176:177], v121 offset:0x1e00
	s_setprio 2
	v_exp_f32_e32 v64, v64
	v_exp_f32_e32 v65, v65
	v_exp_f32_e32 v66, v66
	v_exp_f32_e32 v67, v67
	v_exp_f32_e32 v68, v68
	v_add_f32_e32 v126, 0, v64
	v_exp_f32_e32 v69, v69
	v_add_f32_e32 v126, v65, v126
	v_exp_f32_e32 v70, v70
	v_add_f32_e32 v126, v66, v126
	v_exp_f32_e32 v71, v71
	v_add_f32_e32 v126, v67, v126
	v_exp_f32_e32 v72, v72
	v_add_f32_e32 v126, v68, v126
	v_exp_f32_e32 v73, v73
	v_add_f32_e32 v126, v69, v126
	v_exp_f32_e32 v74, v74
	v_add_f32_e32 v126, v70, v126
	v_exp_f32_e32 v75, v75
	v_add_f32_e32 v126, v71, v126
	v_exp_f32_e32 v76, v76
	v_add_f32_e32 v126, v72, v126
	v_exp_f32_e32 v77, v77
	v_add_f32_e32 v126, v73, v126
	v_exp_f32_e32 v78, v78
	v_add_f32_e32 v126, v74, v126
	v_exp_f32_e32 v79, v79
	v_add_f32_e32 v126, v75, v126
	v_add_f32_e32 v126, v76, v126
	v_add_f32_e32 v126, v77, v126
	v_add_f32_e32 v126, v78, v126
	v_add_f32_e32 v126, v79, v126
	v_add_f32_e32 v120, v126, v120
	v_cvt_pk_bf16_f32 v64, v64, v65
	v_cvt_pk_bf16_f32 v65, v66, v67
	v_cvt_pk_bf16_f32 v66, v68, v69
	v_cvt_pk_bf16_f32 v67, v70, v71
	v_cvt_pk_bf16_f32 v68, v72, v73
	v_cvt_pk_bf16_f32 v69, v74, v75
	v_cvt_pk_bf16_f32 v70, v76, v77
	v_cvt_pk_bf16_f32 v71, v78, v79
	s_nop 0
	v_permlane32_swap_b32_e32 v64, v66
	v_permlane32_swap_b32_e32 v65, v67
	v_permlane32_swap_b32_e32 v68, v70
	v_permlane32_swap_b32_e32 v69, v71
	s_waitcnt lgkmcnt(0)
	s_setprio 1
	v_mfma_f32_32x32x16_bf16 v[0:15], v[64:67], v[144:147], v[0:15]
	s_cmp_lt_i32 s3, s47
	s_cselect_b64 s[74:75], -1, 0
	s_cmp_ge_i32 s3, s52
	s_cselect_b64 s[90:91], -1, 0
	s_or_b64 s[74:75], s[74:75], s[90:91]
	s_and_b64 vcc, exec, s[74:75]
	v_mfma_f32_32x32x16_bf16 v[48:63], v[64:67], v[152:155], v[48:63]
	v_mfma_f32_32x32x16_bf16 v[16:31], v[64:67], v[162:165], v[16:31]
	v_mfma_f32_32x32x16_bf16 v[32:47], v[64:67], v[170:173], v[32:47]
	v_mfma_f32_32x32x16_bf16 v[0:15], v[68:71], v[148:151], v[0:15]
	v_mfma_f32_32x32x16_bf16 v[48:63], v[68:71], v[156:159], v[48:63]
	v_mfma_f32_32x32x16_bf16 v[16:31], v[68:71], v[166:169], v[16:31]
	v_mfma_f32_32x32x16_bf16 v[32:47], v[68:71], v[174:177], v[32:47]
	v_mfma_f32_32x32x16_bf16 v[64:79], v[122:125], v[92:95], 0
	v_mfma_f32_32x32x16_bf16 v[64:79], v[132:135], v[88:91], v[64:79]
	v_mfma_f32_32x32x16_bf16 v[64:79], v[136:139], v[84:87], v[64:79]
	v_mfma_f32_32x32x16_bf16 v[64:79], v[140:143], v[80:83], v[64:79]
	s_setprio 0
	v_add_u32_e32 v122, s7, v119
	s_cbranch_vccnz .LBB0_1955
	v_add_u32_e32 v138, 0x28908, v122
	v_add_u32_e32 v140, 0x28920, v122
	v_add_u32_e32 v142, 0x28928, v122
	v_add_u32_e32 v124, 0x28940, v122
	v_add_u32_e32 v126, 0x28948, v122
	v_add_u32_e32 v132, 0x28960, v122
	v_add_u32_e32 v134, 0x28968, v122
	v_add_u32_e32 v123, 0x28900, v122
	ds_read2_b32 v[124:125], v124 offset1:1
	ds_read2_b32 v[126:127], v126 offset1:1
	ds_read2_b32 v[132:133], v132 offset1:1
	ds_read2_b32 v[134:135], v134 offset1:1
	ds_read2_b32 v[136:137], v123 offset1:1
	ds_read2_b32 v[138:139], v138 offset1:1
	ds_read2_b32 v[140:141], v140 offset1:1
	ds_read2_b32 v[142:143], v142 offset1:1
	s_waitcnt lgkmcnt(0)
	v_pk_add_f32 v[78:79], v[78:79], v[134:135]
	v_pk_add_f32 v[76:77], v[76:77], v[132:133]
	v_pk_add_f32 v[74:75], v[74:75], v[126:127]
	v_pk_add_f32 v[72:73], v[72:73], v[124:125]
	v_pk_add_f32 v[70:71], v[70:71], v[142:143]
	v_pk_add_f32 v[68:69], v[68:69], v[140:141]
	v_pk_add_f32 v[66:67], v[66:67], v[138:139]
	v_pk_add_f32 v[64:65], v[64:65], v[136:137]

.Lstg_d1_t61_20:
	s_setprio 0
	s_add_i32 s1, s0, 0x400
	v_lshl_add_u64 v[96:97], v[96:97], 1, s[56:57]
	s_mov_b32 m0, s0
	v_lshl_add_u64 v[98:99], v[98:99], 1, s[56:57]
	global_load_lds_dwordx4 v[96:97], off
	s_mov_b32 m0, s1
	s_cmp_lg_u32 s47, 61
	global_load_lds_dwordx4 v[98:99], off
	s_cselect_b64 s[0:1], -1, 0
	s_cmp_eq_u32 s45, 61
	s_cselect_b64 s[2:3], -1, 0
	s_cmp_lg_u32 s45, 61
	s_cselect_b64 s[4:5], -1, 0
	s_and_b64 s[0:1], s[4:5], s[0:1]
	s_and_b64 vcc, exec, s[0:1]
	s_cbranch_vccnz .LBB0_1961
	v_cndmask_b32_e64 v96, v112, v113, s[2:3]
	v_pk_mul_f32 v[14:15], v[14:15], v[96:97] op_sel_hi:[1,0]
	v_pk_mul_f32 v[12:13], v[12:13], v[96:97] op_sel_hi:[1,0]
	v_pk_mul_f32 v[10:11], v[10:11], v[96:97] op_sel_hi:[1,0]
	v_pk_mul_f32 v[8:9], v[8:9], v[96:97] op_sel_hi:[1,0]
	v_pk_mul_f32 v[6:7], v[6:7], v[96:97] op_sel_hi:[1,0]
	v_pk_mul_f32 v[4:5], v[4:5], v[96:97] op_sel_hi:[1,0]
	v_pk_mul_f32 v[2:3], v[2:3], v[96:97] op_sel_hi:[1,0]
	v_pk_mul_f32 v[0:1], v[0:1], v[96:97] op_sel_hi:[1,0]
	v_pk_mul_f32 v[62:63], v[62:63], v[96:97] op_sel_hi:[1,0]
	v_pk_mul_f32 v[60:61], v[60:61], v[96:97] op_sel_hi:[1,0]
	v_pk_mul_f32 v[58:59], v[58:59], v[96:97] op_sel_hi:[1,0]
	v_pk_mul_f32 v[56:57], v[56:57], v[96:97] op_sel_hi:[1,0]
	v_pk_mul_f32 v[54:55], v[54:55], v[96:97] op_sel_hi:[1,0]
	v_pk_mul_f32 v[52:53], v[52:53], v[96:97] op_sel_hi:[1,0]
	v_pk_mul_f32 v[50:51], v[50:51], v[96:97] op_sel_hi:[1,0]
	v_pk_mul_f32 v[48:49], v[48:49], v[96:97] op_sel_hi:[1,0]
	v_pk_mul_f32 v[30:31], v[30:31], v[96:97] op_sel_hi:[1,0]
	v_pk_mul_f32 v[28:29], v[28:29], v[96:97] op_sel_hi:[1,0]
	v_pk_mul_f32 v[26:27], v[26:27], v[96:97] op_sel_hi:[1,0]
	v_pk_mul_f32 v[24:25], v[24:25], v[96:97] op_sel_hi:[1,0]
	v_pk_mul_f32 v[22:23], v[22:23], v[96:97] op_sel_hi:[1,0]
	v_pk_mul_f32 v[20:21], v[20:21], v[96:97] op_sel_hi:[1,0]
	v_pk_mul_f32 v[18:19], v[18:19], v[96:97] op_sel_hi:[1,0]
	v_pk_mul_f32 v[16:17], v[16:17], v[96:97] op_sel_hi:[1,0]
	v_pk_mul_f32 v[46:47], v[46:47], v[96:97] op_sel_hi:[1,0]
	v_pk_mul_f32 v[44:45], v[44:45], v[96:97] op_sel_hi:[1,0]
	v_pk_mul_f32 v[42:43], v[42:43], v[96:97] op_sel_hi:[1,0]
	v_pk_mul_f32 v[40:41], v[40:41], v[96:97] op_sel_hi:[1,0]
	v_pk_mul_f32 v[38:39], v[38:39], v[96:97] op_sel_hi:[1,0]
	v_pk_mul_f32 v[36:37], v[36:37], v[96:97] op_sel_hi:[1,0]
	v_pk_mul_f32 v[34:35], v[34:35], v[96:97] op_sel_hi:[1,0]
	v_pk_mul_f32 v[32:33], v[32:33], v[96:97] op_sel_hi:[1,0]
	v_mul_f32_e32 v120, v120, v96
; #define SBAR() __builtin_amdgcn_sched_barrier(0)
; #define ATT_DMA_K(t) do { const bf16_t* kg_ = Kh + (size_t)(t) * 64 * LDK; LAS unsigned char* sb_ = lds + ((t) & 3) * KBUF; \
;     _Pragma("unroll") for (int i_ = 0; i_ < NKP; ++i_) __builtin_amdgcn_global_load_lds((const unsigned*)(kg_ + kgo[i_]), (LAS unsigned*)(sb_ + (wid + 8 * i_) * 1024), 16, 0, 0); } while (0)
; #define ATT_DMA_V(t, vs) do { const bf16_t* vg_ = Vh + (size_t)(t) * 64 * LDV; LAS unsigned char* sb_ = lds + V_OFF + (vs) * SHM_V; \
;     _Pragma("unroll") for (int i_ = 0; i_ < 2; ++i_) __builtin_amdgcn_global_load_lds((const unsigned*)(vg_ + vgo[i_]), (LAS unsigned*)(sb_ + (2 * wid + i_) * 1024), 16, 0, 0); } while (0)
; #define ATT_SEG(t) do { if constexpr (MODE != 0) { if (((t) == tL && tL > 0) || (t) == tR) { const float f_ = (t) == tR ? fR : fL; l_reg *= f_; \
;     _Pragma("unroll") for (int d = 0; d < 4; ++d) _Pragma("unroll") for (int r = 0; r < 16; ++r) o[d][r] *= f_; } } } while (0)
; #define ATT_BIAS(P, t, half) do { if constexpr (MODE != 0) { if ((t) >= tL && (t) < tR) { const LAS float* bp_ = bt + ((t) * 64 + (half) * 32 - qpos + 224 + 4 * hi);     \
;     _Pragma("unroll") for (int r = 0; r < 16; ++r) P[r] += bp_[(r & 3) + 8 * (r >> 2)]; } } } while (0)
; #define ATT_TOP(N) do { asm volatile("s_waitcnt vmcnt(%0)" :: "n"(N) : "memory"); __builtin_amdgcn_s_barrier(); asm volatile("" ::: "memory"); } while (0)
; #define ATT_LGKM0() do { SBAR(); asm volatile("s_waitcnt lgkmcnt(0)" ::: "memory"); SBAR(); } while (0)
; template <int DQK, int MODE, int LDQ, int LDK, int LDV> ...
;     ...
;     f32x16 pA, pB; bf16x8 pa0, pa1;
;     int v0 = 0, v1 = 1, v2 = 2;
;     ATT_TOP(NKP + 2);
;     { bf16x8 kf[NDA]; k_reads<DQK, 0, NDA>(kf, lds, 0, r32, hi); ATT_LGKM0(); qk_mma<0, NDA>(pA, kf, qr);
;       if constexpr (ND0 > NDA) { bf16x8 kg[ND0 - NDA]; k_reads<DQK, NDA, ND0>(kg, lds, 0, r32, hi); ATT_LGKM0(); qk_mma<NDA, ND0>(pA, kg, qr); }
;       ATT_BIAS(pA, 0, 0); }
;     if (wid >= 4) __builtin_amdgcn_s_setprio(1);
;     for (int j = 0; j < NT; ++j) {
;         if (j + 2 < NT) ATT_TOP(NKP + 2); else ATT_TOP(0);
;         if (j + 3 < NT) ATT_DMA_K(j + 3);
;         if (j + 2 < NT) ATT_DMA_V(j + 2, v2);
;         ATT_SEG(j); SBAR();
;         ATT_STEP(pA, pB, 0, v0, true, 1, j);
;         ATT_STEP(pB, pA, 1, v0, (j + 1 < NT), 0, j + 1);
.LBB0_1961:
	ds_read_b128 v[98:101], v107 offset:12288
	ds_read_b128 v[102:105], v108 offset:12288
	ds_read_b128 v[114:117], v109 offset:12288
	ds_read_b128 v[122:125], v110 offset:12288
	v_lshl_add_u32 v96, s49, 14, v106
	ds_read_b64_tr_b16 v[132:133], v96 offset:0
	ds_read_b64_tr_b16 v[134:135], v96 offset:0x800
	ds_read_b64_tr_b16 v[136:137], v96 offset:0x1000
	ds_read_b64_tr_b16 v[138:139], v96 offset:0x1800
	ds_read_b64_tr_b16 v[140:141], v96 offset:0x200
	ds_read_b64_tr_b16 v[142:143], v96 offset:0xa00
	ds_read_b64_tr_b16 v[144:145], v96 offset:0x1200
	ds_read_b64_tr_b16 v[146:147], v96 offset:0x1a00
	ds_read_b64_tr_b16 v[148:149], v96 offset:0x400
	ds_read_b64_tr_b16 v[150:151], v96 offset:0xc00
	ds_read_b64_tr_b16 v[152:153], v96 offset:0x1400
	ds_read_b64_tr_b16 v[154:155], v96 offset:0x1c00
	ds_read_b64_tr_b16 v[156:157], v96 offset:0x600
	ds_read_b64_tr_b16 v[158:159], v96 offset:0xe00
	ds_read_b64_tr_b16 v[162:163], v96 offset:0x1600
	ds_read_b64_tr_b16 v[164:165], v96 offset:0x1e00
	s_setprio 2
	v_exp_f32_e32 v64, v64
	v_exp_f32_e32 v65, v65
	v_exp_f32_e32 v66, v66
	v_exp_f32_e32 v67, v67
	v_exp_f32_e32 v68, v68
	v_add_f32_e32 v97, 0, v64
	v_exp_f32_e32 v69, v69
	v_add_f32_e32 v97, v65, v97
	v_exp_f32_e32 v70, v70
	v_add_f32_e32 v97, v66, v97
	v_exp_f32_e32 v71, v71
	v_add_f32_e32 v97, v67, v97
	v_exp_f32_e32 v72, v72
	v_add_f32_e32 v97, v68, v97
	v_exp_f32_e32 v73, v73
	v_add_f32_e32 v97, v69, v97
	v_exp_f32_e32 v74, v74
	v_add_f32_e32 v97, v70, v97
	v_exp_f32_e32 v75, v75
	v_add_f32_e32 v97, v71, v97
	v_exp_f32_e32 v76, v76
	v_add_f32_e32 v97, v72, v97
	v_exp_f32_e32 v77, v77
	v_add_f32_e32 v97, v73, v97
	v_exp_f32_e32 v78, v78
	v_add_f32_e32 v97, v74, v97
	v_exp_f32_e32 v79, v79
	v_add_f32_e32 v97, v75, v97
	v_add_f32_e32 v97, v76, v97
	v_add_f32_e32 v97, v77, v97
	v_add_f32_e32 v97, v78, v97
	v_add_f32_e32 v97, v79, v97
	v_add_f32_e32 v97, v97, v120
	v_cvt_pk_bf16_f32 v64, v64, v65
	v_cvt_pk_bf16_f32 v65, v66, v67
	v_cvt_pk_bf16_f32 v66, v68, v69
	v_cvt_pk_bf16_f32 v67, v70, v71
	v_cvt_pk_bf16_f32 v68, v72, v73
	v_cvt_pk_bf16_f32 v69, v74, v75
	v_cvt_pk_bf16_f32 v70, v76, v77
	v_cvt_pk_bf16_f32 v71, v78, v79
	s_nop 0
	v_permlane32_swap_b32_e32 v64, v66
	v_permlane32_swap_b32_e32 v65, v67
	v_permlane32_swap_b32_e32 v68, v70
	v_permlane32_swap_b32_e32 v69, v71
	s_waitcnt lgkmcnt(0)
	s_setprio 1
	v_mfma_f32_32x32x16_bf16 v[0:15], v[64:67], v[132:135], v[0:15]
	s_cmp_gt_i32 s47, 61
	s_cselect_b64 s[0:1], -1, 0
	s_cmp_lt_i32 s45, 62
	s_cselect_b64 s[2:3], -1, 0
	s_or_b64 s[0:1], s[0:1], s[2:3]
	s_and_b64 vcc, exec, s[0:1]
	v_mfma_f32_32x32x16_bf16 v[48:63], v[64:67], v[140:143], v[48:63]
	v_mfma_f32_32x32x16_bf16 v[16:31], v[64:67], v[148:151], v[16:31]
	v_mfma_f32_32x32x16_bf16 v[32:47], v[64:67], v[156:159], v[32:47]
	v_mfma_f32_32x32x16_bf16 v[0:15], v[68:71], v[136:139], v[0:15]
	v_mfma_f32_32x32x16_bf16 v[48:63], v[68:71], v[144:147], v[48:63]
	v_mfma_f32_32x32x16_bf16 v[16:31], v[68:71], v[152:155], v[16:31]
	v_mfma_f32_32x32x16_bf16 v[32:47], v[68:71], v[162:165], v[32:47]
	s_waitcnt lgkmcnt(0)
	v_mfma_f32_32x32x16_bf16 v[64:79], v[98:101], v[92:95], 0
	v_mfma_f32_32x32x16_bf16 v[64:79], v[102:105], v[88:91], v[64:79]
	v_mfma_f32_32x32x16_bf16 v[64:79], v[114:117], v[84:87], v[64:79]
	v_mfma_f32_32x32x16_bf16 v[64:79], v[122:125], v[80:83], v[64:79]
	s_setprio 0
	s_cbranch_vccnz .LBB0_1963
	v_sub_u32_e32 v98, 0xf40, v111
	v_lshlrev_b32_e32 v98, 2, v98
	v_add3_u32 v98, s88, v98, v130
	v_add_u32_e32 v114, 0x400, v98
	v_add_u32_e32 v116, 0x408, v98
	v_add_u32_e32 v118, 0x420, v98
	v_add_u32_e32 v120, 0x428, v98
	v_add_u32_e32 v99, 0x440, v98
	v_add_u32_e32 v100, 0x448, v98
	v_add_u32_e32 v102, 0x460, v98
	v_add_u32_e32 v104, 0x468, v98
	ds_read2_b32 v[98:99], v99 offset1:1
	ds_read2_b32 v[100:101], v100 offset1:1
	ds_read2_b32 v[102:103], v102 offset1:1
	ds_read2_b32 v[104:105], v104 offset1:1
	ds_read2_b32 v[114:115], v114 offset1:1
	ds_read2_b32 v[116:117], v116 offset1:1
	ds_read2_b32 v[118:119], v118 offset1:1
	ds_read2_b32 v[120:121], v120 offset1:1
	s_waitcnt lgkmcnt(0)
	v_pk_add_f32 v[78:79], v[78:79], v[104:105]
	v_pk_add_f32 v[76:77], v[76:77], v[102:103]
	v_pk_add_f32 v[74:75], v[74:75], v[100:101]
	v_pk_add_f32 v[72:73], v[72:73], v[98:99]
	v_pk_add_f32 v[70:71], v[70:71], v[120:121]
	v_pk_add_f32 v[68:69], v[68:69], v[118:119]
	v_pk_add_f32 v[66:67], v[66:67], v[116:117]
	v_pk_add_f32 v[64:65], v[64:65], v[114:115]
.LBB0_1963:
	ds_read_b128 v[98:101], v107 offset:16384
	ds_read_b128 v[102:105], v108 offset:16384
	ds_read_b128 v[114:117], v109 offset:16384
	ds_read_b128 v[118:121], v110 offset:16384
	ds_read_b64_tr_b16 v[122:123], v96 offset:0x2000
	ds_read_b64_tr_b16 v[124:125], v96 offset:0x2800
	ds_read_b64_tr_b16 v[132:133], v96 offset:0x3000
	ds_read_b64_tr_b16 v[134:135], v96 offset:0x3800
	ds_read_b64_tr_b16 v[136:137], v96 offset:0x2200
	ds_read_b64_tr_b16 v[138:139], v96 offset:0x2a00
	ds_read_b64_tr_b16 v[140:141], v96 offset:0x3200
	ds_read_b64_tr_b16 v[142:143], v96 offset:0x3a00
	ds_read_b64_tr_b16 v[144:145], v96 offset:0x2400
	ds_read_b64_tr_b16 v[146:147], v96 offset:0x2c00
	ds_read_b64_tr_b16 v[148:149], v96 offset:0x3400
	ds_read_b64_tr_b16 v[150:151], v96 offset:0x3c00
	ds_read_b64_tr_b16 v[152:153], v96 offset:0x2600
	ds_read_b64_tr_b16 v[154:155], v96 offset:0x2e00
	ds_read_b64_tr_b16 v[156:157], v96 offset:0x3600
	ds_read_b64_tr_b16 v[158:159], v96 offset:0x3e00
	s_nop 6
	s_setprio 2
	v_exp_f32_e32 v64, v64
	v_exp_f32_e32 v65, v65
	v_exp_f32_e32 v66, v66
	v_exp_f32_e32 v67, v67
	v_exp_f32_e32 v68, v68
	v_add_f32_e32 v96, 0, v64
	v_exp_f32_e32 v69, v69
	v_add_f32_e32 v96, v65, v96
	v_exp_f32_e32 v70, v70
	v_add_f32_e32 v96, v66, v96
	v_exp_f32_e32 v71, v71
	v_add_f32_e32 v96, v67, v96
	v_exp_f32_e32 v72, v72
	v_add_f32_e32 v96, v68, v96
	v_exp_f32_e32 v73, v73
	v_add_f32_e32 v96, v69, v96
	v_exp_f32_e32 v74, v74
	v_add_f32_e32 v96, v70, v96
	v_exp_f32_e32 v75, v75
	v_add_f32_e32 v96, v71, v96
	v_exp_f32_e32 v76, v76
	v_add_f32_e32 v96, v72, v96
	v_exp_f32_e32 v77, v77
	v_add_f32_e32 v96, v73, v96
	v_exp_f32_e32 v78, v78
	v_add_f32_e32 v96, v74, v96
	v_exp_f32_e32 v79, v79
	v_add_f32_e32 v96, v75, v96
	v_add_f32_e32 v96, v76, v96
	v_add_f32_e32 v96, v77, v96
	v_add_f32_e32 v96, v78, v96
	v_add_f32_e32 v96, v79, v96
	v_add_f32_e32 v96, v97, v96
	v_cvt_pk_bf16_f32 v64, v64, v65
	v_cvt_pk_bf16_f32 v65, v66, v67
	v_cvt_pk_bf16_f32 v66, v68, v69
	v_cvt_pk_bf16_f32 v67, v70, v71
	v_cvt_pk_bf16_f32 v68, v72, v73
	v_cvt_pk_bf16_f32 v69, v74, v75
	v_cvt_pk_bf16_f32 v70, v76, v77
	v_cvt_pk_bf16_f32 v71, v78, v79
	s_nop 0
	v_permlane32_swap_b32_e32 v64, v66
	v_permlane32_swap_b32_e32 v65, v67
	v_permlane32_swap_b32_e32 v68, v70
	v_permlane32_swap_b32_e32 v69, v71
	s_waitcnt lgkmcnt(0)
	s_setprio 1
	s_cmp_lt_u32 s33, 0x100
	s_cbranch_scc1 .Lstg_d1_m61_21
	s_waitcnt vmcnt(0)
	s_barrier

; DI int v_rd_base(int lane) { return ((lane & 3) << 3) | (((lane >> 2) & 3) << 6) | (((lane >> 4) & 1) << 5) | (((lane >> 5) & 1) << 8); }
; template <int DQK, int MODE, int LDQ, int LDK, int LDV> ...
;     ...
;     const int vbase = (int)(unsigned)(size_t)lds + V_OFF + v_rd_base(lane);
;     ...
;     constexpr int NDA = ND0 > 6 ? 6 : ND0;
.Lstg_d1_t62_22:
	s_setprio 0
	s_cmp_lg_u32 s45, 62
	s_cselect_b64 s[6:7], -1, 0
	s_and_b64 s[0:1], s[6:7], s[0:1]
	s_and_b64 vcc, exec, s[0:1]
	s_cbranch_vccnz .LBB0_1967
	v_cndmask_b32_e64 v98, v112, v113, s[4:5]
	v_pk_mul_f32 v[14:15], v[98:99], v[14:15] op_sel_hi:[0,1]
	v_pk_mul_f32 v[12:13], v[98:99], v[12:13] op_sel_hi:[0,1]
	v_pk_mul_f32 v[10:11], v[98:99], v[10:11] op_sel_hi:[0,1]
	v_pk_mul_f32 v[8:9], v[98:99], v[8:9] op_sel_hi:[0,1]
	v_pk_mul_f32 v[6:7], v[98:99], v[6:7] op_sel_hi:[0,1]
	v_pk_mul_f32 v[4:5], v[98:99], v[4:5] op_sel_hi:[0,1]
	v_pk_mul_f32 v[2:3], v[98:99], v[2:3] op_sel_hi:[0,1]
	v_pk_mul_f32 v[0:1], v[98:99], v[0:1] op_sel_hi:[0,1]
	v_pk_mul_f32 v[62:63], v[98:99], v[62:63] op_sel_hi:[0,1]
	v_pk_mul_f32 v[60:61], v[98:99], v[60:61] op_sel_hi:[0,1]
	v_pk_mul_f32 v[58:59], v[98:99], v[58:59] op_sel_hi:[0,1]
	v_pk_mul_f32 v[56:57], v[98:99], v[56:57] op_sel_hi:[0,1]
	v_pk_mul_f32 v[54:55], v[98:99], v[54:55] op_sel_hi:[0,1]
	v_pk_mul_f32 v[52:53], v[98:99], v[52:53] op_sel_hi:[0,1]
	v_pk_mul_f32 v[50:51], v[98:99], v[50:51] op_sel_hi:[0,1]
	v_pk_mul_f32 v[48:49], v[98:99], v[48:49] op_sel_hi:[0,1]
	v_pk_mul_f32 v[30:31], v[98:99], v[30:31] op_sel_hi:[0,1]
	v_pk_mul_f32 v[28:29], v[98:99], v[28:29] op_sel_hi:[0,1]
	v_pk_mul_f32 v[26:27], v[98:99], v[26:27] op_sel_hi:[0,1]
	v_pk_mul_f32 v[24:25], v[98:99], v[24:25] op_sel_hi:[0,1]
	v_pk_mul_f32 v[22:23], v[98:99], v[22:23] op_sel_hi:[0,1]
	v_pk_mul_f32 v[20:21], v[98:99], v[20:21] op_sel_hi:[0,1]
	v_pk_mul_f32 v[18:19], v[98:99], v[18:19] op_sel_hi:[0,1]
	v_pk_mul_f32 v[16:17], v[98:99], v[16:17] op_sel_hi:[0,1]
	v_pk_mul_f32 v[46:47], v[98:99], v[46:47] op_sel_hi:[0,1]
	v_pk_mul_f32 v[44:45], v[98:99], v[44:45] op_sel_hi:[0,1]
	v_pk_mul_f32 v[42:43], v[98:99], v[42:43] op_sel_hi:[0,1]
	v_pk_mul_f32 v[40:41], v[98:99], v[40:41] op_sel_hi:[0,1]
	v_pk_mul_f32 v[38:39], v[98:99], v[38:39] op_sel_hi:[0,1]
	v_pk_mul_f32 v[36:37], v[98:99], v[36:37] op_sel_hi:[0,1]
	v_pk_mul_f32 v[34:35], v[98:99], v[34:35] op_sel_hi:[0,1]
	v_pk_mul_f32 v[32:33], v[98:99], v[32:33] op_sel_hi:[0,1]
	v_mul_f32_e32 v96, v98, v96
.LBB0_1967:
	ds_read_b128 v[100:103], v107 offset:20480
	ds_read_b128 v[114:117], v108 offset:20480
	ds_read_b128 v[118:121], v109 offset:20480
	ds_read_b128 v[122:125], v110 offset:20480
	v_add_u32_e32 v98, 0x8000, v106
	ds_read_b64_tr_b16 v[132:133], v98 offset:0
	ds_read_b64_tr_b16 v[134:135], v98 offset:0x800
	ds_read_b64_tr_b16 v[136:137], v98 offset:0x1000
	ds_read_b64_tr_b16 v[138:139], v98 offset:0x1800
	ds_read_b64_tr_b16 v[140:141], v98 offset:0x200
	ds_read_b64_tr_b16 v[142:143], v98 offset:0xa00
	ds_read_b64_tr_b16 v[144:145], v98 offset:0x1200
	ds_read_b64_tr_b16 v[146:147], v98 offset:0x1a00
	ds_read_b64_tr_b16 v[148:149], v98 offset:0x400
	ds_read_b64_tr_b16 v[150:151], v98 offset:0xc00
	ds_read_b64_tr_b16 v[152:153], v98 offset:0x1400
	ds_read_b64_tr_b16 v[154:155], v98 offset:0x1c00
	ds_read_b64_tr_b16 v[156:157], v98 offset:0x600
	ds_read_b64_tr_b16 v[158:159], v98 offset:0xe00
	ds_read_b64_tr_b16 v[162:163], v98 offset:0x1600
	ds_read_b64_tr_b16 v[164:165], v98 offset:0x1e00
	s_setprio 2
	v_exp_f32_e32 v64, v64
	v_exp_f32_e32 v65, v65
	v_exp_f32_e32 v66, v66
	v_exp_f32_e32 v67, v67
	v_exp_f32_e32 v68, v68
	v_add_f32_e32 v99, 0, v64
	v_exp_f32_e32 v69, v69
	v_add_f32_e32 v99, v65, v99
	v_exp_f32_e32 v70, v70
	v_add_f32_e32 v99, v66, v99
	v_exp_f32_e32 v71, v71
	v_add_f32_e32 v99, v67, v99
	v_exp_f32_e32 v72, v72
	v_add_f32_e32 v99, v68, v99
	v_exp_f32_e32 v73, v73
	v_add_f32_e32 v99, v69, v99
	v_exp_f32_e32 v74, v74
	v_add_f32_e32 v99, v70, v99
	v_exp_f32_e32 v75, v75
	v_add_f32_e32 v99, v71, v99
	v_exp_f32_e32 v76, v76
	v_add_f32_e32 v99, v72, v99
	v_exp_f32_e32 v77, v77
	v_add_f32_e32 v99, v73, v99
	v_exp_f32_e32 v78, v78
	v_add_f32_e32 v99, v74, v99
	v_exp_f32_e32 v79, v79
	v_add_f32_e32 v99, v75, v99
	v_add_f32_e32 v99, v76, v99
	v_add_f32_e32 v99, v77, v99
	v_add_f32_e32 v99, v78, v99
	v_add_f32_e32 v99, v79, v99
	v_add_f32_e32 v96, v99, v96
	v_cvt_pk_bf16_f32 v64, v64, v65
	v_cvt_pk_bf16_f32 v65, v66, v67
	v_cvt_pk_bf16_f32 v66, v68, v69
	v_cvt_pk_bf16_f32 v67, v70, v71
	v_cvt_pk_bf16_f32 v68, v72, v73
	v_cvt_pk_bf16_f32 v69, v74, v75
	v_cvt_pk_bf16_f32 v70, v76, v77
	v_cvt_pk_bf16_f32 v71, v78, v79
	s_nop 0
	v_permlane32_swap_b32_e32 v64, v66
	v_permlane32_swap_b32_e32 v65, v67
	v_permlane32_swap_b32_e32 v68, v70
	v_permlane32_swap_b32_e32 v69, v71
	s_waitcnt lgkmcnt(0)
	s_setprio 1
	v_mfma_f32_32x32x16_bf16 v[0:15], v[64:67], v[132:135], v[0:15]
	s_and_b64 vcc, exec, s[2:3]
	v_mfma_f32_32x32x16_bf16 v[48:63], v[64:67], v[140:143], v[48:63]
	v_mfma_f32_32x32x16_bf16 v[16:31], v[64:67], v[148:151], v[16:31]
	v_mfma_f32_32x32x16_bf16 v[32:47], v[64:67], v[156:159], v[32:47]
	v_mfma_f32_32x32x16_bf16 v[0:15], v[68:71], v[136:139], v[0:15]
	v_mfma_f32_32x32x16_bf16 v[48:63], v[68:71], v[144:147], v[48:63]
	v_mfma_f32_32x32x16_bf16 v[16:31], v[68:71], v[152:155], v[16:31]
	v_mfma_f32_32x32x16_bf16 v[32:47], v[68:71], v[162:165], v[32:47]
	s_waitcnt lgkmcnt(0)
	v_mfma_f32_32x32x16_bf16 v[64:79], v[100:103], v[92:95], 0
	v_mfma_f32_32x32x16_bf16 v[64:79], v[114:117], v[88:91], v[64:79]
	v_mfma_f32_32x32x16_bf16 v[64:79], v[118:121], v[84:87], v[64:79]
	v_mfma_f32_32x32x16_bf16 v[64:79], v[122:125], v[80:83], v[64:79]
	s_setprio 0
	s_cbranch_vccnz .LBB0_1969
	v_add3_u32 v97, s88, v97, v130
	v_add_u32_e32 v118, 0x408, v97
	v_add_u32_e32 v120, 0x420, v97
	v_add_u32_e32 v122, 0x428, v97
	v_add_u32_e32 v100, 0x440, v97
	v_add_u32_e32 v102, 0x448, v97
	v_add_u32_e32 v104, 0x460, v97
	v_add_u32_e32 v99, 0x400, v97
	v_add_u32_e32 v97, 0x468, v97
	ds_read2_b32 v[100:101], v100 offset1:1
	ds_read2_b32 v[102:103], v102 offset1:1
	ds_read2_b32 v[104:105], v104 offset1:1
	ds_read2_b32 v[114:115], v97 offset1:1
	ds_read2_b32 v[116:117], v99 offset1:1
	ds_read2_b32 v[118:119], v118 offset1:1
	ds_read2_b32 v[120:121], v120 offset1:1
	ds_read2_b32 v[122:123], v122 offset1:1
	s_waitcnt lgkmcnt(0)
	v_pk_add_f32 v[78:79], v[78:79], v[114:115]
	v_pk_add_f32 v[76:77], v[76:77], v[104:105]
	v_pk_add_f32 v[74:75], v[74:75], v[102:103]
	v_pk_add_f32 v[72:73], v[72:73], v[100:101]
	v_pk_add_f32 v[70:71], v[70:71], v[122:123]
	v_pk_add_f32 v[68:69], v[68:69], v[120:121]
	v_pk_add_f32 v[66:67], v[66:67], v[118:119]
	v_pk_add_f32 v[64:65], v[64:65], v[116:117]

; DI int v_rd_base(int lane) { return ((lane & 3) << 3) | (((lane >> 2) & 3) << 6) | (((lane >> 4) & 1) << 5) | (((lane >> 5) & 1) << 8); }
; template <int DQK, int MODE, int LDQ, int LDK, int LDV> ...
;     ...
;     const int vbase = (int)(unsigned)(size_t)lds + V_OFF + v_rd_base(lane);
;     ...
;     constexpr int NDA = ND0 > 6 ? 6 : ND0;
.Lstg_d1_t63_24:
	s_setprio 0
	s_cmp_lg_u32 s45, 63
	s_cselect_b64 s[6:7], -1, 0
	s_and_b64 s[0:1], s[6:7], s[0:1]
	s_and_b64 vcc, exec, s[0:1]
	s_cbranch_vccnz .LBB0_1973
	v_cndmask_b32_e64 v98, v112, v113, s[4:5]
	v_pk_mul_f32 v[14:15], v[98:99], v[14:15] op_sel_hi:[0,1]
	v_pk_mul_f32 v[12:13], v[98:99], v[12:13] op_sel_hi:[0,1]
	v_pk_mul_f32 v[10:11], v[98:99], v[10:11] op_sel_hi:[0,1]
	v_pk_mul_f32 v[8:9], v[98:99], v[8:9] op_sel_hi:[0,1]
	v_pk_mul_f32 v[6:7], v[98:99], v[6:7] op_sel_hi:[0,1]
	v_pk_mul_f32 v[4:5], v[98:99], v[4:5] op_sel_hi:[0,1]
	v_pk_mul_f32 v[2:3], v[98:99], v[2:3] op_sel_hi:[0,1]
	v_pk_mul_f32 v[0:1], v[98:99], v[0:1] op_sel_hi:[0,1]
	v_pk_mul_f32 v[62:63], v[98:99], v[62:63] op_sel_hi:[0,1]
	v_pk_mul_f32 v[60:61], v[98:99], v[60:61] op_sel_hi:[0,1]
	v_pk_mul_f32 v[58:59], v[98:99], v[58:59] op_sel_hi:[0,1]
	v_pk_mul_f32 v[56:57], v[98:99], v[56:57] op_sel_hi:[0,1]
	v_pk_mul_f32 v[54:55], v[98:99], v[54:55] op_sel_hi:[0,1]
	v_pk_mul_f32 v[52:53], v[98:99], v[52:53] op_sel_hi:[0,1]
	v_pk_mul_f32 v[50:51], v[98:99], v[50:51] op_sel_hi:[0,1]
	v_pk_mul_f32 v[48:49], v[98:99], v[48:49] op_sel_hi:[0,1]
	v_pk_mul_f32 v[30:31], v[98:99], v[30:31] op_sel_hi:[0,1]
	v_pk_mul_f32 v[28:29], v[98:99], v[28:29] op_sel_hi:[0,1]
	v_pk_mul_f32 v[26:27], v[98:99], v[26:27] op_sel_hi:[0,1]
	v_pk_mul_f32 v[24:25], v[98:99], v[24:25] op_sel_hi:[0,1]
	v_pk_mul_f32 v[22:23], v[98:99], v[22:23] op_sel_hi:[0,1]
	v_pk_mul_f32 v[20:21], v[98:99], v[20:21] op_sel_hi:[0,1]
	v_pk_mul_f32 v[18:19], v[98:99], v[18:19] op_sel_hi:[0,1]
	v_pk_mul_f32 v[16:17], v[98:99], v[16:17] op_sel_hi:[0,1]
	v_pk_mul_f32 v[46:47], v[98:99], v[46:47] op_sel_hi:[0,1]
	v_pk_mul_f32 v[44:45], v[98:99], v[44:45] op_sel_hi:[0,1]
	v_pk_mul_f32 v[42:43], v[98:99], v[42:43] op_sel_hi:[0,1]
	v_pk_mul_f32 v[40:41], v[98:99], v[40:41] op_sel_hi:[0,1]
	v_pk_mul_f32 v[38:39], v[98:99], v[38:39] op_sel_hi:[0,1]
	v_pk_mul_f32 v[36:37], v[98:99], v[36:37] op_sel_hi:[0,1]
	v_pk_mul_f32 v[34:35], v[98:99], v[34:35] op_sel_hi:[0,1]
	v_pk_mul_f32 v[32:33], v[98:99], v[32:33] op_sel_hi:[0,1]
	v_mul_f32_e32 v96, v98, v96
.LBB0_1973:
	ds_read_b128 v[98:101], v107 offset:28672
	ds_read_b128 v[102:105], v108 offset:28672
	ds_read_b128 v[112:115], v109 offset:28672
	ds_read_b128 v[108:111], v110 offset:28672
	ds_read_b64_tr_b16 v[116:117], v106 offset:0
	ds_read_b64_tr_b16 v[118:119], v106 offset:0x800
	ds_read_b64_tr_b16 v[120:121], v106 offset:0x1000
	ds_read_b64_tr_b16 v[122:123], v106 offset:0x1800
	ds_read_b64_tr_b16 v[124:125], v106 offset:0x200
	ds_read_b64_tr_b16 v[126:127], v106 offset:0xa00
	ds_read_b64_tr_b16 v[132:133], v106 offset:0x1200
	ds_read_b64_tr_b16 v[134:135], v106 offset:0x1a00
	ds_read_b64_tr_b16 v[136:137], v106 offset:0x400
	ds_read_b64_tr_b16 v[138:139], v106 offset:0xc00
	ds_read_b64_tr_b16 v[140:141], v106 offset:0x1400
	ds_read_b64_tr_b16 v[142:143], v106 offset:0x1c00
	ds_read_b64_tr_b16 v[144:145], v106 offset:0x600
	ds_read_b64_tr_b16 v[146:147], v106 offset:0xe00
	ds_read_b64_tr_b16 v[148:149], v106 offset:0x1600
	ds_read_b64_tr_b16 v[150:151], v106 offset:0x1e00
	s_setprio 2
	v_exp_f32_e32 v64, v64
	v_exp_f32_e32 v65, v65
	v_exp_f32_e32 v66, v66
	v_exp_f32_e32 v67, v67
	v_exp_f32_e32 v68, v68
	v_add_f32_e32 v107, 0, v64
	v_exp_f32_e32 v69, v69
	v_add_f32_e32 v107, v65, v107
	v_exp_f32_e32 v70, v70
	v_add_f32_e32 v107, v66, v107
	v_exp_f32_e32 v71, v71
	v_add_f32_e32 v107, v67, v107
	v_exp_f32_e32 v72, v72
	v_add_f32_e32 v107, v68, v107
	v_exp_f32_e32 v73, v73
	v_add_f32_e32 v107, v69, v107
	v_exp_f32_e32 v74, v74
	v_add_f32_e32 v107, v70, v107
	v_exp_f32_e32 v75, v75
	v_add_f32_e32 v107, v71, v107
	v_exp_f32_e32 v76, v76
	v_add_f32_e32 v107, v72, v107
	v_exp_f32_e32 v77, v77
	v_add_f32_e32 v107, v73, v107
	v_exp_f32_e32 v78, v78
	v_add_f32_e32 v107, v74, v107
	v_exp_f32_e32 v79, v79
	v_add_f32_e32 v107, v75, v107
	v_add_f32_e32 v107, v76, v107
	v_add_f32_e32 v107, v77, v107
	v_add_f32_e32 v107, v78, v107
	v_add_f32_e32 v107, v79, v107
	v_add_f32_e32 v96, v107, v96
	v_cvt_pk_bf16_f32 v64, v64, v65
	v_cvt_pk_bf16_f32 v65, v66, v67
	v_cvt_pk_bf16_f32 v66, v68, v69
	v_cvt_pk_bf16_f32 v67, v70, v71
	v_cvt_pk_bf16_f32 v68, v72, v73
	v_cvt_pk_bf16_f32 v69, v74, v75
	v_cvt_pk_bf16_f32 v70, v76, v77
	v_cvt_pk_bf16_f32 v71, v78, v79
	s_nop 0
	v_permlane32_swap_b32_e32 v64, v66
	v_permlane32_swap_b32_e32 v65, v67
	v_permlane32_swap_b32_e32 v68, v70
	v_permlane32_swap_b32_e32 v69, v71
	s_waitcnt lgkmcnt(0)
	s_setprio 1
	v_mfma_f32_32x32x16_bf16 v[0:15], v[64:67], v[116:119], v[0:15]
	s_and_b64 vcc, exec, s[2:3]
	v_mfma_f32_32x32x16_bf16 v[48:63], v[64:67], v[124:127], v[48:63]
	v_mfma_f32_32x32x16_bf16 v[16:31], v[64:67], v[136:139], v[16:31]
	v_mfma_f32_32x32x16_bf16 v[32:47], v[64:67], v[144:147], v[32:47]
	v_mfma_f32_32x32x16_bf16 v[0:15], v[68:71], v[120:123], v[0:15]
	v_mfma_f32_32x32x16_bf16 v[48:63], v[68:71], v[132:135], v[48:63]
	v_mfma_f32_32x32x16_bf16 v[16:31], v[68:71], v[140:143], v[16:31]
	v_mfma_f32_32x32x16_bf16 v[32:47], v[68:71], v[148:151], v[32:47]
	s_waitcnt lgkmcnt(0)
	v_mfma_f32_32x32x16_bf16 v[64:79], v[98:101], v[92:95], 0
	v_mfma_f32_32x32x16_bf16 v[64:79], v[102:105], v[88:91], v[64:79]
	v_mfma_f32_32x32x16_bf16 v[64:79], v[112:115], v[84:87], v[64:79]
	v_mfma_f32_32x32x16_bf16 v[64:79], v[108:111], v[80:83], v[64:79]
	s_setprio 0
	s_cbranch_vccnz .LBB0_1975
	v_add3_u32 v80, s88, v97, v130
	v_add_u32_e32 v88, 0x400, v80
	v_add_u32_e32 v90, 0x408, v80
	v_add_u32_e32 v92, 0x420, v80
	v_add_u32_e32 v94, 0x428, v80
	v_add_u32_e32 v81, 0x440, v80
	v_add_u32_e32 v82, 0x448, v80
	v_add_u32_e32 v84, 0x460, v80
	v_add_u32_e32 v86, 0x468, v80
	ds_read2_b32 v[80:81], v81 offset1:1
	ds_read2_b32 v[82:83], v82 offset1:1
	ds_read2_b32 v[84:85], v84 offset1:1
	ds_read2_b32 v[86:87], v86 offset1:1
	ds_read2_b32 v[88:89], v88 offset1:1
	ds_read2_b32 v[90:91], v90 offset1:1
	ds_read2_b32 v[92:93], v92 offset1:1
	ds_read2_b32 v[94:95], v94 offset1:1
	s_waitcnt lgkmcnt(0)
	v_pk_add_f32 v[78:79], v[78:79], v[86:87]
	v_pk_add_f32 v[76:77], v[76:77], v[84:85]
	v_pk_add_f32 v[74:75], v[74:75], v[82:83]
	v_pk_add_f32 v[72:73], v[72:73], v[80:81]
	v_pk_add_f32 v[70:71], v[70:71], v[94:95]
	v_pk_add_f32 v[68:69], v[68:69], v[92:93]
	v_pk_add_f32 v[66:67], v[66:67], v[90:91]
	v_pk_add_f32 v[64:65], v[64:65], v[88:89]
; template <int TAG = 0> DI int fresh_tid(int wv) { int l; asm volatile("v_mbcnt_lo_u32_b32 %0, -1, 0\n\tv_mbcnt_hi_u32_b32 %0, -1, %0 ; site %1" : "=v"(l) : "n"(TAG)); return wv * 64 + l; }
; DI int crow(int r, int hi) { return (r & 3) + 8 * (r >> 2) + 4 * hi; }
; DI float swap_sum(float v) { auto rr = __builtin_amdgcn_permlane32_swap(__float_as_uint(v), __float_as_uint(v), false, false); return __uint_as_float(rr[0]) + __uint_as_float(rr[1]); }
; template <int DQK, int MODE, int LDQ, int LDK, int LDV> ...
;     ...
;     l_reg = swap_sum(l_reg);
;     { const int lane2 = fresh_tid<110 + MODE>(wv) & 63, r32 = lane2 & 31, hi = lane2 >> 5;
;     if (hi == 0) li_l[r32] = l_reg;
;     asm volatile("s_waitcnt lgkmcnt(0)" ::: "memory");
;     float s0v[MODE == 2 ? 16 : 1][4];
;     if constexpr (MODE == 2) {
; #pragma unroll
;         for (int r = 0; r < 16; ++r)
; #pragma unroll
;             for (int d0 = 0; d0 < 4; ++d0) s0v[r][d0] = S0[(size_t)(wid * 32 + crow(r, hi)) * 512 + d0 * 32 + r32];
;     }
.LBB0_1975:
	s_lshl_b32 s0, s44, 2
	s_add_i32 s0, s0, 0
	s_add_i32 s0, s0, 0x24000
	ds_read_b64_tr_b16 v[80:81], v106 offset:0x2000
	ds_read_b64_tr_b16 v[82:83], v106 offset:0x2800
	ds_read_b64_tr_b16 v[84:85], v106 offset:0x3000
	ds_read_b64_tr_b16 v[86:87], v106 offset:0x3800
	ds_read_b64_tr_b16 v[88:89], v106 offset:0x2200
	ds_read_b64_tr_b16 v[90:91], v106 offset:0x2a00
	ds_read_b64_tr_b16 v[92:93], v106 offset:0x3200
	ds_read_b64_tr_b16 v[94:95], v106 offset:0x3a00
	ds_read_b64_tr_b16 v[98:99], v106 offset:0x2400
	ds_read_b64_tr_b16 v[100:101], v106 offset:0x2c00
	ds_read_b64_tr_b16 v[102:103], v106 offset:0x3400
	ds_read_b64_tr_b16 v[104:105], v106 offset:0x3c00
	ds_read_b64_tr_b16 v[108:109], v106 offset:0x2600
	ds_read_b64_tr_b16 v[110:111], v106 offset:0x2e00
	ds_read_b64_tr_b16 v[112:113], v106 offset:0x3600
	ds_read_b64_tr_b16 v[114:115], v106 offset:0x3e00
	s_nop 7
	s_setprio 2
	v_exp_f32_e32 v97, v64
	v_exp_f32_e32 v65, v65
	v_exp_f32_e32 v106, v66
	v_exp_f32_e32 v67, v67
	v_exp_f32_e32 v68, v68
	v_add_f32_e32 v64, 0, v97
	v_exp_f32_e32 v69, v69
	v_add_f32_e32 v64, v65, v64
	v_exp_f32_e32 v70, v70
	v_add_f32_e32 v64, v106, v64
	v_exp_f32_e32 v71, v71
	v_add_f32_e32 v64, v67, v64
	v_exp_f32_e32 v72, v72
	v_add_f32_e32 v64, v68, v64
	v_exp_f32_e32 v73, v73
	v_add_f32_e32 v64, v69, v64
	v_exp_f32_e32 v74, v74
	v_add_f32_e32 v64, v70, v64
	v_exp_f32_e32 v75, v75
	v_add_f32_e32 v64, v71, v64
	v_exp_f32_e32 v76, v76
	v_add_f32_e32 v64, v72, v64
	v_exp_f32_e32 v77, v77
	v_add_f32_e32 v64, v73, v64
	v_exp_f32_e32 v78, v78
	v_add_f32_e32 v64, v74, v64
	v_exp_f32_e32 v79, v79
	v_add_f32_e32 v64, v75, v64
	v_add_f32_e32 v64, v76, v64
	v_add_f32_e32 v64, v77, v64
	v_add_f32_e32 v64, v78, v64
	v_add_f32_e32 v64, v79, v64
	v_add_f32_e32 v64, v96, v64
	v_cvt_pk_bf16_f32 v66, v97, v65
	v_cvt_pk_bf16_f32 v67, v106, v67
	v_cvt_pk_bf16_f32 v68, v68, v69
	v_cvt_pk_bf16_f32 v69, v70, v71
	v_cvt_pk_bf16_f32 v70, v72, v73
	v_cvt_pk_bf16_f32 v71, v74, v75
	v_cvt_pk_bf16_f32 v72, v76, v77
	v_cvt_pk_bf16_f32 v73, v78, v79
	s_nop 0
	v_permlane32_swap_b32_e32 v66, v68
	v_permlane32_swap_b32_e32 v67, v69
	v_permlane32_swap_b32_e32 v70, v72
	v_permlane32_swap_b32_e32 v71, v73
	s_waitcnt lgkmcnt(0)
	s_setprio 1
	v_mfma_f32_32x32x16_bf16 v[0:15], v[66:69], v[80:83], v[0:15]
	v_mfma_f32_32x32x16_bf16 v[48:63], v[66:69], v[88:91], v[48:63]
	v_mfma_f32_32x32x16_bf16 v[16:31], v[66:69], v[98:101], v[16:31]
	v_mfma_f32_32x32x16_bf16 v[32:47], v[66:69], v[108:111], v[32:47]
	v_mfma_f32_32x32x16_bf16 v[0:15], v[70:73], v[84:87], v[0:15]
	v_mfma_f32_32x32x16_bf16 v[48:63], v[70:73], v[92:95], v[48:63]
	v_mfma_f32_32x32x16_bf16 v[16:31], v[70:73], v[102:105], v[16:31]
	v_mfma_f32_32x32x16_bf16 v[32:47], v[70:73], v[112:115], v[32:47]
	s_setprio 0
	v_mov_b32_e32 v66, v64
	v_mbcnt_lo_u32_b32 v65, -1, 0
	v_mbcnt_hi_u32_b32 v65, -1, v65
	s_nop 1
	v_permlane32_swap_b32_e32 v64, v66
	v_and_b32_e32 v114, 63, v65
	v_and_b32_e32 v170, 31, v65
	v_cmp_gt_u32_e32 vcc, 32, v114
	s_and_saveexec_b64 s[2:3], vcc
	v_lshl_add_u32 v67, v170, 2, s0
	v_add_f32_e32 v64, v64, v66
	ds_write_b32 v67, v64
	s_or_b64 exec, exec, s[2:3]
	v_lshrrev_b32_e32 v64, 3, v65
	v_and_b32_e32 v69, 4, v64
	v_or_b32_e32 v102, s46, v69
	v_lshlrev_b32_e32 v130, 2, v170
	v_ashrrev_i32_e32 v103, 31, v102
	v_or_b32_e32 v66, 1, v102
	v_lshl_add_u64 v[92:93], s[54:55], 0, v[130:131]
	v_lshlrev_b64 v[156:157], 11, v[102:103]
	v_ashrrev_i32_e32 v67, 31, v66
	s_waitcnt lgkmcnt(0)
	v_lshl_add_u64 v[64:65], v[92:93], 0, v[156:157]
	v_lshlrev_b64 v[148:149], 11, v[66:67]
	v_lshl_add_u64 v[66:67], v[92:93], 0, v[148:149]
	global_load_dword v110, v[64:65], off
	global_load_dword v111, v[64:65], off offset:128
	global_load_dword v109, v[64:65], off offset:256
	global_load_dword v108, v[64:65], off offset:384
	global_load_dword v106, v[66:67], off
	global_load_dword v107, v[66:67], off offset:128
	global_load_dword v105, v[66:67], off offset:256
	global_load_dword v104, v[66:67], off offset:384
	v_or_b32_e32 v64, 2, v102
	v_or_b32_e32 v66, 3, v102
	v_ashrrev_i32_e32 v65, 31, v64
	v_ashrrev_i32_e32 v67, 31, v66
	v_lshlrev_b64 v[146:147], 11, v[64:65]
	v_lshlrev_b64 v[136:137], 11, v[66:67]
	v_lshl_add_u64 v[64:65], v[92:93], 0, v[146:147]
	v_lshl_add_u64 v[66:67], v[92:93], 0, v[136:137]
	global_load_dword v158, v[64:65], off
	global_load_dword v159, v[64:65], off offset:128
	global_load_dword v155, v[64:65], off offset:256
	global_load_dword v154, v[64:65], off offset:384
	global_load_dword v152, v[66:67], off
	global_load_dword v153, v[66:67], off offset:128
	global_load_dword v151, v[66:67], off offset:256
	global_load_dword v150, v[66:67], off offset:384
	v_or_b32_e32 v64, 8, v102
	v_or_b32_e32 v66, 9, v102
	v_ashrrev_i32_e32 v65, 31, v64
	v_ashrrev_i32_e32 v67, 31, v66
	v_lshlrev_b64 v[134:135], 11, v[64:65]
	v_lshlrev_b64 v[120:121], 11, v[66:67]
	v_lshl_add_u64 v[64:65], v[92:93], 0, v[134:135]
	v_lshl_add_u64 v[66:67], v[92:93], 0, v[120:121]
	global_load_dword v144, v[64:65], off
	global_load_dword v145, v[64:65], off offset:128
	global_load_dword v143, v[64:65], off offset:256
	global_load_dword v142, v[64:65], off offset:384
	global_load_dword v140, v[66:67], off
	global_load_dword v141, v[66:67], off offset:128
	global_load_dword v139, v[66:67], off offset:256
	global_load_dword v138, v[66:67], off offset:384
	v_or_b32_e32 v64, 10, v102
	v_or_b32_e32 v66, 11, v102
	v_ashrrev_i32_e32 v65, 31, v64
	v_ashrrev_i32_e32 v67, 31, v66
	v_lshlrev_b64 v[118:119], 11, v[64:65]
	v_lshlrev_b64 v[90:91], 11, v[66:67]
	v_lshl_add_u64 v[64:65], v[92:93], 0, v[118:119]
	v_lshl_add_u64 v[66:67], v[92:93], 0, v[90:91]
; DI unsigned short f2bf(float x) { unsigned u = __float_as_uint(x); u += 0x7fffu + ((u >> 16) & 1u); return (unsigned short)(u >> 16); }
; DI float shx(float v, int mask, int lane) { return __int_as_float(__builtin_amdgcn_ds_bpermute((lane ^ mask) << 2, __float_as_int(v))); }
; DI int crow(int r, int hi) { return (r & 3) + 8 * (r >> 2) + 4 * hi; }
; template <int DQK, int MODE, int LDQ, int LDK, int LDV> ...
;     ...
;             for (int d0 = 0; d0 < 4; ++d0) s0v[r][d0] = S0[(size_t)(wid * 32 + crow(r, hi)) * 512 + d0 * 32 + r32];
;     }
; #pragma unroll
;     for (int r = 0; r < 16; ++r) { const int orow = wid * 32 + crow(r, hi); const float rl = __builtin_amdgcn_rcpf(li_l[crow(r, hi)]);
;         if constexpr (MODE == 0) {
; #pragma unroll
;             for (int d0 = 0; d0 < 4; ++d0) AOb[(size_t)orow * 1024 + d0 * 32 + r32] = f2bf(o[d0][r] * rl);
;         } else if constexpr (MODE == 1) {
; #pragma unroll
;             for (int d0 = 0; d0 < 4; ++d0) S0[(size_t)orow * 512 + d0 * 32 + r32] = o[d0][r] * rl;
;         } else {
;             float v[4]; float ss = 0.f;
; #pragma unroll
;             for (int d0 = 0; d0 < 4; ++d0) { v[d0] = s0v[r][d0] - lam * (o[d0][r] * rl); ss += v[d0] * v[d0]; }
; #pragma unroll
;             for (int mk = 1; mk <= 16; mk <<= 1) ss += shx(ss, mk, lane2);
;             const float rs = rsqrtf(ss * (1.f / 128.f) + EPS) * 0.8f;
	global_load_dword v132, v[64:65], off
	global_load_dword v133, v[64:65], off offset:128
	global_load_dword v127, v[64:65], off offset:256
	global_load_dword v126, v[64:65], off offset:384
	global_load_dword v124, v[66:67], off
	global_load_dword v125, v[66:67], off offset:128
	global_load_dword v123, v[66:67], off offset:256
	global_load_dword v122, v[66:67], off offset:384
	v_or_b32_e32 v64, 16, v102
	v_or_b32_e32 v66, 17, v102
	v_ashrrev_i32_e32 v65, 31, v64
	v_ashrrev_i32_e32 v67, 31, v66
	v_lshlrev_b64 v[86:87], 11, v[64:65]
	v_lshlrev_b64 v[78:79], 11, v[66:67]
	v_lshl_add_u64 v[64:65], v[92:93], 0, v[86:87]
	v_lshl_add_u64 v[66:67], v[92:93], 0, v[78:79]
	global_load_dword v100, v[64:65], off
	global_load_dword v101, v[64:65], off offset:128
	global_load_dword v99, v[64:65], off offset:256
	global_load_dword v98, v[64:65], off offset:384
	global_load_dword v96, v[66:67], off
	global_load_dword v97, v[66:67], off offset:128
	global_load_dword v95, v[66:67], off offset:256
	global_load_dword v94, v[66:67], off offset:384
	v_or_b32_e32 v64, 18, v102
	v_or_b32_e32 v66, 19, v102
	v_ashrrev_i32_e32 v65, 31, v64
	v_ashrrev_i32_e32 v67, 31, v66
	v_lshlrev_b64 v[76:77], 11, v[64:65]
	v_lshlrev_b64 v[72:73], 11, v[66:67]
	v_lshl_add_u64 v[64:65], v[92:93], 0, v[76:77]
	v_lshl_add_u64 v[66:67], v[92:93], 0, v[72:73]
	v_lshl_add_u32 v169, v69, 2, s0
	global_load_dword v88, v[64:65], off
	global_load_dword v89, v[64:65], off offset:128
	global_load_dword v85, v[64:65], off offset:256
	global_load_dword v84, v[64:65], off offset:384
	global_load_dword v82, v[66:67], off
	global_load_dword v83, v[66:67], off offset:128
	global_load_dword v81, v[66:67], off offset:256
	global_load_dword v80, v[66:67], off offset:384
	ds_read_b128 v[64:67], v169
	v_or_b32_e32 v68, 24, v102
	v_ashrrev_i32_e32 v69, 31, v68
	v_lshlrev_b64 v[74:75], 11, v[68:69]
	ds_read_b128 v[68:71], v169 offset:32
	s_waitcnt lgkmcnt(0)
	v_rcp_f32_e32 v64, v64
	v_mov_b32_e32 v162, v0
	v_mov_b32_e32 v163, v48
	v_rcp_f32_e32 v0, v65
	v_pk_mul_f32 v[162:163], v[162:163], v[64:65] op_sel_hi:[1,0]
	v_mov_b32_e32 v48, v1
	v_lshlrev_b32_e32 v166, 2, v114
	v_pk_mul_f32 v[48:49], v[48:49], v[0:1] op_sel_hi:[1,0]
	v_xor_b32_e32 v164, 4, v166
	v_xor_b32_e32 v165, 8, v166
	v_xor_b32_e32 v168, 16, v166
	v_xor_b32_e32 v167, 32, v166
	v_or_b32_e32 v116, 25, v102
	v_ashrrev_i32_e32 v117, 31, v116
	v_xor_b32_e32 v166, 64, v166
	v_lshl_add_u64 v[112:113], v[92:93], 0, v[74:75]
	s_add_u32 s1, s60, s58
	s_mov_b32 s0, 0x358637bd
	s_addc_u32 s3, s61, s59
	s_lshl_b32 s2, s87, 1
	s_add_u32 s2, s1, s2
	s_addc_u32 s3, s3, 0
	s_waitcnt vmcnt(0)
	v_pk_fma_f32 v[172:173], v[128:129], v[162:163], v[110:111] neg_lo:[1,0,0] neg_hi:[1,0,0]
	v_mov_b32_e32 v162, v32
	v_mov_b32_e32 v163, v16
	v_pk_mul_f32 v[162:163], v[162:163], v[64:65] op_sel_hi:[1,0]
	v_mov_b32_e32 v16, v33
	v_pk_fma_f32 v[174:175], v[128:129], v[162:163], v[108:109] neg_lo:[1,0,0] neg_hi:[1,0,0]
	global_load_dword v163, v130, s[50:51]
	global_load_dword v162, v130, s[50:51] offset:128
	global_load_dword v161, v130, s[50:51] offset:256
	s_nop 0
	global_load_dword v130, v130, s[50:51] offset:384
	v_pk_fma_f32 v[176:177], v[128:129], v[48:49], v[106:107] neg_lo:[1,0,0] neg_hi:[1,0,0]
	v_pk_mul_f32 v[0:1], v[16:17], v[0:1] op_sel_hi:[1,0]
	v_pk_mul_f32 v[110:111], v[172:173], v[172:173]
	v_pk_mul_f32 v[48:49], v[176:177], v[176:177]
	v_pk_fma_f32 v[0:1], v[128:129], v[0:1], v[104:105] neg_lo:[1,0,0] neg_hi:[1,0,0]
	v_pk_mul_f32 v[108:109], v[174:175], v[174:175]
	v_pk_mul_f32 v[16:17], v[0:1], v[0:1]
	v_mov_b32_e32 v32, v48
	v_mov_b32_e32 v33, v110
	v_mov_b32_e32 v110, v49
	v_pk_add_f32 v[32:33], v[32:33], v[110:111]
	v_mov_b32_e32 v48, v17
	v_mov_b32_e32 v49, v109
	v_pk_add_f32 v[32:33], v[48:49], v[32:33]
	v_mov_b32_e32 v17, v108
	v_pk_add_f32 v[16:17], v[16:17], v[32:33]
	ds_bpermute_b32 v33, v164, v17
	ds_bpermute_b32 v32, v164, v16
	v_lshlrev_b64 v[64:65], 11, v[116:117]
	v_lshl_add_u64 v[48:49], v[92:93], 0, v[64:65]
	global_load_dword v116, v[112:113], off
	global_load_dword v117, v[112:113], off offset:128
	global_load_dword v115, v[112:113], off offset:256
	global_load_dword v114, v[112:113], off offset:384
	s_nop 0
	global_load_dword v112, v[48:49], off
	global_load_dword v113, v[48:49], off offset:128
	global_load_dword v111, v[48:49], off offset:256
	global_load_dword v110, v[48:49], off offset:384
	v_or_b32_e32 v48, 26, v102
	s_waitcnt lgkmcnt(0)
	v_pk_add_f32 v[16:17], v[16:17], v[32:33]
	ds_bpermute_b32 v33, v165, v17
	ds_bpermute_b32 v32, v165, v16
	v_or_b32_e32 v102, 27, v102
	v_ashrrev_i32_e32 v49, 31, v48
	v_ashrrev_i32_e32 v103, 31, v102
	v_lshlrev_b64 v[48:49], 11, v[48:49]
	s_waitcnt lgkmcnt(0)
	v_pk_add_f32 v[16:17], v[16:17], v[32:33]
	ds_bpermute_b32 v33, v168, v17
	ds_bpermute_b32 v32, v168, v16
	v_lshl_add_u64 v[104:105], v[92:93], 0, v[48:49]
	v_lshlrev_b32_e32 v170, 1, v170
	v_mov_b32_e32 v171, v131
	v_rcp_f32_e32 v66, v66
	s_waitcnt lgkmcnt(0)
	v_pk_add_f32 v[32:33], v[16:17], v[32:33]
	ds_bpermute_b32 v107, v167, v33
	ds_bpermute_b32 v106, v167, v32
	v_lshlrev_b64 v[16:17], 11, v[102:103]
	v_lshl_add_u64 v[92:93], v[92:93], 0, v[16:17]
	s_waitcnt lgkmcnt(0)
	v_pk_add_f32 v[32:33], v[32:33], v[106:107]
	ds_bpermute_b32 v179, v166, v33
	ds_bpermute_b32 v178, v166, v32
	global_load_dword v108, v[104:105], off
	global_load_dword v109, v[104:105], off offset:128
	global_load_dword v107, v[104:105], off offset:256
	global_load_dword v106, v[104:105], off offset:384
	s_nop 0
	global_load_dword v104, v[92:93], off
	global_load_dword v105, v[92:93], off offset:128
	global_load_dword v103, v[92:93], off offset:256
	global_load_dword v102, v[92:93], off offset:384
	v_mov_b64_e32 v[92:93], s[0:1]
	s_waitcnt lgkmcnt(0)
; DI unsigned short f2bf(float x) { unsigned u = __float_as_uint(x); u += 0x7fffu + ((u >> 16) & 1u); return (unsigned short)(u >> 16); }
; DI float shx(float v, int mask, int lane) { return __int_as_float(__builtin_amdgcn_ds_bpermute((lane ^ mask) << 2, __float_as_int(v))); }
; template <int DQK, int MODE, int LDQ, int LDK, int LDV> ...
;     ...
;         } else {
;             float v[4]; float ss = 0.f;
; #pragma unroll
;             for (int d0 = 0; d0 < 4; ++d0) { v[d0] = s0v[r][d0] - lam * (o[d0][r] * rl); ss += v[d0] * v[d0]; }
; #pragma unroll
;             for (int mk = 1; mk <= 16; mk <<= 1) ss += shx(ss, mk, lane2);
;             const float rs = rsqrtf(ss * (1.f / 128.f) + EPS) * 0.8f;
; #pragma unroll
;             for (int d0 = 0; d0 < 4; ++d0) AOb[(size_t)orow * 1024 + d0 * 32 + r32] = f2bf(v[d0] * rs * gout[d0 * 32 + r32]);
	v_pk_add_f32 v[32:33], v[32:33], v[178:179]
	s_nop 0
	v_pk_fma_f32 v[178:179], v[32:33], s[24:25], v[92:93] op_sel_hi:[1,0,0]
	s_nop 0
	v_mul_f32_e32 v32, 0x4b800000, v179
	v_cmp_gt_f32_e32 vcc, s67, v179
	s_nop 1
	v_cndmask_b32_e32 v32, v179, v32, vcc
	v_rsq_f32_e32 v179, v32
	v_lshl_add_u64 v[32:33], s[2:3], 0, v[170:171]
	v_lshl_add_u64 v[156:157], v[32:33], 0, v[156:157]
	v_lshl_add_u64 v[148:149], v[32:33], 0, v[148:149]
	v_mul_f32_e32 v170, 0x45800000, v179
	v_cndmask_b32_e32 v170, v179, v170, vcc
	v_mul_f32_e32 v170, 0x3f4ccccd, v170
	v_mul_f32_e32 v171, v172, v170
	v_cmp_gt_f32_e32 vcc, s67, v178
	s_mov_b64 s[2:3], 0
	s_waitcnt vmcnt(19)
	v_mul_f32_e32 v171, v163, v171
	v_bfe_u32 v172, v171, 16, 1
	v_add3_u32 v171, v171, v172, s68
	global_store_short_d16_hi v[156:157], v171, off offset:1024
	v_mul_f32_e32 v171, v173, v170
	s_waitcnt vmcnt(19)
	v_mul_f32_e32 v171, v162, v171
	v_bfe_u32 v172, v171, 16, 1
	v_add3_u32 v171, v171, v172, s68
	global_store_short_d16_hi v[156:157], v171, off offset:1088
	v_mul_f32_e32 v171, v175, v170
	s_waitcnt vmcnt(19)
	v_mul_f32_e32 v171, v161, v171
	v_bfe_u32 v172, v171, 16, 1
	v_add3_u32 v171, v171, v172, s68
	global_store_short_d16_hi v[156:157], v171, off offset:1152
	v_mul_f32_e32 v171, 0x4b800000, v178
	v_cndmask_b32_e32 v171, v178, v171, vcc
	v_mul_f32_e32 v170, v174, v170
	v_rsq_f32_e32 v171, v171
	s_waitcnt vmcnt(19)
	v_mul_f32_e32 v170, v130, v170
	v_bfe_u32 v172, v170, 16, 1
	v_add3_u32 v170, v170, v172, s68
	global_store_short_d16_hi v[156:157], v170, off offset:1216
	v_mul_f32_e32 v156, 0x45800000, v171
	v_cndmask_b32_e32 v172, v171, v156, vcc
	v_mov_b32_e32 v156, v2
	v_rcp_f32_e32 v2, v67
	v_mov_b32_e32 v157, v50
	v_mov_b32_e32 v50, v3
	v_pk_mul_f32 v[156:157], v[156:157], v[66:67] op_sel_hi:[1,0]
	v_mov_b32_e32 v170, v34
	v_mov_b32_e32 v171, v18
	v_pk_mul_f32 v[50:51], v[50:51], v[2:3] op_sel_hi:[1,0]
	v_mov_b32_e32 v18, v35
	v_pk_fma_f32 v[156:157], v[128:129], v[156:157], v[158:159] neg_lo:[1,0,0] neg_hi:[1,0,0]
	v_pk_mul_f32 v[170:171], v[170:171], v[66:67] op_sel_hi:[1,0]
	v_pk_fma_f32 v[50:51], v[128:129], v[50:51], v[152:153] neg_lo:[1,0,0] neg_hi:[1,0,0]
	v_pk_mul_f32 v[2:3], v[18:19], v[2:3] op_sel_hi:[1,0]
	v_pk_mul_f32 v[158:159], v[156:157], v[156:157]
	v_pk_fma_f32 v[66:67], v[128:129], v[170:171], v[154:155] neg_lo:[1,0,0] neg_hi:[1,0,0]
	v_pk_mul_f32 v[152:153], v[50:51], v[50:51]
	v_pk_fma_f32 v[2:3], v[128:129], v[2:3], v[150:151] neg_lo:[1,0,0] neg_hi:[1,0,0]
	v_pk_mul_f32 v[154:155], v[66:67], v[66:67]
	v_pk_mul_f32 v[18:19], v[2:3], v[2:3]
	v_mov_b32_e32 v34, v152
	v_mov_b32_e32 v35, v158
	v_mov_b32_e32 v158, v153
	v_pk_add_f32 v[34:35], v[34:35], v[158:159]
	v_mov_b32_e32 v150, v19
	v_mov_b32_e32 v151, v155
	v_pk_add_f32 v[34:35], v[150:151], v[34:35]
	v_mov_b32_e32 v19, v154
	v_pk_add_f32 v[18:19], v[18:19], v[34:35]
	ds_bpermute_b32 v35, v164, v19
	ds_bpermute_b32 v34, v164, v18
	v_mul_f32_e32 v150, 0x3f4ccccd, v172
	v_mul_f32_e32 v151, v176, v150
	v_mul_f32_e32 v151, v163, v151
	v_bfe_u32 v152, v151, 16, 1
	s_waitcnt lgkmcnt(0)
	v_pk_add_f32 v[18:19], v[18:19], v[34:35]
	ds_bpermute_b32 v35, v165, v19
	ds_bpermute_b32 v34, v165, v18
	v_add3_u32 v151, v151, v152, s68
	global_store_short_d16_hi v[148:149], v151, off offset:1024
	v_mul_f32_e32 v151, v177, v150
	v_mul_f32_e32 v151, v162, v151
	s_waitcnt lgkmcnt(0)
	v_pk_add_f32 v[18:19], v[18:19], v[34:35]
	ds_bpermute_b32 v35, v168, v19
	ds_bpermute_b32 v34, v168, v18
	v_bfe_u32 v152, v151, 16, 1
	v_mul_f32_e32 v1, v1, v150
	v_add3_u32 v151, v151, v152, s68
	v_mul_f32_e32 v1, v161, v1
	s_waitcnt lgkmcnt(0)
	v_pk_add_f32 v[18:19], v[18:19], v[34:35]
	ds_bpermute_b32 v35, v167, v19
	ds_bpermute_b32 v34, v167, v18
	global_store_short_d16_hi v[148:149], v151, off offset:1088
	v_bfe_u32 v151, v1, 16, 1
	v_add3_u32 v1, v1, v151, s68
	v_mul_f32_e32 v0, v0, v150
	s_waitcnt lgkmcnt(0)
	v_pk_add_f32 v[18:19], v[18:19], v[34:35]
	ds_bpermute_b32 v35, v166, v19
	ds_bpermute_b32 v34, v166, v18
	global_store_short_d16_hi v[148:149], v1, off offset:1152
	v_mul_f32_e32 v150, v130, v0
	v_bfe_u32 v151, v150, 16, 1
	s_waitcnt lgkmcnt(0)
	v_pk_add_f32 v[0:1], v[18:19], v[34:35]
	s_nop 0
	v_pk_fma_f32 v[0:1], v[0:1], s[24:25], v[92:93] op_sel_hi:[1,0,0]
	s_nop 0
	v_mul_f32_e32 v18, 0x4b800000, v1
	v_cmp_gt_f32_e32 vcc, s67, v1
	s_nop 1
	v_cndmask_b32_e32 v1, v1, v18, vcc
	v_rsq_f32_e32 v1, v1
	v_add3_u32 v18, v150, v151, s68
	global_store_short_d16_hi v[148:149], v18, off offset:1216
	v_lshl_add_u64 v[18:19], v[32:33], 0, v[146:147]
	v_mul_f32_e32 v34, 0x45800000, v1
	v_cndmask_b32_e32 v1, v1, v34, vcc
	v_mul_f32_e32 v1, 0x3f4ccccd, v1
	v_mul_f32_e32 v34, v156, v1
	v_mul_f32_e32 v34, v163, v34
	v_bfe_u32 v35, v34, 16, 1
	v_add3_u32 v34, v34, v35, s68
	global_store_short_d16_hi v[18:19], v34, off offset:1024
	v_mul_f32_e32 v34, v157, v1
	v_mul_f32_e32 v34, v162, v34
	v_bfe_u32 v35, v34, 16, 1
	v_add3_u32 v34, v34, v35, s68
	global_store_short_d16_hi v[18:19], v34, off offset:1088
	v_mul_f32_e32 v34, v67, v1
	v_mul_f32_e32 v34, v161, v34
	v_bfe_u32 v35, v34, 16, 1
	v_add3_u32 v34, v34, v35, s68
	global_store_short_d16_hi v[18:19], v34, off offset:1152
	v_mul_f32_e32 v1, v66, v1
	v_mul_f32_e32 v34, 0x4b800000, v0
	v_cmp_gt_f32_e32 vcc, s67, v0
	v_mul_f32_e32 v1, v130, v1
	v_mov_b32_e32 v66, v36
	v_cndmask_b32_e32 v0, v0, v34, vcc
	v_rsq_f32_e32 v34, v0
	v_bfe_u32 v0, v1, 16, 1
	v_add3_u32 v0, v1, v0, s68
	global_store_short_d16_hi v[18:19], v0, off offset:1216
	v_rcp_f32_e32 v0, v68
	v_mov_b32_e32 v18, v4
	v_rcp_f32_e32 v4, v69
	v_mul_f32_e32 v1, 0x45800000, v34
	v_mov_b32_e32 v19, v52
	v_mov_b32_e32 v52, v5
	v_pk_mul_f32 v[18:19], v[18:19], v[0:1] op_sel_hi:[1,0]
	v_mov_b32_e32 v67, v20
	v_pk_mul_f32 v[52:53], v[52:53], v[4:5] op_sel_hi:[1,0]
	v_mov_b32_e32 v20, v37
	v_cndmask_b32_e32 v146, v34, v1, vcc
	v_pk_fma_f32 v[18:19], v[128:129], v[18:19], v[144:145] neg_lo:[1,0,0] neg_hi:[1,0,0]
	v_pk_mul_f32 v[0:1], v[66:67], v[0:1] op_sel_hi:[1,0]
	v_pk_fma_f32 v[52:53], v[128:129], v[52:53], v[140:141] neg_lo:[1,0,0] neg_hi:[1,0,0]
	v_pk_mul_f32 v[4:5], v[20:21], v[4:5] op_sel_hi:[1,0]
	v_pk_mul_f32 v[34:35], v[18:19], v[18:19]
	v_pk_fma_f32 v[0:1], v[128:129], v[0:1], v[142:143] neg_lo:[1,0,0] neg_hi:[1,0,0]
	v_pk_mul_f32 v[68:69], v[52:53], v[52:53]
	v_pk_fma_f32 v[4:5], v[128:129], v[4:5], v[138:139] neg_lo:[1,0,0] neg_hi:[1,0,0]
	v_pk_mul_f32 v[66:67], v[0:1], v[0:1]
	v_pk_mul_f32 v[20:21], v[4:5], v[4:5]
	v_mov_b32_e32 v36, v68
	v_mov_b32_e32 v37, v34
	v_mov_b32_e32 v34, v69
	v_pk_add_f32 v[34:35], v[36:37], v[34:35]
	v_mov_b32_e32 v36, v21
	v_mov_b32_e32 v37, v67
	v_pk_add_f32 v[34:35], v[36:37], v[34:35]
	v_mov_b32_e32 v21, v66
	v_pk_add_f32 v[20:21], v[20:21], v[34:35]
	ds_bpermute_b32 v35, v164, v21
	ds_bpermute_b32 v34, v164, v20
	v_mul_f32_e32 v66, 0x3f4ccccd, v146
	v_mul_f32_e32 v50, v50, v66
	v_mul_f32_e32 v50, v163, v50
	v_bfe_u32 v67, v50, 16, 1
	s_waitcnt lgkmcnt(0)
; DI unsigned short f2bf(float x) { unsigned u = __float_as_uint(x); u += 0x7fffu + ((u >> 16) & 1u); return (unsigned short)(u >> 16); }
; DI float shx(float v, int mask, int lane) { return __int_as_float(__builtin_amdgcn_ds_bpermute((lane ^ mask) << 2, __float_as_int(v))); }
; template <int DQK, int MODE, int LDQ, int LDK, int LDV> ...
;     ...
;         } else {
;             float v[4]; float ss = 0.f;
; #pragma unroll
;             for (int d0 = 0; d0 < 4; ++d0) { v[d0] = s0v[r][d0] - lam * (o[d0][r] * rl); ss += v[d0] * v[d0]; }
; #pragma unroll
;             for (int mk = 1; mk <= 16; mk <<= 1) ss += shx(ss, mk, lane2);
;             const float rs = rsqrtf(ss * (1.f / 128.f) + EPS) * 0.8f;
; #pragma unroll
;             for (int d0 = 0; d0 < 4; ++d0) AOb[(size_t)orow * 1024 + d0 * 32 + r32] = f2bf(v[d0] * rs * gout[d0 * 32 + r32]);
	v_pk_add_f32 v[20:21], v[20:21], v[34:35]
	ds_bpermute_b32 v35, v165, v21
	ds_bpermute_b32 v34, v165, v20
	v_lshl_add_u64 v[36:37], v[32:33], 0, v[136:137]
	v_add3_u32 v50, v50, v67, s68
	global_store_short_d16_hi v[36:37], v50, off offset:1024
	v_mul_f32_e32 v50, v51, v66
	s_waitcnt lgkmcnt(0)
	v_pk_add_f32 v[20:21], v[20:21], v[34:35]
	ds_bpermute_b32 v35, v168, v21
	ds_bpermute_b32 v34, v168, v20
	v_mul_f32_e32 v50, v162, v50
	v_bfe_u32 v51, v50, 16, 1
	v_mul_f32_e32 v3, v3, v66
	v_add3_u32 v50, v50, v51, s68
	s_waitcnt lgkmcnt(0)
	v_pk_add_f32 v[20:21], v[20:21], v[34:35]
	ds_bpermute_b32 v35, v167, v21
	ds_bpermute_b32 v34, v167, v20
	v_mul_f32_e32 v3, v161, v3
	global_store_short_d16_hi v[36:37], v50, off offset:1088
	v_bfe_u32 v50, v3, 16, 1
	v_add3_u32 v3, v3, v50, s68
	s_waitcnt lgkmcnt(0)
	v_pk_add_f32 v[20:21], v[20:21], v[34:35]
	ds_bpermute_b32 v35, v166, v21
	ds_bpermute_b32 v34, v166, v20
	v_mul_f32_e32 v2, v2, v66
	global_store_short_d16_hi v[36:37], v3, off offset:1152
	v_mul_f32_e32 v50, v130, v2
	v_bfe_u32 v51, v50, 16, 1
	s_waitcnt lgkmcnt(0)
	v_pk_add_f32 v[2:3], v[20:21], v[34:35]
	s_nop 0
	v_pk_fma_f32 v[2:3], v[2:3], s[24:25], v[92:93] op_sel_hi:[1,0,0]
	s_nop 0
	v_mul_f32_e32 v20, 0x4b800000, v3
	v_cmp_gt_f32_e32 vcc, s67, v3
	s_nop 1
	v_cndmask_b32_e32 v3, v3, v20, vcc
	v_rsq_f32_e32 v3, v3
	v_add3_u32 v20, v50, v51, s68
	global_store_short_d16_hi v[36:37], v20, off offset:1216
	v_lshl_add_u64 v[20:21], v[32:33], 0, v[134:135]
	v_mul_f32_e32 v34, 0x45800000, v3
	v_cndmask_b32_e32 v3, v3, v34, vcc
	v_mul_f32_e32 v3, 0x3f4ccccd, v3
	v_mul_f32_e32 v18, v18, v3
	v_mul_f32_e32 v18, v163, v18
	v_bfe_u32 v34, v18, 16, 1
	v_add3_u32 v18, v18, v34, s68
	global_store_short_d16_hi v[20:21], v18, off offset:1024
	v_mul_f32_e32 v18, v19, v3
	v_mul_f32_e32 v18, v162, v18
	v_bfe_u32 v19, v18, 16, 1
	v_mul_f32_e32 v1, v1, v3
	v_add3_u32 v18, v18, v19, s68
	v_mul_f32_e32 v1, v161, v1
	global_store_short_d16_hi v[20:21], v18, off offset:1088
	v_bfe_u32 v18, v1, 16, 1
	v_add3_u32 v1, v1, v18, s68
	global_store_short_d16_hi v[20:21], v1, off offset:1152
	v_mul_f32_e32 v1, 0x4b800000, v2
	v_cmp_gt_f32_e32 vcc, s67, v2
	v_mul_f32_e32 v0, v0, v3
	v_mul_f32_e32 v0, v130, v0
	v_cndmask_b32_e32 v1, v2, v1, vcc
	v_rsq_f32_e32 v1, v1
	v_bfe_u32 v2, v0, 16, 1
	v_add3_u32 v0, v0, v2, s68
	global_store_short_d16_hi v[20:21], v0, off offset:1216
	v_mul_f32_e32 v2, 0x45800000, v1
	v_rcp_f32_e32 v0, v70
	v_cndmask_b32_e32 v66, v1, v2, vcc
	v_mov_b32_e32 v2, v6
	v_rcp_f32_e32 v6, v71
	v_mov_b32_e32 v3, v54
	v_mov_b32_e32 v18, v38
	v_mov_b32_e32 v19, v22
	v_mov_b32_e32 v54, v7
	v_pk_mul_f32 v[2:3], v[2:3], v[0:1] op_sel_hi:[1,0]
	v_pk_mul_f32 v[0:1], v[18:19], v[0:1] op_sel_hi:[1,0]
	v_pk_mul_f32 v[18:19], v[54:55], v[6:7] op_sel_hi:[1,0]
	v_mov_b32_e32 v22, v39
	v_pk_fma_f32 v[2:3], v[128:129], v[2:3], v[132:133] neg_lo:[1,0,0] neg_hi:[1,0,0]
	v_pk_fma_f32 v[20:21], v[128:129], v[18:19], v[124:125] neg_lo:[1,0,0] neg_hi:[1,0,0]
	v_pk_mul_f32 v[6:7], v[22:23], v[6:7] op_sel_hi:[1,0]
	v_pk_mul_f32 v[34:35], v[2:3], v[2:3]
	v_pk_fma_f32 v[0:1], v[128:129], v[0:1], v[126:127] neg_lo:[1,0,0] neg_hi:[1,0,0]
	v_pk_mul_f32 v[50:51], v[20:21], v[20:21]
	v_pk_fma_f32 v[18:19], v[128:129], v[6:7], v[122:123] neg_lo:[1,0,0] neg_hi:[1,0,0]
	v_pk_mul_f32 v[36:37], v[0:1], v[0:1]
	v_pk_mul_f32 v[6:7], v[18:19], v[18:19]
	v_mov_b32_e32 v22, v50
	v_mov_b32_e32 v23, v34
	v_mov_b32_e32 v34, v51
	v_pk_add_f32 v[22:23], v[22:23], v[34:35]
	v_mov_b32_e32 v34, v7
	v_mov_b32_e32 v35, v37
	v_pk_add_f32 v[22:23], v[34:35], v[22:23]
	v_mov_b32_e32 v7, v36
	v_pk_add_f32 v[6:7], v[6:7], v[22:23]
	ds_bpermute_b32 v23, v164, v7
	ds_bpermute_b32 v22, v164, v6
	v_mul_f32_e32 v36, 0x3f4ccccd, v66
	v_mul_f32_e32 v37, v52, v36
	v_mul_f32_e32 v37, v163, v37
	v_bfe_u32 v38, v37, 16, 1
	s_waitcnt lgkmcnt(0)
	v_pk_add_f32 v[6:7], v[6:7], v[22:23]
	ds_bpermute_b32 v23, v165, v7
	ds_bpermute_b32 v22, v165, v6
	v_lshl_add_u64 v[34:35], v[32:33], 0, v[120:121]
	v_add3_u32 v37, v37, v38, s68
	global_store_short_d16_hi v[34:35], v37, off offset:1024
	v_mul_f32_e32 v37, v53, v36
	s_waitcnt lgkmcnt(0)
	v_pk_add_f32 v[6:7], v[6:7], v[22:23]
	ds_bpermute_b32 v23, v168, v7
	ds_bpermute_b32 v22, v168, v6
	v_mul_f32_e32 v37, v162, v37
	v_bfe_u32 v38, v37, 16, 1
	v_mul_f32_e32 v5, v5, v36
	v_add3_u32 v37, v37, v38, s68
	s_waitcnt lgkmcnt(0)
	v_pk_add_f32 v[6:7], v[6:7], v[22:23]
	ds_bpermute_b32 v23, v167, v7
	ds_bpermute_b32 v22, v167, v6
	v_mul_f32_e32 v5, v161, v5
	global_store_short_d16_hi v[34:35], v37, off offset:1088
	v_bfe_u32 v37, v5, 16, 1
	v_add3_u32 v5, v5, v37, s68
	s_waitcnt lgkmcnt(0)
	v_pk_add_f32 v[6:7], v[6:7], v[22:23]
	ds_bpermute_b32 v23, v166, v7
	ds_bpermute_b32 v22, v166, v6
	v_mul_f32_e32 v4, v4, v36
	global_store_short_d16_hi v[34:35], v5, off offset:1152
	v_mul_f32_e32 v36, v130, v4
	v_bfe_u32 v37, v36, 16, 1
	s_waitcnt lgkmcnt(0)
	v_pk_add_f32 v[4:5], v[6:7], v[22:23]
	v_lshl_add_u64 v[22:23], v[32:33], 0, v[118:119]
	v_pk_fma_f32 v[4:5], v[4:5], s[24:25], v[92:93] op_sel_hi:[1,0,0]
	s_nop 0
	v_mul_f32_e32 v6, 0x4b800000, v5
	v_cmp_gt_f32_e32 vcc, s67, v5
	s_nop 1
	v_cndmask_b32_e32 v5, v5, v6, vcc
	v_rsq_f32_e32 v5, v5
	v_add3_u32 v6, v36, v37, s68
	global_store_short_d16_hi v[34:35], v6, off offset:1216
	v_mov_b32_e32 v36, v40
	v_mul_f32_e32 v6, 0x45800000, v5
	v_cndmask_b32_e32 v5, v5, v6, vcc
	v_mul_f32_e32 v5, 0x3f4ccccd, v5
	v_mul_f32_e32 v2, v2, v5
	v_mul_f32_e32 v2, v163, v2
	v_bfe_u32 v6, v2, 16, 1
	v_add3_u32 v2, v2, v6, s68
	global_store_short_d16_hi v[22:23], v2, off offset:1024
	v_mul_f32_e32 v2, v3, v5
	v_mul_f32_e32 v2, v162, v2
	v_bfe_u32 v3, v2, 16, 1
	v_mul_f32_e32 v1, v1, v5
	v_add3_u32 v2, v2, v3, s68
	v_mul_f32_e32 v1, v161, v1
	global_store_short_d16_hi v[22:23], v2, off offset:1088
	v_bfe_u32 v2, v1, 16, 1
	v_add3_u32 v1, v1, v2, s68
	v_mul_f32_e32 v2, 0x4b800000, v4
	v_cmp_gt_f32_e32 vcc, s67, v4
	v_mul_f32_e32 v0, v0, v5
	v_mul_f32_e32 v0, v130, v0
	v_cndmask_b32_e32 v2, v4, v2, vcc
	ds_read_b128 v[4:7], v169 offset:64
	global_store_short_d16_hi v[22:23], v1, off offset:1152
	v_bfe_u32 v1, v0, 16, 1
	v_rsq_f32_e32 v34, v2
	v_add3_u32 v0, v0, v1, s68
	global_store_short_d16_hi v[22:23], v0, off offset:1216
	ds_read_b128 v[0:3], v169 offset:96
	s_waitcnt lgkmcnt(1)
; DI unsigned short f2bf(float x) { unsigned u = __float_as_uint(x); u += 0x7fffu + ((u >> 16) & 1u); return (unsigned short)(u >> 16); }
; DI float shx(float v, int mask, int lane) { return __int_as_float(__builtin_amdgcn_ds_bpermute((lane ^ mask) << 2, __float_as_int(v))); }
; template <int DQK, int MODE, int LDQ, int LDK, int LDV> ...
;     ...
;         } else {
;             float v[4]; float ss = 0.f;
; #pragma unroll
;             for (int d0 = 0; d0 < 4; ++d0) { v[d0] = s0v[r][d0] - lam * (o[d0][r] * rl); ss += v[d0] * v[d0]; }
; #pragma unroll
;             for (int mk = 1; mk <= 16; mk <<= 1) ss += shx(ss, mk, lane2);
;             const float rs = rsqrtf(ss * (1.f / 128.f) + EPS) * 0.8f;
; #pragma unroll
;             for (int d0 = 0; d0 < 4; ++d0) AOb[(size_t)orow * 1024 + d0 * 32 + r32] = f2bf(v[d0] * rs * gout[d0 * 32 + r32]);
	v_rcp_f32_e32 v4, v4
	v_mul_f32_e32 v22, 0x45800000, v34
	v_cndmask_b32_e32 v52, v34, v22, vcc
	v_mov_b32_e32 v22, v8
	v_mov_b32_e32 v23, v56
	v_mov_b32_e32 v37, v24
	v_pk_mul_f32 v[22:23], v[22:23], v[4:5] op_sel_hi:[1,0]
	v_pk_mul_f32 v[36:37], v[36:37], v[4:5] op_sel_hi:[1,0]
	v_rcp_f32_e32 v4, v5
	v_mov_b32_e32 v56, v9
	v_mov_b32_e32 v24, v41
	v_pk_fma_f32 v[22:23], v[128:129], v[22:23], v[100:101] neg_lo:[1,0,0] neg_hi:[1,0,0]
	v_pk_mul_f32 v[8:9], v[56:57], v[4:5] op_sel_hi:[1,0]
	v_pk_mul_f32 v[4:5], v[24:25], v[4:5] op_sel_hi:[1,0]
	v_pk_fma_f32 v[8:9], v[128:129], v[8:9], v[96:97] neg_lo:[1,0,0] neg_hi:[1,0,0]
	v_pk_mul_f32 v[34:35], v[22:23], v[22:23]
	v_pk_fma_f32 v[36:37], v[128:129], v[36:37], v[98:99] neg_lo:[1,0,0] neg_hi:[1,0,0]
	v_pk_mul_f32 v[50:51], v[8:9], v[8:9]
	v_pk_fma_f32 v[4:5], v[128:129], v[4:5], v[94:95] neg_lo:[1,0,0] neg_hi:[1,0,0]
	v_pk_mul_f32 v[38:39], v[36:37], v[36:37]
	v_pk_mul_f32 v[24:25], v[4:5], v[4:5]
	v_mov_b32_e32 v40, v50
	v_mov_b32_e32 v41, v34
	v_mov_b32_e32 v34, v51
	v_pk_add_f32 v[34:35], v[40:41], v[34:35]
	v_mov_b32_e32 v40, v25
	v_mov_b32_e32 v41, v39
	v_pk_add_f32 v[34:35], v[40:41], v[34:35]
	v_mov_b32_e32 v25, v38
	v_pk_add_f32 v[24:25], v[24:25], v[34:35]
	ds_bpermute_b32 v35, v164, v25
	ds_bpermute_b32 v34, v164, v24
	v_mul_f32_e32 v40, 0x3f4ccccd, v52
	v_mul_f32_e32 v20, v20, v40
	v_mul_f32_e32 v20, v163, v20
	v_bfe_u32 v41, v20, 16, 1
	s_waitcnt lgkmcnt(0)
	v_pk_add_f32 v[24:25], v[24:25], v[34:35]
	ds_bpermute_b32 v35, v165, v25
	ds_bpermute_b32 v34, v165, v24
	v_lshl_add_u64 v[38:39], v[32:33], 0, v[90:91]
	v_add3_u32 v20, v20, v41, s68
	global_store_short_d16_hi v[38:39], v20, off offset:1024
	v_mul_f32_e32 v41, v21, v40
	s_waitcnt lgkmcnt(0)
	v_pk_add_f32 v[20:21], v[24:25], v[34:35]
	ds_bpermute_b32 v25, v168, v21
	ds_bpermute_b32 v24, v168, v20
	v_mul_f32_e32 v34, v162, v41
	v_bfe_u32 v35, v34, 16, 1
	v_mul_f32_e32 v19, v19, v40
	v_add3_u32 v34, v34, v35, s68
	s_waitcnt lgkmcnt(0)
	v_pk_add_f32 v[20:21], v[20:21], v[24:25]
	ds_bpermute_b32 v25, v167, v21
	ds_bpermute_b32 v24, v167, v20
	v_mul_f32_e32 v19, v161, v19
	global_store_short_d16_hi v[38:39], v34, off offset:1088
	v_bfe_u32 v34, v19, 16, 1
	v_add3_u32 v19, v19, v34, s68
	s_waitcnt lgkmcnt(0)
	v_pk_add_f32 v[20:21], v[20:21], v[24:25]
	ds_bpermute_b32 v25, v166, v21
	ds_bpermute_b32 v24, v166, v20
	v_mul_f32_e32 v18, v18, v40
	global_store_short_d16_hi v[38:39], v19, off offset:1152
	v_mul_f32_e32 v34, v130, v18
	v_bfe_u32 v35, v34, 16, 1
	s_waitcnt lgkmcnt(0)
	v_pk_add_f32 v[18:19], v[20:21], v[24:25]
	v_rcp_f32_e32 v6, v6
	v_pk_fma_f32 v[18:19], v[18:19], s[24:25], v[92:93] op_sel_hi:[1,0,0]
	v_rcp_f32_e32 v0, v0
	v_mul_f32_e32 v20, 0x4b800000, v19
	v_cmp_gt_f32_e32 vcc, s67, v19
	v_rcp_f32_e32 v2, v2
	s_nop 0
	v_cndmask_b32_e32 v19, v19, v20, vcc
	v_rsq_f32_e32 v19, v19
	v_add3_u32 v20, v34, v35, s68
	global_store_short_d16_hi v[38:39], v20, off offset:1216
	v_lshl_add_u64 v[20:21], v[32:33], 0, v[86:87]
	v_mul_f32_e32 v24, 0x45800000, v19
	v_cndmask_b32_e32 v19, v19, v24, vcc
	v_mul_f32_e32 v19, 0x3f4ccccd, v19
	v_mul_f32_e32 v22, v22, v19
	v_mul_f32_e32 v22, v163, v22
	v_bfe_u32 v24, v22, 16, 1
	v_add3_u32 v22, v22, v24, s68
	global_store_short_d16_hi v[20:21], v22, off offset:1024
	v_mul_f32_e32 v22, v23, v19
	v_mul_f32_e32 v22, v162, v22
	v_bfe_u32 v23, v22, 16, 1
	v_add3_u32 v22, v22, v23, s68
	global_store_short_d16_hi v[20:21], v22, off offset:1088
	v_mul_f32_e32 v22, v37, v19
	v_mul_f32_e32 v22, v161, v22
	v_bfe_u32 v23, v22, 16, 1
	v_add3_u32 v22, v22, v23, s68
	global_store_short_d16_hi v[20:21], v22, off offset:1152
	v_mul_f32_e32 v22, 0x4b800000, v18
	v_cmp_gt_f32_e32 vcc, s67, v18
	v_mul_f32_e32 v19, v36, v19
	v_mul_f32_e32 v19, v130, v19
	v_cndmask_b32_e32 v18, v18, v22, vcc
	v_rsq_f32_e32 v18, v18
	v_bfe_u32 v22, v19, 16, 1
	v_add3_u32 v19, v19, v22, s68
	global_store_short_d16_hi v[20:21], v19, off offset:1216
	v_mul_f32_e32 v19, 0x45800000, v18
	v_cndmask_b32_e32 v38, v18, v19, vcc
	v_mov_b32_e32 v18, v10
	v_mov_b32_e32 v19, v58
	v_mov_b32_e32 v22, v42
	v_mov_b32_e32 v23, v26
	v_pk_mul_f32 v[18:19], v[18:19], v[6:7] op_sel_hi:[1,0]
	v_pk_mul_f32 v[22:23], v[22:23], v[6:7] op_sel_hi:[1,0]
	v_rcp_f32_e32 v6, v7
	v_mov_b32_e32 v58, v11
	v_mov_b32_e32 v26, v43
	v_pk_fma_f32 v[18:19], v[128:129], v[18:19], v[88:89] neg_lo:[1,0,0] neg_hi:[1,0,0]
	v_pk_mul_f32 v[10:11], v[58:59], v[6:7] op_sel_hi:[1,0]
	v_pk_mul_f32 v[6:7], v[26:27], v[6:7] op_sel_hi:[1,0]
	v_pk_fma_f32 v[10:11], v[128:129], v[10:11], v[82:83] neg_lo:[1,0,0] neg_hi:[1,0,0]
	v_pk_mul_f32 v[20:21], v[18:19], v[18:19]
	v_pk_fma_f32 v[22:23], v[128:129], v[22:23], v[84:85] neg_lo:[1,0,0] neg_hi:[1,0,0]
	v_pk_mul_f32 v[34:35], v[10:11], v[10:11]
	v_pk_fma_f32 v[6:7], v[128:129], v[6:7], v[80:81] neg_lo:[1,0,0] neg_hi:[1,0,0]
	v_pk_mul_f32 v[24:25], v[22:23], v[22:23]
	v_pk_mul_f32 v[26:27], v[6:7], v[6:7]
	v_mov_b32_e32 v36, v34
	v_mov_b32_e32 v37, v20
	v_mov_b32_e32 v20, v35
	v_pk_add_f32 v[20:21], v[36:37], v[20:21]
	v_mov_b32_e32 v34, v27
	v_mov_b32_e32 v35, v25
	v_pk_add_f32 v[20:21], v[34:35], v[20:21]
	v_mov_b32_e32 v27, v24
	v_pk_add_f32 v[20:21], v[26:27], v[20:21]
	ds_bpermute_b32 v25, v164, v21
	ds_bpermute_b32 v24, v164, v20
	v_mul_f32_e32 v34, 0x3f4ccccd, v38
	v_mul_f32_e32 v8, v8, v34
	v_mul_f32_e32 v8, v163, v8
	v_bfe_u32 v35, v8, 16, 1
	s_waitcnt lgkmcnt(0)
	v_pk_add_f32 v[20:21], v[20:21], v[24:25]
	ds_bpermute_b32 v25, v165, v21
	ds_bpermute_b32 v24, v165, v20
	v_lshl_add_u64 v[26:27], v[32:33], 0, v[78:79]
	v_add3_u32 v8, v8, v35, s68
	global_store_short_d16_hi v[26:27], v8, off offset:1024
	v_mul_f32_e32 v35, v9, v34
	s_waitcnt lgkmcnt(0)
; DI unsigned short f2bf(float x) { unsigned u = __float_as_uint(x); u += 0x7fffu + ((u >> 16) & 1u); return (unsigned short)(u >> 16); }
; DI float shx(float v, int mask, int lane) { return __int_as_float(__builtin_amdgcn_ds_bpermute((lane ^ mask) << 2, __float_as_int(v))); }
; template <int DQK, int MODE, int LDQ, int LDK, int LDV> ...
;     ...
;         } else {
;             float v[4]; float ss = 0.f;
; #pragma unroll
;             for (int d0 = 0; d0 < 4; ++d0) { v[d0] = s0v[r][d0] - lam * (o[d0][r] * rl); ss += v[d0] * v[d0]; }
; #pragma unroll
;             for (int mk = 1; mk <= 16; mk <<= 1) ss += shx(ss, mk, lane2);
;             const float rs = rsqrtf(ss * (1.f / 128.f) + EPS) * 0.8f;
; #pragma unroll
;             for (int d0 = 0; d0 < 4; ++d0) AOb[(size_t)orow * 1024 + d0 * 32 + r32] = f2bf(v[d0] * rs * gout[d0 * 32 + r32]);
	v_pk_add_f32 v[8:9], v[20:21], v[24:25]
	ds_bpermute_b32 v21, v168, v9
	ds_bpermute_b32 v20, v168, v8
	v_mul_f32_e32 v24, v162, v35
	v_bfe_u32 v25, v24, 16, 1
	v_mul_f32_e32 v5, v5, v34
	v_add3_u32 v24, v24, v25, s68
	s_waitcnt lgkmcnt(0)
	v_pk_add_f32 v[8:9], v[8:9], v[20:21]
	ds_bpermute_b32 v21, v167, v9
	ds_bpermute_b32 v20, v167, v8
	v_mul_f32_e32 v5, v161, v5
	global_store_short_d16_hi v[26:27], v24, off offset:1088
	v_bfe_u32 v24, v5, 16, 1
	v_add3_u32 v5, v5, v24, s68
	s_waitcnt lgkmcnt(0)
	v_pk_add_f32 v[8:9], v[8:9], v[20:21]
	ds_bpermute_b32 v21, v166, v9
	ds_bpermute_b32 v20, v166, v8
	v_mul_f32_e32 v4, v4, v34
	global_store_short_d16_hi v[26:27], v5, off offset:1152
	v_mul_f32_e32 v24, v130, v4
	v_bfe_u32 v25, v24, 16, 1
	s_waitcnt lgkmcnt(0)
	v_pk_add_f32 v[4:5], v[8:9], v[20:21]
	s_nop 0
	v_pk_fma_f32 v[4:5], v[4:5], s[24:25], v[92:93] op_sel_hi:[1,0,0]
	s_nop 0
	v_mul_f32_e32 v8, 0x4b800000, v5
	v_cmp_gt_f32_e32 vcc, s67, v5
	s_nop 1
	v_cndmask_b32_e32 v5, v5, v8, vcc
	v_rsq_f32_e32 v5, v5
	v_add3_u32 v8, v24, v25, s68
	global_store_short_d16_hi v[26:27], v8, off offset:1216
	v_lshl_add_u64 v[8:9], v[32:33], 0, v[76:77]
	v_mul_f32_e32 v20, 0x45800000, v5
	v_cndmask_b32_e32 v5, v5, v20, vcc
	v_mul_f32_e32 v5, 0x3f4ccccd, v5
	v_mul_f32_e32 v18, v18, v5
	v_mul_f32_e32 v18, v163, v18
	v_bfe_u32 v20, v18, 16, 1
	v_add3_u32 v18, v18, v20, s68
	global_store_short_d16_hi v[8:9], v18, off offset:1024
	v_mul_f32_e32 v18, v19, v5
	v_mul_f32_e32 v18, v162, v18
	v_bfe_u32 v19, v18, 16, 1
	v_add3_u32 v18, v18, v19, s68
	global_store_short_d16_hi v[8:9], v18, off offset:1088
	v_mul_f32_e32 v18, v23, v5
	v_mul_f32_e32 v18, v161, v18
	v_bfe_u32 v19, v18, 16, 1
	v_add3_u32 v18, v18, v19, s68
	global_store_short_d16_hi v[8:9], v18, off offset:1152
	v_mul_f32_e32 v18, 0x4b800000, v4
	v_cmp_gt_f32_e32 vcc, s67, v4
	v_mul_f32_e32 v5, v22, v5
	v_mul_f32_e32 v5, v130, v5
	v_cndmask_b32_e32 v4, v4, v18, vcc
	v_rsq_f32_e32 v4, v4
	v_bfe_u32 v18, v5, 16, 1
	v_add3_u32 v5, v5, v18, s68
	global_store_short_d16_hi v[8:9], v5, off offset:1216
	v_mul_f32_e32 v5, 0x45800000, v4
	v_cndmask_b32_e32 v34, v4, v5, vcc
	v_mov_b32_e32 v4, v12
	v_mov_b32_e32 v5, v60
	v_mov_b32_e32 v18, v44
	v_mov_b32_e32 v19, v28
	v_pk_mul_f32 v[4:5], v[4:5], v[0:1] op_sel_hi:[1,0]
	v_pk_mul_f32 v[18:19], v[18:19], v[0:1] op_sel_hi:[1,0]
	v_rcp_f32_e32 v0, v1
	v_mov_b32_e32 v60, v13
	v_mov_b32_e32 v28, v45
	s_waitcnt vmcnt(58)
	v_pk_fma_f32 v[4:5], v[128:129], v[4:5], v[116:117] neg_lo:[1,0,0] neg_hi:[1,0,0]
	v_pk_mul_f32 v[12:13], v[60:61], v[0:1] op_sel_hi:[1,0]
	v_pk_mul_f32 v[0:1], v[28:29], v[0:1] op_sel_hi:[1,0]
	s_waitcnt vmcnt(54)
	v_pk_fma_f32 v[12:13], v[128:129], v[12:13], v[112:113] neg_lo:[1,0,0] neg_hi:[1,0,0]
	v_pk_mul_f32 v[8:9], v[4:5], v[4:5]
	v_pk_fma_f32 v[18:19], v[128:129], v[18:19], v[114:115] neg_lo:[1,0,0] neg_hi:[1,0,0]
	v_pk_mul_f32 v[22:23], v[12:13], v[12:13]
	s_waitcnt vmcnt(52)
	v_pk_fma_f32 v[0:1], v[128:129], v[0:1], v[110:111] neg_lo:[1,0,0] neg_hi:[1,0,0]
	v_pk_mul_f32 v[20:21], v[18:19], v[18:19]
	v_pk_mul_f32 v[24:25], v[0:1], v[0:1]
	v_mov_b32_e32 v26, v22
	v_mov_b32_e32 v27, v8
	v_mov_b32_e32 v8, v23
	v_pk_add_f32 v[8:9], v[26:27], v[8:9]
	v_mov_b32_e32 v22, v25
	v_mov_b32_e32 v23, v21
	v_pk_add_f32 v[8:9], v[22:23], v[8:9]
	v_mov_b32_e32 v25, v20
	v_pk_add_f32 v[8:9], v[24:25], v[8:9]
	ds_bpermute_b32 v21, v164, v9
	ds_bpermute_b32 v20, v164, v8
	v_mul_f32_e32 v24, 0x3f4ccccd, v34
	v_mul_f32_e32 v10, v10, v24
	v_mul_f32_e32 v10, v163, v10
	v_bfe_u32 v25, v10, 16, 1
	s_waitcnt lgkmcnt(0)
	v_pk_add_f32 v[8:9], v[8:9], v[20:21]
	ds_bpermute_b32 v21, v165, v9
	ds_bpermute_b32 v20, v165, v8
	v_lshl_add_u64 v[22:23], v[32:33], 0, v[72:73]
	v_add3_u32 v10, v10, v25, s68
	global_store_short_d16_hi v[22:23], v10, off offset:1024
	v_mul_f32_e32 v25, v11, v24
	s_waitcnt lgkmcnt(0)
	v_pk_add_f32 v[8:9], v[8:9], v[20:21]
	ds_bpermute_b32 v11, v168, v9
	ds_bpermute_b32 v10, v168, v8
	v_mul_f32_e32 v20, v162, v25
	v_bfe_u32 v21, v20, 16, 1
	v_mul_f32_e32 v7, v7, v24
	v_add3_u32 v20, v20, v21, s68
	s_waitcnt lgkmcnt(0)
	v_pk_add_f32 v[8:9], v[8:9], v[10:11]
	ds_bpermute_b32 v11, v167, v9
	ds_bpermute_b32 v10, v167, v8
	v_mul_f32_e32 v7, v161, v7
	global_store_short_d16_hi v[22:23], v20, off offset:1088
	v_bfe_u32 v20, v7, 16, 1
	v_add3_u32 v7, v7, v20, s68
	s_waitcnt lgkmcnt(0)
	v_pk_add_f32 v[8:9], v[8:9], v[10:11]
	ds_bpermute_b32 v11, v166, v9
	ds_bpermute_b32 v10, v166, v8
	v_mul_f32_e32 v6, v6, v24
	global_store_short_d16_hi v[22:23], v7, off offset:1152
	v_mul_f32_e32 v20, v130, v6
	v_bfe_u32 v21, v20, 16, 1
	s_waitcnt lgkmcnt(0)
; DI unsigned short f2bf(float x) { unsigned u = __float_as_uint(x); u += 0x7fffu + ((u >> 16) & 1u); return (unsigned short)(u >> 16); }
; DI float shx(float v, int mask, int lane) { return __int_as_float(__builtin_amdgcn_ds_bpermute((lane ^ mask) << 2, __float_as_int(v))); }
; template <int DQK, int MODE, int LDQ, int LDK, int LDV> ...
;     ...
;         } else {
;             float v[4]; float ss = 0.f;
; #pragma unroll
;             for (int d0 = 0; d0 < 4; ++d0) { v[d0] = s0v[r][d0] - lam * (o[d0][r] * rl); ss += v[d0] * v[d0]; }
; #pragma unroll
;             for (int mk = 1; mk <= 16; mk <<= 1) ss += shx(ss, mk, lane2);
;             const float rs = rsqrtf(ss * (1.f / 128.f) + EPS) * 0.8f;
; #pragma unroll
;             for (int d0 = 0; d0 < 4; ++d0) AOb[(size_t)orow * 1024 + d0 * 32 + r32] = f2bf(v[d0] * rs * gout[d0 * 32 + r32]);
	v_pk_add_f32 v[6:7], v[8:9], v[10:11]
	s_nop 0
	v_pk_fma_f32 v[6:7], v[6:7], s[24:25], v[92:93] op_sel_hi:[1,0,0]
	s_nop 0
	v_mul_f32_e32 v8, 0x4b800000, v7
	v_cmp_gt_f32_e32 vcc, s67, v7
	s_nop 1
	v_cndmask_b32_e32 v7, v7, v8, vcc
	v_rsq_f32_e32 v7, v7
	v_add3_u32 v8, v20, v21, s68
	global_store_short_d16_hi v[22:23], v8, off offset:1216
	v_lshl_add_u64 v[8:9], v[32:33], 0, v[74:75]
	v_mul_f32_e32 v10, 0x45800000, v7
	v_cndmask_b32_e32 v7, v7, v10, vcc
	v_mul_f32_e32 v7, 0x3f4ccccd, v7
	v_mul_f32_e32 v4, v4, v7
	v_mul_f32_e32 v4, v163, v4
	v_bfe_u32 v10, v4, 16, 1
	v_add3_u32 v4, v4, v10, s68
	global_store_short_d16_hi v[8:9], v4, off offset:1024
	v_mul_f32_e32 v4, v5, v7
	v_mul_f32_e32 v4, v162, v4
	v_bfe_u32 v5, v4, 16, 1
	v_add3_u32 v4, v4, v5, s68
	global_store_short_d16_hi v[8:9], v4, off offset:1088
	v_mul_f32_e32 v4, v19, v7
	v_mul_f32_e32 v4, v161, v4
	v_bfe_u32 v5, v4, 16, 1
	v_add3_u32 v4, v4, v5, s68
	v_mul_f32_e32 v5, 0x4b800000, v6
	v_cmp_gt_f32_e32 vcc, s67, v6
	global_store_short_d16_hi v[8:9], v4, off offset:1152
	v_mul_f32_e32 v4, v18, v7
	v_cndmask_b32_e32 v5, v6, v5, vcc
	v_rsq_f32_e32 v5, v5
	v_mul_f32_e32 v4, v130, v4
	v_bfe_u32 v6, v4, 16, 1
	v_add3_u32 v4, v4, v6, s68
	global_store_short_d16_hi v[8:9], v4, off offset:1216
	v_mul_f32_e32 v4, 0x45800000, v5
	v_cndmask_b32_e32 v24, v5, v4, vcc
	v_mov_b32_e32 v4, v14
	v_mov_b32_e32 v5, v62
	v_mov_b32_e32 v8, v46
	v_mov_b32_e32 v9, v30
	v_pk_mul_f32 v[4:5], v[4:5], v[2:3] op_sel_hi:[1,0]
	v_pk_mul_f32 v[8:9], v[8:9], v[2:3] op_sel_hi:[1,0]
	v_rcp_f32_e32 v2, v3
	v_mov_b32_e32 v62, v15
	v_mov_b32_e32 v30, v47
	s_waitcnt vmcnt(58)
	v_pk_fma_f32 v[4:5], v[128:129], v[4:5], v[108:109] neg_lo:[1,0,0] neg_hi:[1,0,0]
	v_pk_mul_f32 v[14:15], v[62:63], v[2:3] op_sel_hi:[1,0]
	v_pk_mul_f32 v[2:3], v[30:31], v[2:3] op_sel_hi:[1,0]
	s_waitcnt vmcnt(54)
	v_pk_fma_f32 v[14:15], v[128:129], v[14:15], v[104:105] neg_lo:[1,0,0] neg_hi:[1,0,0]
	v_pk_mul_f32 v[6:7], v[4:5], v[4:5]
	v_pk_fma_f32 v[8:9], v[128:129], v[8:9], v[106:107] neg_lo:[1,0,0] neg_hi:[1,0,0]
	v_pk_mul_f32 v[18:19], v[14:15], v[14:15]
	s_waitcnt vmcnt(52)
	v_pk_fma_f32 v[2:3], v[128:129], v[2:3], v[102:103] neg_lo:[1,0,0] neg_hi:[1,0,0]
	v_pk_mul_f32 v[10:11], v[8:9], v[8:9]
	v_pk_mul_f32 v[20:21], v[2:3], v[2:3]
	v_mov_b32_e32 v22, v18
	v_mov_b32_e32 v23, v6
	v_mov_b32_e32 v6, v19
	v_pk_add_f32 v[6:7], v[22:23], v[6:7]
	v_mov_b32_e32 v18, v21
	v_mov_b32_e32 v19, v11
	v_pk_add_f32 v[6:7], v[18:19], v[6:7]
	v_mov_b32_e32 v21, v10
	v_pk_add_f32 v[6:7], v[20:21], v[6:7]
	ds_bpermute_b32 v11, v164, v7
	ds_bpermute_b32 v10, v164, v6
	v_mul_f32_e32 v20, 0x3f4ccccd, v24
	v_mul_f32_e32 v12, v12, v20
	v_mul_f32_e32 v12, v163, v12
	v_bfe_u32 v21, v12, 16, 1
	s_waitcnt lgkmcnt(0)
	v_pk_add_f32 v[6:7], v[6:7], v[10:11]
	ds_bpermute_b32 v11, v165, v7
	ds_bpermute_b32 v10, v165, v6
	v_lshl_add_u64 v[18:19], v[32:33], 0, v[64:65]
	v_add3_u32 v12, v12, v21, s68
	global_store_short_d16_hi v[18:19], v12, off offset:1024
	v_mul_f32_e32 v12, v13, v20
	s_waitcnt lgkmcnt(0)
	v_pk_add_f32 v[6:7], v[6:7], v[10:11]
	ds_bpermute_b32 v11, v168, v7
	ds_bpermute_b32 v10, v168, v6
	v_mul_f32_e32 v12, v162, v12
	v_bfe_u32 v13, v12, 16, 1
	v_mul_f32_e32 v1, v1, v20
	v_add3_u32 v12, v12, v13, s68
	s_waitcnt lgkmcnt(0)
	v_pk_add_f32 v[6:7], v[6:7], v[10:11]
	ds_bpermute_b32 v11, v167, v7
	ds_bpermute_b32 v10, v167, v6
	v_mul_f32_e32 v1, v161, v1
	global_store_short_d16_hi v[18:19], v12, off offset:1088
	v_bfe_u32 v12, v1, 16, 1
	v_add3_u32 v1, v1, v12, s68
	s_waitcnt lgkmcnt(0)
	v_pk_add_f32 v[6:7], v[6:7], v[10:11]
	ds_bpermute_b32 v11, v166, v7
	ds_bpermute_b32 v10, v166, v6
	v_mul_f32_e32 v0, v0, v20
	global_store_short_d16_hi v[18:19], v1, off offset:1152
	v_mul_f32_e32 v12, v130, v0
	v_bfe_u32 v13, v12, 16, 1
	s_waitcnt lgkmcnt(0)
	v_pk_add_f32 v[0:1], v[6:7], v[10:11]
	s_nop 0
	v_pk_fma_f32 v[0:1], v[0:1], s[24:25], v[92:93] op_sel_hi:[1,0,0]
	s_nop 0
	v_mul_f32_e32 v6, 0x4b800000, v1
	v_cmp_gt_f32_e32 vcc, s67, v1
	s_nop 1
	v_cndmask_b32_e32 v1, v1, v6, vcc
	v_rsq_f32_e32 v1, v1
	v_add3_u32 v6, v12, v13, s68
	global_store_short_d16_hi v[18:19], v6, off offset:1216
	v_lshl_add_u64 v[6:7], v[32:33], 0, v[48:49]
	v_mul_f32_e32 v10, 0x45800000, v1
	v_cndmask_b32_e32 v1, v1, v10, vcc
	v_mul_f32_e32 v1, 0x3f4ccccd, v1
	v_mul_f32_e32 v4, v4, v1
	v_mul_f32_e32 v4, v163, v4
	v_bfe_u32 v10, v4, 16, 1
	v_add3_u32 v4, v4, v10, s68
	global_store_short_d16_hi v[6:7], v4, off offset:1024
	v_mul_f32_e32 v4, v5, v1
	v_mul_f32_e32 v4, v162, v4
	v_bfe_u32 v5, v4, 16, 1
	v_add3_u32 v4, v4, v5, s68
	global_store_short_d16_hi v[6:7], v4, off offset:1088
	v_mul_f32_e32 v4, v9, v1
	v_mul_f32_e32 v4, v161, v4
	v_bfe_u32 v5, v4, 16, 1
	v_add3_u32 v4, v4, v5, s68
	global_store_short_d16_hi v[6:7], v4, off offset:1152
	v_mul_f32_e32 v4, 0x4b800000, v0
	v_cmp_gt_f32_e32 vcc, s67, v0
	v_mul_f32_e32 v1, v8, v1
	v_mul_f32_e32 v1, v130, v1
	v_cndmask_b32_e32 v0, v0, v4, vcc
	v_rsq_f32_e32 v0, v0
	v_bfe_u32 v4, v1, 16, 1
	v_add3_u32 v1, v1, v4, s68
	global_store_short_d16_hi v[6:7], v1, off offset:1216
	v_mul_f32_e32 v1, 0x45800000, v0
	v_cndmask_b32_e32 v0, v0, v1, vcc
	v_mul_f32_e32 v4, 0x3f4ccccd, v0
	v_mul_f32_e32 v5, v14, v4
	v_mul_f32_e32 v5, v163, v5
	v_bfe_u32 v6, v5, 16, 1
	v_lshl_add_u64 v[0:1], v[32:33], 0, v[16:17]
	v_add3_u32 v5, v5, v6, s68
	global_store_short_d16_hi v[0:1], v5, off offset:1024
	v_mul_f32_e32 v5, v15, v4
	v_mul_f32_e32 v5, v162, v5
	v_bfe_u32 v6, v5, 16, 1
	v_mul_f32_e32 v3, v3, v4
	v_add3_u32 v5, v5, v6, s68
	v_mul_f32_e32 v3, v161, v3
	global_store_short_d16_hi v[0:1], v5, off offset:1088
	v_bfe_u32 v5, v3, 16, 1
	v_mul_f32_e32 v2, v2, v4
	v_add3_u32 v3, v3, v5, s68
	v_mul_f32_e32 v2, v130, v2
	global_store_short_d16_hi v[0:1], v3, off offset:1152
	v_bfe_u32 v3, v2, 16, 1
	v_add3_u32 v2, v2, v3, s68
	global_store_short_d16_hi v[0:1], v2, off offset:1216
	s_waitcnt vmcnt(63) expcnt(7) lgkmcnt(15)
	s_barrier

.Lstg_mla_top_2:
	s_setprio 0
	s_mov_b32 m0, s1
	s_mov_b32 s0, s5
	s_mov_b32 s5, s44
	s_mov_b32 s44, s4
	s_lshl_b32 s4, s4, 14
	global_load_lds_dwordx4 v136, s[34:35]
	s_add_i32 m0, s1, 0x2000
	s_add_i32 s4, s52, s4
	global_load_lds_dwordx4 v138, s[34:35]
	s_add_i32 m0, s1, 0x4000
	s_add_i32 s6, s4, 0x400
	global_load_lds_dwordx4 v140, s[34:35]
	s_mov_b32 m0, s4
	s_add_i32 s1, s43, -3
	global_load_lds_dwordx4 v144, s[34:35]
	s_mov_b32 m0, s6
	s_nop 0
	global_load_lds_dwordx4 v142, s[34:35]
	s_and_b32 s1, s1, 3
	s_mulk_i32 s1, 0x6000
	v_add_u32_e32 v246, s1, v158
	v_add_u32_e32 v174, v246, v151
	v_add_u32_e32 v178, v246, v149
	v_add_u32_e32 v182, v246, v148
	v_add_u32_e32 v186, v246, v147
	v_add_u32_e32 v190, v246, v146
	v_add_u32_e32 v194, v246, v150
	s_lshl_b32 s1, s0, 14
	ds_read_b128 v[174:177], v174 offset:12288
	ds_read_b128 v[178:181], v178 offset:12288
	ds_read_b128 v[182:185], v182 offset:12288
	ds_read_b128 v[186:189], v186 offset:12288
	ds_read_b128 v[190:193], v190 offset:12288
	ds_read_b128 v[194:197], v194 offset:12288
	v_add_u32_e32 v254, s1, v130
	ds_read_b64_tr_b16 v[198:199], v254 offset:0
	ds_read_b64_tr_b16 v[200:201], v254 offset:0x800
	ds_read_b64_tr_b16 v[202:203], v254 offset:0x1000
	ds_read_b64_tr_b16 v[204:205], v254 offset:0x1800
	ds_read_b64_tr_b16 v[206:207], v254 offset:0x200
	ds_read_b64_tr_b16 v[208:209], v254 offset:0xa00
	ds_read_b64_tr_b16 v[210:211], v254 offset:0x1200
	ds_read_b64_tr_b16 v[212:213], v254 offset:0x1a00
	ds_read_b64_tr_b16 v[214:215], v254 offset:0x400
	ds_read_b64_tr_b16 v[216:217], v254 offset:0xc00
	ds_read_b64_tr_b16 v[218:219], v254 offset:0x1400
	ds_read_b64_tr_b16 v[220:221], v254 offset:0x1c00
	ds_read_b64_tr_b16 v[222:223], v254 offset:0x600
	ds_read_b64_tr_b16 v[224:225], v254 offset:0xe00
	ds_read_b64_tr_b16 v[226:227], v254 offset:0x1600
	ds_read_b64_tr_b16 v[228:229], v254 offset:0x1e00
	s_setprio 2
	v_exp_f32_e32 v64, v64
	v_exp_f32_e32 v65, v65
	v_exp_f32_e32 v66, v66
	v_exp_f32_e32 v67, v67
	v_exp_f32_e32 v68, v68
	v_add_f32_e32 v230, 0, v64
	v_exp_f32_e32 v69, v69
	v_add_f32_e32 v230, v65, v230
	v_exp_f32_e32 v70, v70
	v_add_f32_e32 v230, v66, v230
	v_exp_f32_e32 v71, v71
	v_add_f32_e32 v230, v67, v230
	v_exp_f32_e32 v72, v72
	v_add_f32_e32 v230, v68, v230
	v_exp_f32_e32 v73, v73
	v_add_f32_e32 v230, v69, v230
	v_exp_f32_e32 v74, v74
	v_add_f32_e32 v230, v70, v230
	v_exp_f32_e32 v75, v75
	v_add_f32_e32 v230, v71, v230
	v_exp_f32_e32 v76, v76
	v_add_f32_e32 v230, v72, v230
	v_exp_f32_e32 v77, v77
	v_add_f32_e32 v230, v73, v230
	v_exp_f32_e32 v78, v78
	v_add_f32_e32 v230, v74, v230
	v_exp_f32_e32 v79, v79
	v_add_f32_e32 v230, v75, v230
	v_add_f32_e32 v230, v76, v230
	v_add_f32_e32 v230, v77, v230
	v_add_f32_e32 v230, v78, v230
	v_add_f32_e32 v230, v79, v230
	v_add_f32_e32 v173, v173, v230
	v_cvt_pk_bf16_f32 v64, v64, v65
	v_cvt_pk_bf16_f32 v65, v66, v67
	v_cvt_pk_bf16_f32 v66, v68, v69
	v_cvt_pk_bf16_f32 v67, v70, v71
	v_cvt_pk_bf16_f32 v68, v72, v73
	v_cvt_pk_bf16_f32 v69, v74, v75
	v_cvt_pk_bf16_f32 v70, v76, v77
	v_cvt_pk_bf16_f32 v71, v78, v79
	s_nop 0
	v_permlane32_swap_b32_e32 v64, v66
	v_permlane32_swap_b32_e32 v65, v67
	v_permlane32_swap_b32_e32 v68, v70
	v_permlane32_swap_b32_e32 v69, v71
	s_waitcnt lgkmcnt(0)
	v_add_u32_e32 v72, v246, v152
	v_add_u32_e32 v73, v246, v153
	ds_read_b128 v[230:233], v72 offset:12288
	ds_read_b128 v[234:237], v73 offset:12288
	v_add_u32_e32 v72, v246, v154
	v_add_u32_e32 v73, v246, v155
	ds_read_b128 v[238:241], v72 offset:12288
	ds_read_b128 v[242:245], v73 offset:12288
	v_add_u32_e32 v72, v246, v156
	v_add_u32_e32 v73, v246, v157
	ds_read_b128 v[246:249], v72 offset:12288
	ds_read_b128 v[250:253], v73 offset:12288
	s_setprio 1
	v_mfma_f32_32x32x16_bf16 v[48:63], v[64:67], v[198:201], v[48:63]
	v_mfma_f32_32x32x16_bf16 v[32:47], v[64:67], v[206:209], v[32:47]
	v_mfma_f32_32x32x16_bf16 v[16:31], v[64:67], v[214:217], v[16:31]
	v_mfma_f32_32x32x16_bf16 v[0:15], v[64:67], v[222:225], v[0:15]
	v_mfma_f32_32x32x16_bf16 v[48:63], v[68:71], v[202:205], v[48:63]
	v_mfma_f32_32x32x16_bf16 v[32:47], v[68:71], v[210:213], v[32:47]
	v_mfma_f32_32x32x16_bf16 v[16:31], v[68:71], v[218:221], v[16:31]
	v_mfma_f32_32x32x16_bf16 v[0:15], v[68:71], v[226:229], v[0:15]
	s_waitcnt lgkmcnt(0)
; #define SBAR() __builtin_amdgcn_sched_barrier(0)
; #define ATT_DMA_K(t) do { const bf16_t* kg_ = Kh + (size_t)(t) * 64 * LDK; LAS unsigned char* sb_ = lds + ((t) & 3) * KBUF; \
;     _Pragma("unroll") for (int i_ = 0; i_ < NKP; ++i_) __builtin_amdgcn_global_load_lds((const unsigned*)(kg_ + kgo[i_]), (LAS unsigned*)(sb_ + (wid + 8 * i_) * 1024), 16, 0, 0); } while (0)
; #define ATT_DMA_V(t, vs) do { const bf16_t* vg_ = Vh + (size_t)(t) * 64 * LDV; LAS unsigned char* sb_ = lds + V_OFF + (vs) * SHM_V; \
;     _Pragma("unroll") for (int i_ = 0; i_ < 2; ++i_) __builtin_amdgcn_global_load_lds((const unsigned*)(vg_ + vgo[i_]), (LAS unsigned*)(sb_ + (2 * wid + i_) * 1024), 16, 0, 0); } while (0)
; #define ATT_SEG(t) do { if constexpr (MODE != 0) { if (((t) == tL && tL > 0) || (t) == tR) { const float f_ = (t) == tR ? fR : fL; l_reg *= f_; \
;     _Pragma("unroll") for (int d = 0; d < 4; ++d) _Pragma("unroll") for (int r = 0; r < 16; ++r) o[d][r] *= f_; } } } while (0)
; #define ATT_BIAS(P, t, half) do { if constexpr (MODE != 0) { if ((t) >= tL && (t) < tR) { const LAS float* bp_ = bt + ((t) * 64 + (half) * 32 - qpos + 224 + 4 * hi);     \
;     _Pragma("unroll") for (int r = 0; r < 16; ++r) P[r] += bp_[(r & 3) + 8 * (r >> 2)]; } } } while (0)
; #define ATT_TOP(N) do { asm volatile("s_waitcnt vmcnt(%0)" :: "n"(N) : "memory"); __builtin_amdgcn_s_barrier(); asm volatile("" ::: "memory"); } while (0)
; #define ATT_LGKM0() do { SBAR(); asm volatile("s_waitcnt lgkmcnt(0)" ::: "memory"); SBAR(); } while (0)
; template <int DQK, int MODE, int LDQ, int LDK, int LDV> ...
;     ...
;     f32x16 pA, pB; bf16x8 pa0, pa1;
;     int v0 = 0, v1 = 1, v2 = 2;
;     ATT_TOP(NKP + 2);
;     { bf16x8 kf[NDA]; k_reads<DQK, 0, NDA>(kf, lds, 0, r32, hi); ATT_LGKM0(); qk_mma<0, NDA>(pA, kf, qr);
;       if constexpr (ND0 > NDA) { bf16x8 kg[ND0 - NDA]; k_reads<DQK, NDA, ND0>(kg, lds, 0, r32, hi); ATT_LGKM0(); qk_mma<NDA, ND0>(pA, kg, qr); }
;       ATT_BIAS(pA, 0, 0); }
;     if (wid >= 4) __builtin_amdgcn_s_setprio(1);
;     for (int j = 0; j < NT; ++j) {
;         if (j + 2 < NT) ATT_TOP(NKP + 2); else ATT_TOP(0);
;         if (j + 3 < NT) ATT_DMA_K(j + 3);
;         if (j + 2 < NT) ATT_DMA_V(j + 2, v2);
;         ATT_SEG(j); SBAR();
;         ATT_STEP(pA, pB, 0, v0, true, 1, j);
;         ATT_STEP(pB, pA, 1, v0, (j + 1 < NT), 0, j + 1);
	v_mfma_f32_32x32x16_bf16 v[64:79], v[174:177], v[80:83], 0
	v_mfma_f32_32x32x16_bf16 v[64:79], v[178:181], v[84:87], v[64:79]
	v_mfma_f32_32x32x16_bf16 v[64:79], v[182:185], v[88:91], v[64:79]
	v_mfma_f32_32x32x16_bf16 v[64:79], v[186:189], v[92:95], v[64:79]
	v_mfma_f32_32x32x16_bf16 v[64:79], v[190:193], v[96:99], v[64:79]
	v_mfma_f32_32x32x16_bf16 v[64:79], v[194:197], v[100:103], v[64:79]
	v_mfma_f32_32x32x16_bf16 v[64:79], v[230:233], v[104:107], v[64:79]
	v_mfma_f32_32x32x16_bf16 v[64:79], v[234:237], v[108:111], v[64:79]
	v_mfma_f32_32x32x16_bf16 v[64:79], v[238:241], v[112:115], v[64:79]
	v_mfma_f32_32x32x16_bf16 v[64:79], v[242:245], v[116:119], v[64:79]
	v_mfma_f32_32x32x16_bf16 v[64:79], v[246:249], v[120:123], v[64:79]
	v_mfma_f32_32x32x16_bf16 v[64:79], v[250:253], v[124:127], v[64:79]
	s_setprio 0
	s_add_i32 s4, s43, -2
	s_and_b32 s4, s4, 3
	s_mulk_i32 s4, 0x6000
	v_add_u32_e32 v246, s4, v158
	v_add_u32_e32 v174, v246, v151
	v_add_u32_e32 v178, v246, v149
	v_add_u32_e32 v182, v246, v148
	v_add_u32_e32 v186, v246, v147
	v_add_u32_e32 v190, v246, v146
	v_add_u32_e32 v194, v246, v150
	ds_read_b128 v[174:177], v174
	ds_read_b128 v[178:181], v178
	ds_read_b128 v[182:185], v182
	ds_read_b128 v[186:189], v186
	ds_read_b128 v[190:193], v190
	ds_read_b128 v[194:197], v194
	ds_read_b64_tr_b16 v[198:199], v254 offset:0x2000
	ds_read_b64_tr_b16 v[200:201], v254 offset:0x2800
	ds_read_b64_tr_b16 v[202:203], v254 offset:0x3000
	ds_read_b64_tr_b16 v[204:205], v254 offset:0x3800
	ds_read_b64_tr_b16 v[206:207], v254 offset:0x2200
	ds_read_b64_tr_b16 v[208:209], v254 offset:0x2a00
	ds_read_b64_tr_b16 v[210:211], v254 offset:0x3200
	ds_read_b64_tr_b16 v[212:213], v254 offset:0x3a00
	ds_read_b64_tr_b16 v[214:215], v254 offset:0x2400
	ds_read_b64_tr_b16 v[216:217], v254 offset:0x2c00
	ds_read_b64_tr_b16 v[218:219], v254 offset:0x3400
	ds_read_b64_tr_b16 v[220:221], v254 offset:0x3c00
	ds_read_b64_tr_b16 v[222:223], v254 offset:0x2600
	ds_read_b64_tr_b16 v[224:225], v254 offset:0x2e00
	ds_read_b64_tr_b16 v[226:227], v254 offset:0x3600
	ds_read_b64_tr_b16 v[228:229], v254 offset:0x3e00
	s_setprio 2
	v_exp_f32_e32 v64, v64
	v_exp_f32_e32 v65, v65
	v_exp_f32_e32 v66, v66
	v_exp_f32_e32 v67, v67
	v_exp_f32_e32 v68, v68
	v_add_f32_e32 v230, 0, v64
	v_exp_f32_e32 v69, v69
	v_add_f32_e32 v230, v65, v230
	v_exp_f32_e32 v70, v70
	v_add_f32_e32 v230, v66, v230
	v_exp_f32_e32 v71, v71
	v_add_f32_e32 v230, v67, v230
	v_exp_f32_e32 v72, v72
	v_add_f32_e32 v230, v68, v230
	v_exp_f32_e32 v73, v73
	v_add_f32_e32 v230, v69, v230
	v_exp_f32_e32 v74, v74
	v_add_f32_e32 v230, v70, v230
	v_exp_f32_e32 v75, v75
	v_add_f32_e32 v230, v71, v230
	v_exp_f32_e32 v76, v76
	v_add_f32_e32 v230, v72, v230
	v_exp_f32_e32 v77, v77
	v_add_f32_e32 v230, v73, v230
	v_exp_f32_e32 v78, v78
	v_add_f32_e32 v230, v74, v230
	v_exp_f32_e32 v79, v79
	v_add_f32_e32 v230, v75, v230
	v_add_f32_e32 v230, v76, v230
	v_add_f32_e32 v230, v77, v230
	v_add_f32_e32 v230, v78, v230
	v_add_f32_e32 v230, v79, v230
	v_add_f32_e32 v173, v173, v230
	v_cvt_pk_bf16_f32 v64, v64, v65
	v_cvt_pk_bf16_f32 v65, v66, v67
	v_cvt_pk_bf16_f32 v66, v68, v69
	v_cvt_pk_bf16_f32 v67, v70, v71
	v_cvt_pk_bf16_f32 v68, v72, v73
	v_cvt_pk_bf16_f32 v69, v74, v75
	v_cvt_pk_bf16_f32 v70, v76, v77
	v_cvt_pk_bf16_f32 v71, v78, v79
	s_nop 0
	v_permlane32_swap_b32_e32 v64, v66
	v_permlane32_swap_b32_e32 v65, v67
	v_permlane32_swap_b32_e32 v68, v70
	v_permlane32_swap_b32_e32 v69, v71
	s_waitcnt lgkmcnt(0)
	v_add_u32_e32 v72, v246, v152
	v_add_u32_e32 v73, v246, v153
	ds_read_b128 v[230:233], v72
	ds_read_b128 v[234:237], v73
	v_add_u32_e32 v72, v246, v154
	v_add_u32_e32 v73, v246, v155
	ds_read_b128 v[238:241], v72
	ds_read_b128 v[242:245], v73
	v_add_u32_e32 v72, v246, v156
	v_add_u32_e32 v73, v246, v157
	ds_read_b128 v[246:249], v72
	ds_read_b128 v[250:253], v73
	s_setprio 1
	s_cmp_lt_u32 s33, 0x100
	s_cbranch_scc1 .Lstg_mla_mid_3
	s_waitcnt vmcnt(5)
	s_barrier

.Lstg_mla_t61_4:
	s_setprio 0
	v_lshl_add_u64 v[132:133], v[132:133], 1, s[0:1]
	s_mov_b32 m0, s6
	v_lshl_add_u64 v[134:135], v[134:135], 1, s[0:1]
	global_load_lds_dwordx4 v[132:133], off
	s_mov_b32 m0, s7
	s_nop 0
	global_load_lds_dwordx4 v[134:135], off
	ds_read_b128 v[132:135], v161 offset:36864
	ds_read_b128 v[136:139], v162 offset:36864
	ds_read_b128 v[140:143], v163 offset:36864
	ds_read_b128 v[174:177], v164 offset:36864
	ds_read_b128 v[178:181], v165 offset:36864
	ds_read_b128 v[182:185], v166 offset:36864
	v_lshl_add_u32 v144, s5, 14, v130
	ds_read_b64_tr_b16 v[186:187], v144 offset:0
	ds_read_b64_tr_b16 v[188:189], v144 offset:0x800
	ds_read_b64_tr_b16 v[190:191], v144 offset:0x1000
	ds_read_b64_tr_b16 v[192:193], v144 offset:0x1800
	ds_read_b64_tr_b16 v[194:195], v144 offset:0x200
	ds_read_b64_tr_b16 v[196:197], v144 offset:0xa00
	ds_read_b64_tr_b16 v[198:199], v144 offset:0x1200
	ds_read_b64_tr_b16 v[200:201], v144 offset:0x1a00
	ds_read_b64_tr_b16 v[202:203], v144 offset:0x400
	ds_read_b64_tr_b16 v[204:205], v144 offset:0xc00
	ds_read_b64_tr_b16 v[206:207], v144 offset:0x1400
	ds_read_b64_tr_b16 v[208:209], v144 offset:0x1c00
	ds_read_b64_tr_b16 v[210:211], v144 offset:0x600
	ds_read_b64_tr_b16 v[212:213], v144 offset:0xe00
	ds_read_b64_tr_b16 v[214:215], v144 offset:0x1600
	ds_read_b64_tr_b16 v[216:217], v144 offset:0x1e00
	s_setprio 2
	v_exp_f32_e32 v64, v64
	v_exp_f32_e32 v65, v65
	v_exp_f32_e32 v66, v66
	v_exp_f32_e32 v67, v67
	v_exp_f32_e32 v68, v68
	v_add_f32_e32 v145, 0, v64
	v_exp_f32_e32 v69, v69
	v_add_f32_e32 v145, v65, v145
	v_exp_f32_e32 v70, v70
	v_add_f32_e32 v145, v66, v145
	v_exp_f32_e32 v71, v71
	v_add_f32_e32 v145, v67, v145
	v_exp_f32_e32 v72, v72
	v_add_f32_e32 v145, v68, v145
	v_exp_f32_e32 v73, v73
	v_add_f32_e32 v145, v69, v145
	v_exp_f32_e32 v74, v74
	v_add_f32_e32 v145, v70, v145
	v_exp_f32_e32 v75, v75
	v_add_f32_e32 v145, v71, v145
	v_exp_f32_e32 v76, v76
	v_add_f32_e32 v145, v72, v145
	v_exp_f32_e32 v77, v77
	v_add_f32_e32 v145, v73, v145
	v_exp_f32_e32 v78, v78
	v_add_f32_e32 v145, v74, v145
	v_exp_f32_e32 v79, v79
	v_add_f32_e32 v145, v75, v145
	v_add_f32_e32 v145, v76, v145
	v_add_f32_e32 v145, v77, v145
	v_add_f32_e32 v145, v78, v145
	v_add_f32_e32 v145, v79, v145
	v_add_f32_e32 v145, v173, v145
	v_cvt_pk_bf16_f32 v64, v64, v65
	v_cvt_pk_bf16_f32 v65, v66, v67
	v_cvt_pk_bf16_f32 v66, v68, v69
	v_cvt_pk_bf16_f32 v67, v70, v71
	v_cvt_pk_bf16_f32 v68, v72, v73
	v_cvt_pk_bf16_f32 v69, v74, v75
	v_cvt_pk_bf16_f32 v70, v76, v77
	v_cvt_pk_bf16_f32 v71, v78, v79
	s_nop 0
	v_permlane32_swap_b32_e32 v64, v66
	v_permlane32_swap_b32_e32 v65, v67
	v_permlane32_swap_b32_e32 v68, v70
	v_permlane32_swap_b32_e32 v69, v71
	s_waitcnt lgkmcnt(0)
	ds_read_b128 v[218:221], v167 offset:36864
	ds_read_b128 v[222:225], v168 offset:36864
	ds_read_b128 v[226:229], v169 offset:36864
	ds_read_b128 v[230:233], v170 offset:36864
	ds_read_b128 v[234:237], v171 offset:36864
	ds_read_b128 v[238:241], v172 offset:36864
	s_setprio 1
	v_mfma_f32_32x32x16_bf16 v[48:63], v[64:67], v[186:189], v[48:63]
	v_mfma_f32_32x32x16_bf16 v[32:47], v[64:67], v[194:197], v[32:47]
	v_mfma_f32_32x32x16_bf16 v[16:31], v[64:67], v[202:205], v[16:31]
	v_mfma_f32_32x32x16_bf16 v[0:15], v[64:67], v[210:213], v[0:15]
	v_mfma_f32_32x32x16_bf16 v[48:63], v[68:71], v[190:193], v[48:63]
	v_mfma_f32_32x32x16_bf16 v[32:47], v[68:71], v[198:201], v[32:47]
	v_mfma_f32_32x32x16_bf16 v[16:31], v[68:71], v[206:209], v[16:31]
	v_mfma_f32_32x32x16_bf16 v[0:15], v[68:71], v[214:217], v[0:15]
	s_waitcnt lgkmcnt(0)
; #define LAS __attribute__((address_space(3)))
; DI void expsum(f32x16& p, float& l_reg, bf16x8& pa0, bf16x8& pa1) {
; #pragma unroll
;     for (int r = 0; r < 16; ++r) p[r] = __builtin_amdgcn_exp2f(p[r]);
;     float ps = 0.f;
; #pragma unroll
;     for (int r = 0; r < 16; ++r) ps += p[r];
;     l_reg += ps; asm volatile("" : "+v"(l_reg));
;     ...
;     ATT_PK4(p, 0, pa0); ATT_PK4(p, 8, pa1);
;     ...
; }
; DI int v_rd_base(int lane) { return ((lane & 3) << 3) | (((lane >> 2) & 3) << 6) | (((lane >> 4) & 1) << 5) | (((lane >> 5) & 1) << 8); }
; template <int OFF> DI s16x4 tr_read(int vb) { s16x4 r; asm volatile("ds_read_b64_tr_b16 %0, %1 offset:%2" : "=&v"(r) : "v"(vb), "i"(OFF) : "memory"); return r; }
; template <int H> DI void v_reads(s16x4* vf, int vb) {
;     vf[0] = tr_read<v_rd_off(0, 2 * H, 0)>(vb); vf[1] = tr_read<v_rd_off(0, 2 * H, 1)>(vb); vf[2] = tr_read<v_rd_off(0, 2 * H + 1, 0)>(vb); vf[3] = tr_read<v_rd_off(0, 2 * H + 1, 1)>(vb);
;     vf[4] = tr_read<v_rd_off(1, 2 * H, 0)>(vb); vf[5] = tr_read<v_rd_off(1, 2 * H, 1)>(vb); vf[6] = tr_read<v_rd_off(1, 2 * H + 1, 0)>(vb); vf[7] = tr_read<v_rd_off(1, 2 * H + 1, 1)>(vb);
;     vf[8] = tr_read<v_rd_off(2, 2 * H, 0)>(vb); vf[9] = tr_read<v_rd_off(2, 2 * H, 1)>(vb); vf[10] = tr_read<v_rd_off(2, 2 * H + 1, 0)>(vb); vf[11] = tr_read<v_rd_off(2, 2 * H + 1, 1)>(vb);
;     vf[12] = tr_read<v_rd_off(3, 2 * H, 0)>(vb); vf[13] = tr_read<v_rd_off(3, 2 * H, 1)>(vb); vf[14] = tr_read<v_rd_off(3, 2 * H + 1, 0)>(vb); vf[15] = tr_read<v_rd_off(3, 2 * H + 1, 1)>(vb);
; }
; DI void pv_mma(f32x16* o, const s16x4* vf, bf16x8 pa0, bf16x8 pa1) {
;     ...
; #pragma unroll
;     for (int d0 = 0; d0 < 4; ++d0) {
;         o[d0] = __builtin_amdgcn_mfma_f32_32x32x16_bf16(pa0, ATT_PK(vf[4 * d0], vf[4 * d0 + 1]), o[d0], 0, 0, 0);
;         o[d0] = __builtin_amdgcn_mfma_f32_32x32x16_bf16(pa1, ATT_PK(vf[4 * d0 + 2], vf[4 * d0 + 3]), o[d0], 0, 0, 0); }
;     ...
; }
; template <int DQK, int D0A, int D0B> DI void k_reads(bf16x8* kf, const LAS unsigned char* Ks, int half, int r32, int hi) {
; #pragma unroll
;     for (int d0 = D0A; d0 < D0B; ++d0) kf[d0 - D0A] = *(const LAS bf16x8*)(Ks + half * (32 * DQK * 2) + kswz<DQK>(r32, (d0 * 16 + hi * 8) * 2));
; }
; template <int D0A, int D0B> DI void qk_mma(f32x16& p, const bf16x8* kf, const bf16x8* qr) {
; #pragma unroll
;     for (int d0 = D0A; d0 < D0B; ++d0) {
	v_mfma_f32_32x32x16_bf16 v[64:79], v[132:135], v[80:83], 0
	v_mfma_f32_32x32x16_bf16 v[64:79], v[136:139], v[84:87], v[64:79]
	v_mfma_f32_32x32x16_bf16 v[64:79], v[140:143], v[88:91], v[64:79]
	v_mfma_f32_32x32x16_bf16 v[64:79], v[174:177], v[92:95], v[64:79]
	v_mfma_f32_32x32x16_bf16 v[64:79], v[178:181], v[96:99], v[64:79]
	v_mfma_f32_32x32x16_bf16 v[64:79], v[182:185], v[100:103], v[64:79]
	s_waitcnt lgkmcnt(0)
	v_mfma_f32_32x32x16_bf16 v[64:79], v[218:221], v[104:107], v[64:79]
	v_mfma_f32_32x32x16_bf16 v[64:79], v[222:225], v[108:111], v[64:79]
	v_mfma_f32_32x32x16_bf16 v[64:79], v[226:229], v[112:115], v[64:79]
	v_mfma_f32_32x32x16_bf16 v[64:79], v[230:233], v[116:119], v[64:79]
	v_mfma_f32_32x32x16_bf16 v[64:79], v[234:237], v[120:123], v[64:79]
	v_mfma_f32_32x32x16_bf16 v[64:79], v[238:241], v[124:127], v[64:79]
	s_setprio 0
	ds_read_b128 v[132:135], v161 offset:49152
	ds_read_b128 v[136:139], v162 offset:49152
	ds_read_b128 v[140:143], v163 offset:49152
	ds_read_b128 v[174:177], v164 offset:49152
	ds_read_b128 v[178:181], v165 offset:49152
	ds_read_b128 v[182:185], v166 offset:49152
	ds_read_b64_tr_b16 v[186:187], v144 offset:0x2000
	ds_read_b64_tr_b16 v[188:189], v144 offset:0x2800
	ds_read_b64_tr_b16 v[190:191], v144 offset:0x3000
	ds_read_b64_tr_b16 v[192:193], v144 offset:0x3800
	ds_read_b64_tr_b16 v[194:195], v144 offset:0x2200
	ds_read_b64_tr_b16 v[196:197], v144 offset:0x2a00
	ds_read_b64_tr_b16 v[198:199], v144 offset:0x3200
	ds_read_b64_tr_b16 v[200:201], v144 offset:0x3a00
	ds_read_b64_tr_b16 v[202:203], v144 offset:0x2400
	ds_read_b64_tr_b16 v[204:205], v144 offset:0x2c00
	ds_read_b64_tr_b16 v[206:207], v144 offset:0x3400
	ds_read_b64_tr_b16 v[208:209], v144 offset:0x3c00
	ds_read_b64_tr_b16 v[210:211], v144 offset:0x2600
	ds_read_b64_tr_b16 v[212:213], v144 offset:0x2e00
	ds_read_b64_tr_b16 v[214:215], v144 offset:0x3600
	ds_read_b64_tr_b16 v[216:217], v144 offset:0x3e00
	s_nop 5
	s_setprio 2
	v_exp_f32_e32 v64, v64
	v_exp_f32_e32 v65, v65
	v_exp_f32_e32 v66, v66
	v_exp_f32_e32 v67, v67
	v_exp_f32_e32 v68, v68
	v_add_f32_e32 v144, 0, v64
	v_exp_f32_e32 v69, v69
	v_add_f32_e32 v144, v65, v144
	v_exp_f32_e32 v70, v70
	v_add_f32_e32 v144, v66, v144
	v_exp_f32_e32 v71, v71
	v_add_f32_e32 v144, v67, v144
	v_exp_f32_e32 v72, v72
	v_add_f32_e32 v144, v68, v144
	v_exp_f32_e32 v73, v73
	v_add_f32_e32 v144, v69, v144
	v_exp_f32_e32 v74, v74
	v_add_f32_e32 v144, v70, v144
	v_exp_f32_e32 v75, v75
	v_add_f32_e32 v144, v71, v144
	v_exp_f32_e32 v76, v76
	v_add_f32_e32 v144, v72, v144
	v_exp_f32_e32 v77, v77
	v_add_f32_e32 v144, v73, v144
	v_exp_f32_e32 v78, v78
	v_add_f32_e32 v144, v74, v144
	v_exp_f32_e32 v79, v79
	v_add_f32_e32 v144, v75, v144
	v_add_f32_e32 v144, v76, v144
	v_add_f32_e32 v144, v77, v144
	v_add_f32_e32 v144, v78, v144
	v_add_f32_e32 v144, v79, v144
	v_add_f32_e32 v144, v145, v144
	v_cvt_pk_bf16_f32 v64, v64, v65
	v_cvt_pk_bf16_f32 v65, v66, v67
	v_cvt_pk_bf16_f32 v66, v68, v69
	v_cvt_pk_bf16_f32 v67, v70, v71
	v_cvt_pk_bf16_f32 v68, v72, v73
	v_cvt_pk_bf16_f32 v69, v74, v75
	v_cvt_pk_bf16_f32 v70, v76, v77
	v_cvt_pk_bf16_f32 v71, v78, v79
	s_nop 0
	v_permlane32_swap_b32_e32 v64, v66
	v_permlane32_swap_b32_e32 v65, v67
	v_permlane32_swap_b32_e32 v68, v70
	v_permlane32_swap_b32_e32 v69, v71
	s_waitcnt lgkmcnt(0)
	ds_read_b128 v[218:221], v167 offset:49152
	ds_read_b128 v[222:225], v168 offset:49152
	ds_read_b128 v[226:229], v169 offset:49152
	ds_read_b128 v[230:233], v170 offset:49152
	ds_read_b128 v[234:237], v171 offset:49152
	ds_read_b128 v[238:241], v172 offset:49152
	s_setprio 1
	s_cmp_lt_u32 s33, 0x100
	s_cbranch_scc1 .Lstg_mla_m61_5
	s_waitcnt vmcnt(0)
	s_barrier

; #define LAS __attribute__((address_space(3)))
; DI void expsum(f32x16& p, float& l_reg, bf16x8& pa0, bf16x8& pa1) {
; #pragma unroll
;     for (int r = 0; r < 16; ++r) p[r] = __builtin_amdgcn_exp2f(p[r]);
;     float ps = 0.f;
; #pragma unroll
;     for (int r = 0; r < 16; ++r) ps += p[r];
;     l_reg += ps; asm volatile("" : "+v"(l_reg));
;     ...
;     ATT_PK4(p, 0, pa0); ATT_PK4(p, 8, pa1);
;     ...
; }
; DI int v_rd_base(int lane) { return ((lane & 3) << 3) | (((lane >> 2) & 3) << 6) | (((lane >> 4) & 1) << 5) | (((lane >> 5) & 1) << 8); }
; template <int OFF> DI s16x4 tr_read(int vb) { s16x4 r; asm volatile("ds_read_b64_tr_b16 %0, %1 offset:%2" : "=&v"(r) : "v"(vb), "i"(OFF) : "memory"); return r; }
; template <int H> DI void v_reads(s16x4* vf, int vb) {
;     vf[0] = tr_read<v_rd_off(0, 2 * H, 0)>(vb); vf[1] = tr_read<v_rd_off(0, 2 * H, 1)>(vb); vf[2] = tr_read<v_rd_off(0, 2 * H + 1, 0)>(vb); vf[3] = tr_read<v_rd_off(0, 2 * H + 1, 1)>(vb);
;     vf[4] = tr_read<v_rd_off(1, 2 * H, 0)>(vb); vf[5] = tr_read<v_rd_off(1, 2 * H, 1)>(vb); vf[6] = tr_read<v_rd_off(1, 2 * H + 1, 0)>(vb); vf[7] = tr_read<v_rd_off(1, 2 * H + 1, 1)>(vb);
;     vf[8] = tr_read<v_rd_off(2, 2 * H, 0)>(vb); vf[9] = tr_read<v_rd_off(2, 2 * H, 1)>(vb); vf[10] = tr_read<v_rd_off(2, 2 * H + 1, 0)>(vb); vf[11] = tr_read<v_rd_off(2, 2 * H + 1, 1)>(vb);
;     vf[12] = tr_read<v_rd_off(3, 2 * H, 0)>(vb); vf[13] = tr_read<v_rd_off(3, 2 * H, 1)>(vb); vf[14] = tr_read<v_rd_off(3, 2 * H + 1, 0)>(vb); vf[15] = tr_read<v_rd_off(3, 2 * H + 1, 1)>(vb);
; }
; DI void pv_mma(f32x16* o, const s16x4* vf, bf16x8 pa0, bf16x8 pa1) {
;     ...
; #pragma unroll
;     for (int d0 = 0; d0 < 4; ++d0) {
;         o[d0] = __builtin_amdgcn_mfma_f32_32x32x16_bf16(pa0, ATT_PK(vf[4 * d0], vf[4 * d0 + 1]), o[d0], 0, 0, 0);
;         o[d0] = __builtin_amdgcn_mfma_f32_32x32x16_bf16(pa1, ATT_PK(vf[4 * d0 + 2], vf[4 * d0 + 3]), o[d0], 0, 0, 0); }
;     ...
; }
; template <int DQK, int D0A, int D0B> DI void k_reads(bf16x8* kf, const LAS unsigned char* Ks, int half, int r32, int hi) {
; #pragma unroll
;     for (int d0 = D0A; d0 < D0B; ++d0) kf[d0 - D0A] = *(const LAS bf16x8*)(Ks + half * (32 * DQK * 2) + kswz<DQK>(r32, (d0 * 16 + hi * 8) * 2));
; }
; template <int D0A, int D0B> DI void qk_mma(f32x16& p, const bf16x8* kf, const bf16x8* qr) {
; #pragma unroll
;     for (int d0 = D0A; d0 < D0B; ++d0) {
.Lstg_mla_t62_6:
	s_setprio 0
	ds_read_b128 v[132:135], v161 offset:61440
	ds_read_b128 v[136:139], v162 offset:61440
	ds_read_b128 v[140:143], v163 offset:61440
	ds_read_b128 v[174:177], v164 offset:61440
	ds_read_b128 v[162:165], v165 offset:61440
	ds_read_b128 v[178:181], v166 offset:61440
	v_add_u32_e32 v145, 0x8000, v130
	ds_read_b64_tr_b16 v[182:183], v145 offset:0
	ds_read_b64_tr_b16 v[184:185], v145 offset:0x800
	ds_read_b64_tr_b16 v[186:187], v145 offset:0x1000
	ds_read_b64_tr_b16 v[188:189], v145 offset:0x1800
	ds_read_b64_tr_b16 v[190:191], v145 offset:0x200
	ds_read_b64_tr_b16 v[192:193], v145 offset:0xa00
	ds_read_b64_tr_b16 v[194:195], v145 offset:0x1200
	ds_read_b64_tr_b16 v[196:197], v145 offset:0x1a00
	ds_read_b64_tr_b16 v[198:199], v145 offset:0x400
	ds_read_b64_tr_b16 v[200:201], v145 offset:0xc00
	ds_read_b64_tr_b16 v[202:203], v145 offset:0x1400
	ds_read_b64_tr_b16 v[204:205], v145 offset:0x1c00
	ds_read_b64_tr_b16 v[206:207], v145 offset:0x600
	ds_read_b64_tr_b16 v[208:209], v145 offset:0xe00
	ds_read_b64_tr_b16 v[210:211], v145 offset:0x1600
	ds_read_b64_tr_b16 v[212:213], v145 offset:0x1e00
	s_nop 3
	s_setprio 2
	v_exp_f32_e32 v64, v64
	v_exp_f32_e32 v65, v65
	v_exp_f32_e32 v66, v66
	v_exp_f32_e32 v67, v67
	v_exp_f32_e32 v68, v68
	v_add_f32_e32 v161, 0, v64
	v_exp_f32_e32 v69, v69
	v_add_f32_e32 v161, v65, v161
	v_exp_f32_e32 v70, v70
	v_add_f32_e32 v161, v66, v161
	v_exp_f32_e32 v71, v71
	v_add_f32_e32 v161, v67, v161
	v_exp_f32_e32 v72, v72
	v_add_f32_e32 v161, v68, v161
	v_exp_f32_e32 v73, v73
	v_add_f32_e32 v161, v69, v161
	v_exp_f32_e32 v74, v74
	v_add_f32_e32 v161, v70, v161
	v_exp_f32_e32 v75, v75
	v_add_f32_e32 v161, v71, v161
	v_exp_f32_e32 v76, v76
	v_add_f32_e32 v161, v72, v161
	v_exp_f32_e32 v77, v77
	v_add_f32_e32 v161, v73, v161
	v_exp_f32_e32 v78, v78
	v_add_f32_e32 v161, v74, v161
	v_exp_f32_e32 v79, v79
	v_add_f32_e32 v161, v75, v161
	v_add_f32_e32 v161, v76, v161
	v_add_f32_e32 v161, v77, v161
	v_add_f32_e32 v161, v78, v161
	v_add_f32_e32 v161, v79, v161
	v_add_f32_e32 v144, v144, v161
	v_cvt_pk_bf16_f32 v64, v64, v65
	v_cvt_pk_bf16_f32 v65, v66, v67
	v_cvt_pk_bf16_f32 v66, v68, v69
	v_cvt_pk_bf16_f32 v67, v70, v71
	v_cvt_pk_bf16_f32 v68, v72, v73
	v_cvt_pk_bf16_f32 v69, v74, v75
	v_cvt_pk_bf16_f32 v70, v76, v77
	v_cvt_pk_bf16_f32 v71, v78, v79
	s_nop 0
	v_permlane32_swap_b32_e32 v64, v66
	v_permlane32_swap_b32_e32 v65, v67
	v_permlane32_swap_b32_e32 v68, v70
	v_permlane32_swap_b32_e32 v69, v71
	s_waitcnt lgkmcnt(0)
	ds_read_b128 v[214:217], v167 offset:61440
	ds_read_b128 v[218:221], v168 offset:61440
	ds_read_b128 v[166:169], v169 offset:61440
	ds_read_b128 v[222:225], v170 offset:61440
	ds_read_b128 v[226:229], v171 offset:61440
	ds_read_b128 v[170:173], v172 offset:61440
	s_setprio 1
	v_mfma_f32_32x32x16_bf16 v[48:63], v[64:67], v[182:185], v[48:63]
	v_mfma_f32_32x32x16_bf16 v[32:47], v[64:67], v[190:193], v[32:47]
	v_mfma_f32_32x32x16_bf16 v[16:31], v[64:67], v[198:201], v[16:31]
	v_mfma_f32_32x32x16_bf16 v[0:15], v[64:67], v[206:209], v[0:15]
	v_mfma_f32_32x32x16_bf16 v[48:63], v[68:71], v[186:189], v[48:63]
	v_mfma_f32_32x32x16_bf16 v[32:47], v[68:71], v[194:197], v[32:47]
	v_mfma_f32_32x32x16_bf16 v[16:31], v[68:71], v[202:205], v[16:31]
	v_mfma_f32_32x32x16_bf16 v[0:15], v[68:71], v[210:213], v[0:15]
	s_waitcnt lgkmcnt(0)
	v_mfma_f32_32x32x16_bf16 v[64:79], v[132:135], v[80:83], 0
	v_mfma_f32_32x32x16_bf16 v[64:79], v[136:139], v[84:87], v[64:79]
	v_mfma_f32_32x32x16_bf16 v[64:79], v[140:143], v[88:91], v[64:79]
	v_mfma_f32_32x32x16_bf16 v[64:79], v[174:177], v[92:95], v[64:79]
	v_mfma_f32_32x32x16_bf16 v[64:79], v[162:165], v[96:99], v[64:79]
	v_mfma_f32_32x32x16_bf16 v[64:79], v[178:181], v[100:103], v[64:79]
	s_waitcnt lgkmcnt(0)
; #define LAS __attribute__((address_space(3)))
; DI void expsum(f32x16& p, float& l_reg, bf16x8& pa0, bf16x8& pa1) {
; #pragma unroll
;     for (int r = 0; r < 16; ++r) p[r] = __builtin_amdgcn_exp2f(p[r]);
;     float ps = 0.f;
; #pragma unroll
;     for (int r = 0; r < 16; ++r) ps += p[r];
;     l_reg += ps; asm volatile("" : "+v"(l_reg));
;     ...
;     ATT_PK4(p, 0, pa0); ATT_PK4(p, 8, pa1);
;     ...
; }
; DI int v_rd_base(int lane) { return ((lane & 3) << 3) | (((lane >> 2) & 3) << 6) | (((lane >> 4) & 1) << 5) | (((lane >> 5) & 1) << 8); }
; template <int OFF> DI s16x4 tr_read(int vb) { s16x4 r; asm volatile("ds_read_b64_tr_b16 %0, %1 offset:%2" : "=&v"(r) : "v"(vb), "i"(OFF) : "memory"); return r; }
; template <int H> DI void v_reads(s16x4* vf, int vb) {
;     vf[0] = tr_read<v_rd_off(0, 2 * H, 0)>(vb); vf[1] = tr_read<v_rd_off(0, 2 * H, 1)>(vb); vf[2] = tr_read<v_rd_off(0, 2 * H + 1, 0)>(vb); vf[3] = tr_read<v_rd_off(0, 2 * H + 1, 1)>(vb);
;     vf[4] = tr_read<v_rd_off(1, 2 * H, 0)>(vb); vf[5] = tr_read<v_rd_off(1, 2 * H, 1)>(vb); vf[6] = tr_read<v_rd_off(1, 2 * H + 1, 0)>(vb); vf[7] = tr_read<v_rd_off(1, 2 * H + 1, 1)>(vb);
;     vf[8] = tr_read<v_rd_off(2, 2 * H, 0)>(vb); vf[9] = tr_read<v_rd_off(2, 2 * H, 1)>(vb); vf[10] = tr_read<v_rd_off(2, 2 * H + 1, 0)>(vb); vf[11] = tr_read<v_rd_off(2, 2 * H + 1, 1)>(vb);
;     vf[12] = tr_read<v_rd_off(3, 2 * H, 0)>(vb); vf[13] = tr_read<v_rd_off(3, 2 * H, 1)>(vb); vf[14] = tr_read<v_rd_off(3, 2 * H + 1, 0)>(vb); vf[15] = tr_read<v_rd_off(3, 2 * H + 1, 1)>(vb);
; }
; DI void pv_mma(f32x16* o, const s16x4* vf, bf16x8 pa0, bf16x8 pa1) {
;     ...
; #pragma unroll
;     for (int d0 = 0; d0 < 4; ++d0) {
;         o[d0] = __builtin_amdgcn_mfma_f32_32x32x16_bf16(pa0, ATT_PK(vf[4 * d0], vf[4 * d0 + 1]), o[d0], 0, 0, 0);
;         o[d0] = __builtin_amdgcn_mfma_f32_32x32x16_bf16(pa1, ATT_PK(vf[4 * d0 + 2], vf[4 * d0 + 3]), o[d0], 0, 0, 0); }
;     ...
; }
; template <int DQK, int D0A, int D0B> DI void k_reads(bf16x8* kf, const LAS unsigned char* Ks, int half, int r32, int hi) {
; #pragma unroll
;     for (int d0 = D0A; d0 < D0B; ++d0) kf[d0 - D0A] = *(const LAS bf16x8*)(Ks + half * (32 * DQK * 2) + kswz<DQK>(r32, (d0 * 16 + hi * 8) * 2));
; }
; template <int D0A, int D0B> DI void qk_mma(f32x16& p, const bf16x8* kf, const bf16x8* qr) {
; #pragma unroll
;     for (int d0 = D0A; d0 < D0B; ++d0) {
	v_mfma_f32_32x32x16_bf16 v[64:79], v[214:217], v[104:107], v[64:79]
	v_mfma_f32_32x32x16_bf16 v[64:79], v[218:221], v[108:111], v[64:79]
	v_mfma_f32_32x32x16_bf16 v[64:79], v[166:169], v[112:115], v[64:79]
	v_mfma_f32_32x32x16_bf16 v[64:79], v[222:225], v[116:119], v[64:79]
	v_mfma_f32_32x32x16_bf16 v[64:79], v[226:229], v[120:123], v[64:79]
	v_mfma_f32_32x32x16_bf16 v[64:79], v[170:173], v[124:127], v[64:79]
	s_setprio 0
	v_add_u32_e32 v158, 0x12000, v158
	v_add_u32_e32 v132, v158, v151
	v_add_u32_e32 v136, v158, v149
	v_add_u32_e32 v140, v158, v148
	v_add_u32_e32 v161, v158, v147
	ds_read_b128 v[132:135], v132
	ds_read_b128 v[136:139], v136
	ds_read_b128 v[140:143], v140
	ds_read_b128 v[162:165], v161
	v_add_u32_e32 v161, v158, v146
	v_add_u32_e32 v170, v158, v150
	ds_read_b128 v[166:169], v161
	ds_read_b128 v[170:173], v170
	ds_read_b64_tr_b16 v[174:175], v145 offset:0x2000
	ds_read_b64_tr_b16 v[176:177], v145 offset:0x2800
	ds_read_b64_tr_b16 v[178:179], v145 offset:0x3000
	ds_read_b64_tr_b16 v[180:181], v145 offset:0x3800
	ds_read_b64_tr_b16 v[182:183], v145 offset:0x2200
	ds_read_b64_tr_b16 v[184:185], v145 offset:0x2a00
	ds_read_b64_tr_b16 v[186:187], v145 offset:0x3200
	ds_read_b64_tr_b16 v[188:189], v145 offset:0x3a00
	ds_read_b64_tr_b16 v[190:191], v145 offset:0x2400
	ds_read_b64_tr_b16 v[192:193], v145 offset:0x2c00
	ds_read_b64_tr_b16 v[194:195], v145 offset:0x3400
	ds_read_b64_tr_b16 v[196:197], v145 offset:0x3c00
	ds_read_b64_tr_b16 v[198:199], v145 offset:0x2600
	ds_read_b64_tr_b16 v[200:201], v145 offset:0x2e00
	ds_read_b64_tr_b16 v[202:203], v145 offset:0x3600
	ds_read_b64_tr_b16 v[204:205], v145 offset:0x3e00
	s_setprio 2
	v_exp_f32_e32 v64, v64
	v_exp_f32_e32 v65, v65
	v_exp_f32_e32 v66, v66
	v_exp_f32_e32 v67, v67
	v_exp_f32_e32 v68, v68
	v_add_f32_e32 v145, 0, v64
	v_exp_f32_e32 v69, v69
	v_add_f32_e32 v145, v65, v145
	v_exp_f32_e32 v70, v70
	v_add_f32_e32 v145, v66, v145
	v_exp_f32_e32 v71, v71
	v_add_f32_e32 v145, v67, v145
	v_exp_f32_e32 v72, v72
	v_add_f32_e32 v145, v68, v145
	v_exp_f32_e32 v73, v73
	v_add_f32_e32 v145, v69, v145
	v_exp_f32_e32 v74, v74
	v_add_f32_e32 v145, v70, v145
	v_exp_f32_e32 v75, v75
	v_add_f32_e32 v145, v71, v145
	v_exp_f32_e32 v76, v76
	v_add_f32_e32 v145, v72, v145
	v_exp_f32_e32 v77, v77
	v_add_f32_e32 v145, v73, v145
	v_exp_f32_e32 v78, v78
	v_add_f32_e32 v145, v74, v145
	v_exp_f32_e32 v79, v79
	v_add_f32_e32 v145, v75, v145
	v_add_f32_e32 v145, v76, v145
	v_add_f32_e32 v145, v77, v145
	v_add_f32_e32 v145, v78, v145
	v_add_f32_e32 v145, v79, v145
	v_add_f32_e32 v161, v144, v145
	v_cvt_pk_bf16_f32 v64, v64, v65
	v_cvt_pk_bf16_f32 v65, v66, v67
	v_cvt_pk_bf16_f32 v66, v68, v69
	v_cvt_pk_bf16_f32 v67, v70, v71
	v_cvt_pk_bf16_f32 v68, v72, v73
	v_cvt_pk_bf16_f32 v69, v74, v75
	v_cvt_pk_bf16_f32 v70, v76, v77
	v_cvt_pk_bf16_f32 v71, v78, v79
	s_nop 0
	v_permlane32_swap_b32_e32 v64, v66
	v_permlane32_swap_b32_e32 v65, v67
	v_permlane32_swap_b32_e32 v68, v70
	v_permlane32_swap_b32_e32 v69, v71
	s_waitcnt lgkmcnt(0)
	v_add_u32_e32 v72, v158, v152
	v_add_u32_e32 v73, v158, v153
	ds_read_b128 v[206:209], v72
	ds_read_b128 v[210:213], v73
	v_add_u32_e32 v72, v158, v154
	v_add_u32_e32 v73, v158, v155
	ds_read_b128 v[214:217], v72
	ds_read_b128 v[218:221], v73
	v_add_u32_e32 v72, v158, v156
	v_add_u32_e32 v73, v158, v157
	ds_read_b128 v[222:225], v72
	ds_read_b128 v[226:229], v73
	s_setprio 1
	s_cmp_lt_u32 s33, 0x100
	s_cbranch_scc1 .Lstg_mla_m62_7
	s_waitcnt vmcnt(0)
	s_barrier

; #define LAS __attribute__((address_space(3)))
; DI void expsum(f32x16& p, float& l_reg, bf16x8& pa0, bf16x8& pa1) {
; #pragma unroll
;     for (int r = 0; r < 16; ++r) p[r] = __builtin_amdgcn_exp2f(p[r]);
;     float ps = 0.f;
; #pragma unroll
;     for (int r = 0; r < 16; ++r) ps += p[r];
;     l_reg += ps; asm volatile("" : "+v"(l_reg));
;     ...
;     ATT_PK4(p, 0, pa0); ATT_PK4(p, 8, pa1);
;     ...
; }
; DI int v_rd_base(int lane) { return ((lane & 3) << 3) | (((lane >> 2) & 3) << 6) | (((lane >> 4) & 1) << 5) | (((lane >> 5) & 1) << 8); }
; template <int OFF> DI s16x4 tr_read(int vb) { s16x4 r; asm volatile("ds_read_b64_tr_b16 %0, %1 offset:%2" : "=&v"(r) : "v"(vb), "i"(OFF) : "memory"); return r; }
; template <int H> DI void v_reads(s16x4* vf, int vb) {
;     vf[0] = tr_read<v_rd_off(0, 2 * H, 0)>(vb); vf[1] = tr_read<v_rd_off(0, 2 * H, 1)>(vb); vf[2] = tr_read<v_rd_off(0, 2 * H + 1, 0)>(vb); vf[3] = tr_read<v_rd_off(0, 2 * H + 1, 1)>(vb);
;     vf[4] = tr_read<v_rd_off(1, 2 * H, 0)>(vb); vf[5] = tr_read<v_rd_off(1, 2 * H, 1)>(vb); vf[6] = tr_read<v_rd_off(1, 2 * H + 1, 0)>(vb); vf[7] = tr_read<v_rd_off(1, 2 * H + 1, 1)>(vb);
;     vf[8] = tr_read<v_rd_off(2, 2 * H, 0)>(vb); vf[9] = tr_read<v_rd_off(2, 2 * H, 1)>(vb); vf[10] = tr_read<v_rd_off(2, 2 * H + 1, 0)>(vb); vf[11] = tr_read<v_rd_off(2, 2 * H + 1, 1)>(vb);
;     vf[12] = tr_read<v_rd_off(3, 2 * H, 0)>(vb); vf[13] = tr_read<v_rd_off(3, 2 * H, 1)>(vb); vf[14] = tr_read<v_rd_off(3, 2 * H + 1, 0)>(vb); vf[15] = tr_read<v_rd_off(3, 2 * H + 1, 1)>(vb);
; }
; DI void pv_mma(f32x16* o, const s16x4* vf, bf16x8 pa0, bf16x8 pa1) {
;     ...
; #pragma unroll
;     for (int d0 = 0; d0 < 4; ++d0) {
;         o[d0] = __builtin_amdgcn_mfma_f32_32x32x16_bf16(pa0, ATT_PK(vf[4 * d0], vf[4 * d0 + 1]), o[d0], 0, 0, 0);
;         o[d0] = __builtin_amdgcn_mfma_f32_32x32x16_bf16(pa1, ATT_PK(vf[4 * d0 + 2], vf[4 * d0 + 3]), o[d0], 0, 0, 0); }
;     ...
; }
; template <int DQK, int D0A, int D0B> DI void k_reads(bf16x8* kf, const LAS unsigned char* Ks, int half, int r32, int hi) {
; #pragma unroll
;     for (int d0 = D0A; d0 < D0B; ++d0) kf[d0 - D0A] = *(const LAS bf16x8*)(Ks + half * (32 * DQK * 2) + kswz<DQK>(r32, (d0 * 16 + hi * 8) * 2));
; }
; template <int D0A, int D0B> DI void qk_mma(f32x16& p, const bf16x8* kf, const bf16x8* qr) {
; #pragma unroll
;     for (int d0 = D0A; d0 < D0B; ++d0) {
.Lstg_mla_t63_8:
	s_setprio 0
	v_add_u32_e32 v158, s82, v159
	v_add_u32_e32 v132, v158, v151
	v_add_u32_e32 v136, v158, v149
	v_add_u32_e32 v140, v158, v148
	v_add_u32_e32 v144, v158, v147
	ds_read_b128 v[132:135], v132
	ds_read_b128 v[136:139], v136
	ds_read_b128 v[140:143], v140
	ds_read_b128 v[162:165], v144
	v_add_u32_e32 v144, v158, v146
	v_add_u32_e32 v148, v158, v150
	ds_read_b128 v[144:147], v144
	ds_read_b128 v[148:151], v148
	ds_read_b64_tr_b16 v[166:167], v130 offset:0
	ds_read_b64_tr_b16 v[168:169], v130 offset:0x800
	ds_read_b64_tr_b16 v[170:171], v130 offset:0x1000
	ds_read_b64_tr_b16 v[172:173], v130 offset:0x1800
	ds_read_b64_tr_b16 v[174:175], v130 offset:0x200
	ds_read_b64_tr_b16 v[176:177], v130 offset:0xa00
	ds_read_b64_tr_b16 v[178:179], v130 offset:0x1200
	ds_read_b64_tr_b16 v[180:181], v130 offset:0x1a00
	ds_read_b64_tr_b16 v[182:183], v130 offset:0x400
	ds_read_b64_tr_b16 v[184:185], v130 offset:0xc00
	ds_read_b64_tr_b16 v[186:187], v130 offset:0x1400
	ds_read_b64_tr_b16 v[188:189], v130 offset:0x1c00
	ds_read_b64_tr_b16 v[190:191], v130 offset:0x600
	ds_read_b64_tr_b16 v[192:193], v130 offset:0xe00
	ds_read_b64_tr_b16 v[194:195], v130 offset:0x1600
	ds_read_b64_tr_b16 v[196:197], v130 offset:0x1e00
	s_setprio 2
	v_exp_f32_e32 v64, v64
	v_exp_f32_e32 v65, v65
	v_exp_f32_e32 v66, v66
	v_exp_f32_e32 v67, v67
	v_exp_f32_e32 v68, v68
	v_add_f32_e32 v159, 0, v64
	v_exp_f32_e32 v69, v69
	v_add_f32_e32 v159, v65, v159
	v_exp_f32_e32 v70, v70
	v_add_f32_e32 v159, v66, v159
	v_exp_f32_e32 v71, v71
	v_add_f32_e32 v159, v67, v159
	v_exp_f32_e32 v72, v72
	v_add_f32_e32 v159, v68, v159
	v_exp_f32_e32 v73, v73
	v_add_f32_e32 v159, v69, v159
	v_exp_f32_e32 v74, v74
	v_add_f32_e32 v159, v70, v159
	v_exp_f32_e32 v75, v75
	v_add_f32_e32 v159, v71, v159
	v_exp_f32_e32 v76, v76
	v_add_f32_e32 v159, v72, v159
	v_exp_f32_e32 v77, v77
	v_add_f32_e32 v159, v73, v159
	v_exp_f32_e32 v78, v78
	v_add_f32_e32 v159, v74, v159
	v_exp_f32_e32 v79, v79
	v_add_f32_e32 v159, v75, v159
	v_add_f32_e32 v159, v76, v159
	v_add_f32_e32 v159, v77, v159
	v_add_f32_e32 v159, v78, v159
	v_add_f32_e32 v159, v79, v159
	v_add_f32_e32 v161, v161, v159
	v_cvt_pk_bf16_f32 v64, v64, v65
	v_cvt_pk_bf16_f32 v65, v66, v67
	v_cvt_pk_bf16_f32 v66, v68, v69
	v_cvt_pk_bf16_f32 v67, v70, v71
	v_cvt_pk_bf16_f32 v68, v72, v73
	v_cvt_pk_bf16_f32 v69, v74, v75
	v_cvt_pk_bf16_f32 v70, v76, v77
	v_cvt_pk_bf16_f32 v71, v78, v79
	s_nop 0
	v_permlane32_swap_b32_e32 v64, v66
	v_permlane32_swap_b32_e32 v65, v67
	v_permlane32_swap_b32_e32 v68, v70
	v_permlane32_swap_b32_e32 v69, v71
	s_waitcnt lgkmcnt(0)
	v_add_u32_e32 v72, v158, v152
	v_add_u32_e32 v73, v158, v153
	ds_read_b128 v[198:201], v72
	ds_read_b128 v[202:205], v73
	v_add_u32_e32 v72, v158, v154
	v_add_u32_e32 v73, v158, v155
	ds_read_b128 v[152:155], v72
	ds_read_b128 v[206:209], v73
	v_add_u32_e32 v72, v158, v156
	v_add_u32_e32 v73, v158, v157
	ds_read_b128 v[156:159], v72
	ds_read_b128 v[210:213], v73
	s_setprio 1
	v_mfma_f32_32x32x16_bf16 v[48:63], v[64:67], v[166:169], v[48:63]
	v_mfma_f32_32x32x16_bf16 v[32:47], v[64:67], v[174:177], v[32:47]
	v_mfma_f32_32x32x16_bf16 v[16:31], v[64:67], v[182:185], v[16:31]
	v_mfma_f32_32x32x16_bf16 v[0:15], v[64:67], v[190:193], v[0:15]
	v_mfma_f32_32x32x16_bf16 v[48:63], v[68:71], v[170:173], v[48:63]
	v_mfma_f32_32x32x16_bf16 v[32:47], v[68:71], v[178:181], v[32:47]
	v_mfma_f32_32x32x16_bf16 v[16:31], v[68:71], v[186:189], v[16:31]
	v_mfma_f32_32x32x16_bf16 v[0:15], v[68:71], v[194:197], v[0:15]
	s_waitcnt lgkmcnt(0)
; template <int TAG = 0> DI int fresh_tid(int wv) { int l; asm volatile("v_mbcnt_lo_u32_b32 %0, -1, 0\n\tv_mbcnt_hi_u32_b32 %0, -1, %0 ; site %1" : "=v"(l) : "n"(TAG)); return wv * 64 + l; }
; DI void expsum(f32x16& p, float& l_reg, bf16x8& pa0, bf16x8& pa1) {
; #pragma unroll
;     for (int r = 0; r < 16; ++r) p[r] = __builtin_amdgcn_exp2f(p[r]);
;     float ps = 0.f;
; #pragma unroll
;     for (int r = 0; r < 16; ++r) ps += p[r];
;     l_reg += ps; asm volatile("" : "+v"(l_reg));
;     ...
;     ATT_PK4(p, 0, pa0); ATT_PK4(p, 8, pa1);
;     ...
; }
; DI int v_rd_base(int lane) { return ((lane & 3) << 3) | (((lane >> 2) & 3) << 6) | (((lane >> 4) & 1) << 5) | (((lane >> 5) & 1) << 8); }
; template <int OFF> DI s16x4 tr_read(int vb) { s16x4 r; asm volatile("ds_read_b64_tr_b16 %0, %1 offset:%2" : "=&v"(r) : "v"(vb), "i"(OFF) : "memory"); return r; }
; template <int H> DI void v_reads(s16x4* vf, int vb) {
;     vf[0] = tr_read<v_rd_off(0, 2 * H, 0)>(vb); vf[1] = tr_read<v_rd_off(0, 2 * H, 1)>(vb); vf[2] = tr_read<v_rd_off(0, 2 * H + 1, 0)>(vb); vf[3] = tr_read<v_rd_off(0, 2 * H + 1, 1)>(vb);
;     vf[4] = tr_read<v_rd_off(1, 2 * H, 0)>(vb); vf[5] = tr_read<v_rd_off(1, 2 * H, 1)>(vb); vf[6] = tr_read<v_rd_off(1, 2 * H + 1, 0)>(vb); vf[7] = tr_read<v_rd_off(1, 2 * H + 1, 1)>(vb);
;     vf[8] = tr_read<v_rd_off(2, 2 * H, 0)>(vb); vf[9] = tr_read<v_rd_off(2, 2 * H, 1)>(vb); vf[10] = tr_read<v_rd_off(2, 2 * H + 1, 0)>(vb); vf[11] = tr_read<v_rd_off(2, 2 * H + 1, 1)>(vb);
;     vf[12] = tr_read<v_rd_off(3, 2 * H, 0)>(vb); vf[13] = tr_read<v_rd_off(3, 2 * H, 1)>(vb); vf[14] = tr_read<v_rd_off(3, 2 * H + 1, 0)>(vb); vf[15] = tr_read<v_rd_off(3, 2 * H + 1, 1)>(vb);
; }
; DI void pv_mma(f32x16* o, const s16x4* vf, bf16x8 pa0, bf16x8 pa1) {
;     ...
; #pragma unroll
;     for (int d0 = 0; d0 < 4; ++d0) {
;         o[d0] = __builtin_amdgcn_mfma_f32_32x32x16_bf16(pa0, ATT_PK(vf[4 * d0], vf[4 * d0 + 1]), o[d0], 0, 0, 0);
;         o[d0] = __builtin_amdgcn_mfma_f32_32x32x16_bf16(pa1, ATT_PK(vf[4 * d0 + 2], vf[4 * d0 + 3]), o[d0], 0, 0, 0); }
;     ...
; }
; template <int DQK, int MODE, int LDQ, int LDK, int LDV> ...
;     ...
;     __builtin_amdgcn_s_setprio(0);
;     ...
;     l_reg = swap_sum(l_reg);
;     { const int lane2 = fresh_tid<110 + MODE>(wv) & 63, r32 = lane2 & 31, hi = lane2 >> 5;
;     if (hi == 0) li_l[r32] = l_reg;
;     asm volatile("s_waitcnt lgkmcnt(0)" ::: "memory");
	v_mfma_f32_32x32x16_bf16 v[64:79], v[132:135], v[80:83], 0
	v_mfma_f32_32x32x16_bf16 v[64:79], v[136:139], v[84:87], v[64:79]
	v_mfma_f32_32x32x16_bf16 v[64:79], v[140:143], v[88:91], v[64:79]
	v_mfma_f32_32x32x16_bf16 v[64:79], v[162:165], v[92:95], v[64:79]
	v_mfma_f32_32x32x16_bf16 v[64:79], v[144:147], v[96:99], v[64:79]
	v_mfma_f32_32x32x16_bf16 v[64:79], v[148:151], v[100:103], v[64:79]
	s_waitcnt lgkmcnt(0)
	v_mfma_f32_32x32x16_bf16 v[64:79], v[198:201], v[104:107], v[64:79]
	v_mfma_f32_32x32x16_bf16 v[64:79], v[202:205], v[108:111], v[64:79]
	v_mfma_f32_32x32x16_bf16 v[64:79], v[152:155], v[112:115], v[64:79]
	v_mfma_f32_32x32x16_bf16 v[64:79], v[206:209], v[116:119], v[64:79]
	v_mfma_f32_32x32x16_bf16 v[64:79], v[156:159], v[120:123], v[64:79]
	v_mfma_f32_32x32x16_bf16 v[64:79], v[210:213], v[124:127], v[64:79]
	s_setprio 0
	ds_read_b64_tr_b16 v[80:81], v130 offset:0x2000
	ds_read_b64_tr_b16 v[82:83], v130 offset:0x2800
	ds_read_b64_tr_b16 v[84:85], v130 offset:0x3000
	ds_read_b64_tr_b16 v[86:87], v130 offset:0x3800
	ds_read_b64_tr_b16 v[88:89], v130 offset:0x2200
	ds_read_b64_tr_b16 v[90:91], v130 offset:0x2a00
	ds_read_b64_tr_b16 v[92:93], v130 offset:0x3200
	ds_read_b64_tr_b16 v[94:95], v130 offset:0x3a00
	ds_read_b64_tr_b16 v[96:97], v130 offset:0x2400
	ds_read_b64_tr_b16 v[98:99], v130 offset:0x2c00
	ds_read_b64_tr_b16 v[100:101], v130 offset:0x3400
	ds_read_b64_tr_b16 v[102:103], v130 offset:0x3c00
	ds_read_b64_tr_b16 v[104:105], v130 offset:0x2600
	ds_read_b64_tr_b16 v[106:107], v130 offset:0x2e00
	ds_read_b64_tr_b16 v[108:109], v130 offset:0x3600
	ds_read_b64_tr_b16 v[110:111], v130 offset:0x3e00
	s_nop 11
	s_setprio 2
	v_exp_f32_e32 v112, v64
	v_exp_f32_e32 v65, v65
	v_exp_f32_e32 v113, v66
	v_exp_f32_e32 v67, v67
	v_exp_f32_e32 v68, v68
	v_add_f32_e32 v64, 0, v112
	v_exp_f32_e32 v69, v69
	v_add_f32_e32 v64, v65, v64
	v_exp_f32_e32 v70, v70
	v_add_f32_e32 v64, v113, v64
	v_exp_f32_e32 v71, v71
	v_add_f32_e32 v64, v67, v64
	v_exp_f32_e32 v72, v72
	v_add_f32_e32 v64, v68, v64
	v_exp_f32_e32 v73, v73
	v_add_f32_e32 v64, v69, v64
	v_exp_f32_e32 v74, v74
	v_add_f32_e32 v64, v70, v64
	v_exp_f32_e32 v75, v75
	v_add_f32_e32 v64, v71, v64
	v_exp_f32_e32 v76, v76
	v_add_f32_e32 v64, v72, v64
	v_exp_f32_e32 v77, v77
	v_add_f32_e32 v64, v73, v64
	v_exp_f32_e32 v78, v78
	v_add_f32_e32 v64, v74, v64
	v_exp_f32_e32 v79, v79
	v_add_f32_e32 v64, v75, v64
	v_add_f32_e32 v64, v76, v64
	v_add_f32_e32 v64, v77, v64
	v_add_f32_e32 v64, v78, v64
	v_add_f32_e32 v64, v79, v64
	v_add_f32_e32 v64, v161, v64
	v_cvt_pk_bf16_f32 v66, v112, v65
	v_cvt_pk_bf16_f32 v67, v113, v67
	v_cvt_pk_bf16_f32 v68, v68, v69
	v_cvt_pk_bf16_f32 v69, v70, v71
	v_cvt_pk_bf16_f32 v70, v72, v73
	v_cvt_pk_bf16_f32 v71, v74, v75
	v_cvt_pk_bf16_f32 v72, v76, v77
	v_cvt_pk_bf16_f32 v73, v78, v79
	s_nop 0
	v_permlane32_swap_b32_e32 v66, v68
	v_permlane32_swap_b32_e32 v67, v69
	v_permlane32_swap_b32_e32 v70, v72
	v_permlane32_swap_b32_e32 v71, v73
	s_waitcnt lgkmcnt(0)
	s_setprio 1
	v_mfma_f32_32x32x16_bf16 v[48:63], v[66:69], v[80:83], v[48:63]
	v_mfma_f32_32x32x16_bf16 v[32:47], v[66:69], v[88:91], v[32:47]
	v_mfma_f32_32x32x16_bf16 v[16:31], v[66:69], v[96:99], v[16:31]
	v_mfma_f32_32x32x16_bf16 v[0:15], v[66:69], v[104:107], v[0:15]
	v_mfma_f32_32x32x16_bf16 v[48:63], v[70:73], v[84:87], v[48:63]
	v_mfma_f32_32x32x16_bf16 v[32:47], v[70:73], v[92:95], v[32:47]
	v_mfma_f32_32x32x16_bf16 v[16:31], v[70:73], v[100:103], v[16:31]
	v_mfma_f32_32x32x16_bf16 v[0:15], v[70:73], v[108:111], v[0:15]
	s_setprio 0
	v_mbcnt_lo_u32_b32 v66, -1, 0
	v_mbcnt_hi_u32_b32 v66, -1, v66
	v_mov_b32_e32 v67, v64
	v_and_b32_e32 v65, 31, v66
	v_bfe_u32 v66, v66, 5, 1
	v_permlane32_swap_b32_e32 v64, v67
	v_cmp_eq_u32_e32 vcc, 0, v66
	s_and_saveexec_b64 s[2:3], vcc
	s_cbranch_execz .LBB0_1910
	v_lshl_add_u32 v68, v65, 2, s4
	v_add_f32_e32 v64, v64, v67
	ds_write_b32 v68, v64
	s_branch .LBB0_1910
